# scan: counted vmcnt waits, LDS reads software-pipelined in G strips + state update, items sharing C/B tiles co-located per XCD; gate_norm row loop hand-pipelined
# speedup vs baseline: 1.0060x; 1.0060x over previous
;     __device__ __forceinline__ const char* b(const pg8::Unit& u) const { return (const char*)ws + boff + (size_t)u.pn * 256 * K_ * 2 + (u.kq < 0 ? 0 : u.kq * (K_ / 4) * 2); }
;     __device__ __forceinline__ const char* b(const pg8::Unit& u) const { return (const char*)ws + boff + (size_t)u.pn * 256 * D * 2; }
;     __device__ __forceinline__ const char* b(const pg8::Unit& u) const { return (const char*)ws + boff + (size_t)u.pn * 256 * D * 2; }
;     __device__ __forceinline__ const char* b(const pg8::Unit& u) const { return (const char*)ws + WS_A + ((size_t)u.pn * 256 * D + (size_t)(u.pm >> 1) * 256) * 2; }
; template <int MODE> __device__ __forceinline__ void ssd_scan_phase(Frame& F, int j, bool ctx_out) {
;     ...
;     for (int item = blockIdx.x; item < 256; item += F.G) {
;         const int ph = item & 1, dir = (item >> 1) & 1, g = (item >> 2) & 7, b = item >> 5, h = g * 8 + w;
;         const float a_h = -expf(F.in[I_ALOG][(j * 2 + dir) * NH + h]) * LOG2E;
;         const float dtbias = F.in[I_DTB][(j * 2 + dir) * NH + h];
;         const float dsk = dir == 0 ? F.in[I_DSK][(j * 2 + 0) * NH + h] + F.in[I_DSK][(j * 2 + 1) * NH + h] : 0.f;
.LBB0_472:
	s_and_b32 s101, s79, 0xe0
	s_and_b32 s100, s79, 7
	s_lshl_b32 s100, s100, 2
	s_or_b32 s101, s101, s100
	s_bfe_u32 s100, s79, 0x20003
	s_or_b32 s101, s101, s100
	s_bfe_u32 s7, s101, 0x10001
	s_bfe_u32 s15, s101, 0x30002
	s_lshl_b32 s6, s15, 3
	v_readlane_b32 s0, v251, 20
	s_lshl_b32 s11, s7, 6
	s_add_i32 s6, s6, s0
	s_or_b32 s0, s11, s78
	s_add_i32 s0, s0, s6
	s_mov_b32 s1, s92
	v_readlane_b32 s36, v251, 4
	s_lshl_b64 s[0:1], s[0:1], 2
	v_readlane_b32 s46, v251, 14
	v_readlane_b32 s47, v251, 15
	s_add_u32 s4, s46, s0
	v_readlane_b32 s44, v251, 12
	s_addc_u32 s5, s47, s1
	v_readlane_b32 s45, v251, 13
	s_add_u32 s0, s44, s0
	s_addc_u32 s1, s45, s1
	global_load_dword v1, v177, s[4:5]
	global_load_dword v202, v177, s[0:1]
	s_and_b32 s0, 2, s101
	v_readlane_b32 s38, v251, 6
	v_readlane_b32 s39, v251, 7
	s_cmp_eq_u32 s7, 0
	v_readlane_b32 s37, v251, 5
	s_cselect_b64 s[38:39], -1, 0
	s_cmp_lg_u32 s0, 0
	s_cselect_b64 s[36:37], -1, 0
	v_readlane_b32 s48, v251, 16
	v_readlane_b32 s49, v251, 17
	s_and_b64 vcc, exec, s[36:37]
	v_readlane_b32 s40, v251, 8
	v_readlane_b32 s41, v251, 9
	v_readlane_b32 s42, v251, 10
	v_readlane_b32 s43, v251, 11
	v_readlane_b32 s50, v251, 18
	v_readlane_b32 s51, v251, 19
	s_cbranch_vccnz .LBB0_474
	s_add_i32 s0, s78, s6
	s_mov_b32 s1, s92
	s_lshl_b64 s[0:1], s[0:1], 2
	s_add_u32 s0, s48, s0
	s_addc_u32 s1, s49, s1
	global_load_dword v0, v177, s[0:1]
	global_load_dword v2, v177, s[0:1] offset:256
	s_mov_b64 s[0:1], 0x1f600000
	s_waitcnt vmcnt(0)
	v_add_f32_e32 v203, v0, v2
	s_branch .LBB0_475

; __device__ __forceinline__ int fresh_lane() { int l; asm volatile("v_mbcnt_lo_u32_b32 %0, -1, 0\n\tv_mbcnt_hi_u32_b32 %0, -1, %0" : "=v"(l)); return l; }
;     __device__ __forceinline__ const char* b(const pg8::Unit& u) const { return (const char*)ws + boff + (size_t)u.pn * 256 * K_ * 2 + (u.kq < 0 ? 0 : u.kq * (K_ / 4) * 2); }
;     __device__ __forceinline__ const char* b(const pg8::Unit& u) const { return (const char*)ws + boff + (size_t)u.pn * 256 * D * 2; }
;     __device__ __forceinline__ const char* b(const pg8::Unit& u) const { return (const char*)ws + boff + (size_t)u.pn * 256 * D * 2; }
;     __device__ __forceinline__ const char* b(const pg8::Unit& u) const { return (const char*)ws + WS_A + ((size_t)u.pn * 256 * D + (size_t)(u.pm >> 1) * 256) * 2; }
; #define SCAN_DMA(dstbase, srcptr_row0, pitch_elems) do { _Pragma("unroll") for (int q_ = 0; q_ < 4; ++q_) { const int idx_ = tid + 512 * q_, row_ = idx_ >> 4, c16_ = (idx_ & 15) ^ (row_ & 15); \
;         __builtin_amdgcn_global_load_lds((const unsigned*)((srcptr_row0) + (size_t)row_ * (pitch_elems) + c16_ * 8), (LAS unsigned*)((dstbase) + (w * 64 + 512 * q_) * 16), 16, 0, 0); } } while (0)
; template <int MODE> __device__ __forceinline__ void ssd_scan_phase(Frame& F, int j, bool ctx_out) {
;     ...
;             const int tid0 = w * 64 + fresh_lane(); const int tid = tid0;
;             const bool isctx0 = true; const int cc0 = dir == 0 ? 0 : 1; const int row00 = MLAT + b * LCTX + cc0 * 128;
;             if (ctx_out && !(MODE & 8) && isctx0) { SCAN_DMA(CS, cm + (size_t)row00 * GNW + g * 128, GNW); SCAN_DMA(R0, bm + (size_t)row00 * GNW + g * 128, GNW); }
.LBB0_475:
	s_ashr_i32 s10, s101, 5
	s_lshl_b32 s80, s10, 8
	v_readlane_b32 s26, v255, 33
	s_addk_i32 s80, 0x4000
	s_lshl_b32 s14, s7, 7
	v_readlane_b32 s27, v255, 34
	s_or_b32 s40, s80, s14
	s_mov_b64 s[4:5], -1
	s_and_b64 vcc, exec, s[26:27]
	v_mbcnt_lo_u32_b32 v0, -1, 0
	v_mbcnt_hi_u32_b32 v0, -1, v0
	s_cbranch_vccz .LBB0_477
	s_ashr_i32 s41, s40, 31
	s_lshl_b64 s[4:5], s[40:41], 11
	v_readlane_b32 s17, v253, 11
	v_add_u32_e32 v14, s33, v0
	s_add_u32 s17, s17, s4
	v_readlane_b32 s26, v253, 12
	s_addc_u32 s26, s26, s5
	s_lshl_b32 s42, s15, 7
	s_lshl_b32 s27, s15, 8
	v_ashrrev_i32_e32 v2, 4, v14
	s_add_u32 s30, s17, s27
	v_xor_b32_e32 v6, v2, v0
	v_ashrrev_i32_e32 v3, 31, v2
	s_addc_u32 s31, s26, 0
	v_lshlrev_b64 v[2:3], 11, v[2:3]
	v_lshlrev_b32_e32 v6, 4, v6
	v_lshl_add_u64 v[4:5], s[30:31], 0, v[2:3]
	v_and_b32_e32 v176, 0xf0, v6
	s_mov_b32 m0, s16
	v_lshl_add_u64 v[4:5], v[4:5], 0, v[176:177]
	global_load_lds_dwordx4 v[4:5], off
	v_add_u32_e32 v4, 0x200, v14
	v_ashrrev_i32_e32 v4, 4, v4
	v_xor_b32_e32 v8, v4, v0
	v_ashrrev_i32_e32 v5, 31, v4
	v_lshlrev_b64 v[4:5], 11, v[4:5]
	v_lshlrev_b32_e32 v8, 4, v8
	v_lshl_add_u64 v[6:7], s[30:31], 0, v[4:5]
	v_and_b32_e32 v8, 0xf0, v8
	v_mov_b32_e32 v9, v177
	v_lshl_add_u64 v[6:7], v[6:7], 0, v[8:9]
	s_add_i32 m0, s16, 0x2000
	v_mov_b32_e32 v13, v177
	global_load_lds_dwordx4 v[6:7], off
	v_add_u32_e32 v6, 0x400, v14
	v_ashrrev_i32_e32 v6, 4, v6
	v_xor_b32_e32 v12, v6, v0
	v_ashrrev_i32_e32 v7, 31, v6
	v_lshlrev_b64 v[6:7], 11, v[6:7]
	v_lshlrev_b32_e32 v12, 4, v12
	v_lshl_add_u64 v[10:11], s[30:31], 0, v[6:7]
	v_and_b32_e32 v12, 0xf0, v12
	v_lshl_add_u64 v[10:11], v[10:11], 0, v[12:13]
	s_add_i32 m0, s16, 0x4000
	v_mov_b32_e32 v17, v177
	global_load_lds_dwordx4 v[10:11], off
	v_add_u32_e32 v10, 0x600, v14
	v_ashrrev_i32_e32 v10, 4, v10
	v_ashrrev_i32_e32 v11, 31, v10
	v_xor_b32_e32 v0, v10, v0
	v_lshlrev_b64 v[10:11], 11, v[10:11]
	v_lshl_add_u64 v[14:15], s[30:31], 0, v[10:11]
	s_add_i32 m0, s16, 0x6000
	v_readlane_b32 s30, v253, 7
	v_readlane_b32 s31, v253, 8
	s_add_u32 s4, s30, s4
	s_addc_u32 s5, s31, s5
	v_lshlrev_b32_e32 v0, 4, v0
	s_add_u32 s4, s4, s27
	v_and_b32_e32 v16, 0xf0, v0
	s_addc_u32 s5, s5, 0
	v_lshl_add_u64 v[14:15], v[14:15], 0, v[16:17]
	v_lshl_add_u64 v[2:3], s[4:5], 0, v[2:3]
	global_load_lds_dwordx4 v[14:15], off
	v_lshl_add_u64 v[2:3], v[2:3], 0, v[176:177]
	s_add_i32 m0, s16, 0x8000
	s_mov_b32 s43, s92
	global_load_lds_dwordx4 v[2:3], off
	v_lshl_add_u64 v[2:3], s[4:5], 0, v[4:5]
	v_lshl_add_u64 v[2:3], v[2:3], 0, v[8:9]
	s_add_i32 m0, s16, 0xa000
	s_nop 0
	global_load_lds_dwordx4 v[2:3], off
	v_lshl_add_u64 v[2:3], s[4:5], 0, v[6:7]
	v_lshl_add_u64 v[2:3], v[2:3], 0, v[12:13]
	s_add_i32 m0, s16, 0xc000
	s_nop 0
	global_load_lds_dwordx4 v[2:3], off
	v_lshl_add_u64 v[2:3], s[4:5], 0, v[10:11]
	v_lshl_add_u64 v[2:3], v[2:3], 0, v[16:17]
	s_add_i32 m0, s16, 0xe000
	s_mov_b64 s[4:5], 0
	global_load_lds_dwordx4 v[2:3], off

; __device__ __forceinline__ int fresh_lane() { int l; asm volatile("v_mbcnt_lo_u32_b32 %0, -1, 0\n\tv_mbcnt_hi_u32_b32 %0, -1, %0" : "=v"(l)); return l; }
;     __device__ __forceinline__ const char* b(const pg8::Unit& u) const { return (const char*)ws + boff + (size_t)u.pn * 256 * K_ * 2 + (u.kq < 0 ? 0 : u.kq * (K_ / 4) * 2); }
;     __device__ __forceinline__ const char* b(const pg8::Unit& u) const { return (const char*)ws + boff + (size_t)u.pn * 256 * D * 2; }
;     __device__ __forceinline__ const char* b(const pg8::Unit& u) const { return (const char*)ws + boff + (size_t)u.pn * 256 * D * 2; }
; template <int MODE> __device__ __forceinline__ void ssd_scan_phase(Frame& F, int j, bool ctx_out) {
;     ...
;         const float a_h = -expf(F.in[I_ALOG][(j * 2 + dir) * NH + h]) * LOG2E;
;         const float dtbias = F.in[I_DTB][(j * 2 + dir) * NH + h];
;         const float dsk = dir == 0 ? F.in[I_DSK][(j * 2 + 0) * NH + h] + F.in[I_DSK][(j * 2 + 1) * NH + h] : 0.f;
;         bf16_t* yout = dir == 0 ? (bf16_t*)(F.ws + WS_XBCP) : (bf16_t*)(F.ws + WS_YB);
;         f32x4 hT[8][2];
; #pragma unroll
;         for (int nt = 0; nt < 8; ++nt) { hT[nt][0] = (f32x4){0.f, 0.f, 0.f, 0.f}; hT[nt][1] = (f32x4){0.f, 0.f, 0.f, 0.f}; }
;         {
;             const int tid0 = w * 64 + fresh_lane(); const int tid = tid0;
;             const bool isctx0 = true; const int cc0 = dir == 0 ? 0 : 1; const int row00 = MLAT + b * LCTX + cc0 * 128;
;             if (ctx_out && !(MODE & 8) && isctx0) { SCAN_DMA(CS, cm + (size_t)row00 * GNW + g * 128, GNW); SCAN_DMA(R0, bm + (size_t)row00 * GNW + g * 128, GNW); }
;         }
;         float dtr0, dtr1;
;         { const int lane0 = fresh_lane(); const int cc0 = dir == 0 ? 0 : 1, row00 = MLAT + b * LCTX + cc0 * 128;
;           dtr0 = dtb[(size_t)(row00 + lane0) * 128 + dir * 64 + h]; dtr1 = dtb[(size_t)(row00 + 64 + lane0) * 128 + dir * 64 + h]; }
;         bf16x8 xf[2][4];
;         { const int lane0 = fresh_lane(), fr0 = lane0 & 15, fq0 = lane0 >> 4; const int cc0 = dir == 0 ? 0 : 1;
;           const bf16_t* xl0 = xst + (size_t)NB * DI * LSEQ + ((size_t)(b * DI + h * 64 + ph * 32)) * LCTX + cc0 * 128 + (size_t)fr0 * LCTX + 8 * fq0;
; #pragma unroll
;           for (int pt = 0; pt < 2; ++pt)
; #pragma unroll
;               for (int ks = 0; ks < 4; ++ks) xf[pt][ks] = *(const bf16x8*)(xl0 + (size_t)(16 * pt) * LCTX + 32 * ks); }
.LBB0_479:
	s_waitcnt vmcnt(0)
	v_mul_f32_e32 v0, 0x3fb8aa3b, v1
	v_rndne_f32_e32 v2, v0
	s_mov_b32 s4, 0x3fb8aa3b
	v_sub_f32_e32 v3, v0, v2
	v_fma_f32 v0, v1, s4, -v0
	v_fmac_f32_e32 v0, 0x32a5705f, v1
	v_add_f32_e32 v0, v3, v0
	v_exp_f32_e32 v0, v0
	v_cvt_i32_f32_e32 v2, v2
	s_add_u32 s15, s66, s0
	s_mov_b32 s0, 0xc2ce8ed0
	v_cmp_ngt_f32_e32 vcc, s0, v1
	v_ldexp_f32 v2, v0, v2
	s_mov_b32 s0, 0x42b17218
	v_cndmask_b32_e32 v2, 0, v2, vcc
	v_cmp_nlt_f32_e32 vcc, s0, v1
	v_mov_b32_e32 v1, 0x7f800000
	v_readlane_b32 s46, v252, 60
	v_cndmask_b32_e32 v1, v1, v2, vcc
	v_mul_f32_e32 v204, 0xbfb8aa3b, v1
	v_mbcnt_lo_u32_b32 v1, -1, 0
	v_mbcnt_hi_u32_b32 v1, -1, v1
	v_readlane_b32 s47, v252, 61
	v_add_u32_e32 v2, s40, v1
	v_ashrrev_i32_e32 v3, 31, v2
	v_lshlrev_b64 v[4:5], 9, v[2:3]
	v_add_u32_e32 v2, 64, v2
	v_ashrrev_i32_e32 v3, 31, v2
	v_lshlrev_b64 v[2:3], 9, v[2:3]
	s_addc_u32 s17, s67, s1
	v_lshl_add_u64 v[4:5], s[46:47], 0, v[4:5]
	s_lshl_b32 s0, s11, 2
	s_mov_b32 s1, s92
	v_lshl_add_u64 v[2:3], s[46:47], 0, v[2:3]
	v_lshl_add_u64 v[4:5], v[4:5], 0, s[0:1]
	v_lshl_add_u64 v[2:3], v[2:3], 0, s[0:1]
	s_lshl_b32 s1, s10, 12
	s_lshl_b32 s4, s6, 6
	s_add_i32 s4, s4, s1
	s_lshl_b32 s1, s101, 5
	s_and_b32 s26, s1, 32
	s_or_b32 s44, s4, s26
	s_ashr_i32 s45, s44, 31
	s_lshl_b32 s34, s6, 2
	s_mov_b32 s35, s92
	s_lshl_b64 s[4:5], s[44:45], 9
	v_readlane_b32 s1, v253, 19
	v_lshl_add_u64 v[4:5], v[4:5], 0, s[34:35]
	s_add_u32 s30, s1, s4
	v_readlane_b32 s1, v253, 20
	v_lshl_add_u64 v[2:3], v[2:3], 0, s[34:35]
	global_load_dword v189, v[4:5], off
	global_load_dword v193, v[2:3], off
	v_mbcnt_lo_u32_b32 v1, -1, 0
	v_mbcnt_hi_u32_b32 v1, -1, v1
	s_addc_u32 s31, s1, s5
	s_lshl_b32 s1, s14, 1
	s_add_u32 s4, s30, s1
	v_lshlrev_b32_e32 v2, 9, v1
	v_ashrrev_i32_e32 v1, 1, v1
	s_addc_u32 s5, s31, 0
	v_and_b32_e32 v176, 0x1e00, v2
	v_and_b32_e32 v4, -8, v1
	v_lshl_add_u64 v[2:3], s[4:5], 0, v[176:177]
	v_ashrrev_i32_e32 v5, 31, v4
	v_lshl_add_u64 v[2:3], v[4:5], 1, v[2:3]
	s_movk_i32 s1, 0x2000
	global_load_dwordx4 v[140:143], v[2:3], off
	global_load_dwordx4 v[136:139], v[2:3], off offset:64
	global_load_dwordx4 v[100:103], v[2:3], off offset:128
	global_load_dwordx4 v[8:11], v[2:3], off offset:192
	v_add_co_u32_e32 v2, vcc, s1, v2
	s_add_u32 s0, s46, s0
	s_nop 0
	v_addc_co_u32_e32 v3, vcc, 0, v3, vcc
	global_load_dwordx4 v[144:147], v[2:3], off
	global_load_dwordx4 v[76:79], v[2:3], off offset:64
	global_load_dwordx4 v[48:51], v[2:3], off offset:128
	global_load_dwordx4 v[44:47], v[2:3], off offset:192
	s_addc_u32 s1, s47, 0
	s_add_u32 s34, s0, s34
	s_addc_u32 s35, s1, 0
	s_lshl_b32 s81, s10, 11
	s_lshl_b64 s[0:1], s[44:45], 12
	v_readlane_b32 s5, v253, 15
	s_add_u32 s96, s5, s0
	v_readlane_b32 s0, v253, 16
	s_addc_u32 s97, s0, s1
	s_lshl_b32 s0, s10, 10
	s_add_i32 s0, s42, s0
	s_ashr_i32 s1, s0, 31
	s_lshl_b64 s[10:11], s[0:1], 9
	v_readlane_b32 s5, v253, 21
	s_add_u32 s50, s5, s10
	v_readlane_b32 s5, v253, 22
	s_addc_u32 s51, s5, s11
	s_lshl_b64 s[0:1], s[0:1], 12
	v_readlane_b32 s5, v253, 13
	s_add_u32 s10, s5, s0
	v_readlane_b32 s0, v253, 14
	s_addc_u32 s11, s0, s1
	s_and_b64 s[0:1], s[38:39], exec
	s_cselect_b32 s0, 0x7c, 0
	s_add_i32 s72, s18, s0
	s_lshl_b32 s0, s6, 7
	s_add_u32 s0, s15, s0
	s_addc_u32 s1, s17, 0
	s_lshl_b32 s5, s26, 1
	s_add_u32 s0, s0, s5
	s_addc_u32 s1, s1, 0
	s_xor_b32 s76, s40, 0x80
	s_lshl_b64 s[14:15], s[42:43], 1
	v_readlane_b32 s5, v253, 11
	s_add_u32 s77, s5, s14
	v_readlane_b32 s5, v253, 12
	s_addc_u32 s73, s5, s15
	v_readlane_b32 s26, v253, 7
	v_readlane_b32 s27, v253, 8
	s_add_u32 s74, s26, s14
	s_addc_u32 s75, s27, s15
	s_and_b64 s[14:15], s[38:39], exec
	s_movk_i32 s5, 0xfc
	s_cselect_b32 s5, s5, 0x80
	s_add_i32 s14, s18, s5
	s_and_b64 s[40:41], s[38:39], exec
	s_movk_i32 s5, 0x17c
	s_cselect_b32 s5, s5, 0x100
	s_add_i32 s15, s18, s5
	s_and_b64 s[40:41], s[38:39], exec
	s_movk_i32 s5, 0x1fc
	v_mov_b32_e32 v0, 0
	s_cselect_b32 s5, s5, 0x180
	s_mov_b32 s4, 0
	s_add_i32 s6, s18, s5
	s_xor_b32 s7, s7, 1
	v_mov_b32_e32 v1, v0
	v_mov_b32_e32 v2, v0
	v_mov_b32_e32 v3, v0
	v_mov_b32_e32 v4, v0
	v_mov_b32_e32 v5, v0
	v_mov_b32_e32 v6, v0
	v_mov_b32_e32 v7, v0
	v_mov_b32_e32 v12, v0
	v_mov_b32_e32 v13, v0
	v_mov_b32_e32 v14, v0
	v_mov_b32_e32 v15, v0
	v_mov_b32_e32 v16, v0
	v_mov_b32_e32 v17, v0
	v_mov_b32_e32 v18, v0
	v_mov_b32_e32 v19, v0
	v_mov_b32_e32 v20, v0
	v_mov_b32_e32 v21, v0
	v_mov_b32_e32 v22, v0
	v_mov_b32_e32 v23, v0
	v_mov_b32_e32 v24, v0
	v_mov_b32_e32 v25, v0
	v_mov_b32_e32 v26, v0
	v_mov_b32_e32 v27, v0
	v_mov_b32_e32 v28, v0
	v_mov_b32_e32 v29, v0
	v_mov_b32_e32 v30, v0
	v_mov_b32_e32 v31, v0
	v_mov_b32_e32 v32, v0
	v_mov_b32_e32 v33, v0
	v_mov_b32_e32 v34, v0
	v_mov_b32_e32 v35, v0
	v_mov_b32_e32 v36, v0
	v_mov_b32_e32 v37, v0
	v_mov_b32_e32 v38, v0
	v_mov_b32_e32 v39, v0
	v_mov_b32_e32 v40, v0
	v_mov_b32_e32 v41, v0
	v_mov_b32_e32 v42, v0
	v_mov_b32_e32 v43, v0
	v_mov_b32_e32 v52, v0
	v_mov_b32_e32 v53, v0
	v_mov_b32_e32 v54, v0
	v_mov_b32_e32 v55, v0
	v_mov_b32_e32 v56, v0
	v_mov_b32_e32 v57, v0
	v_mov_b32_e32 v58, v0
	v_mov_b32_e32 v59, v0
	v_mov_b32_e32 v60, v0
	v_mov_b32_e32 v61, v0
	v_mov_b32_e32 v62, v0
	v_mov_b32_e32 v63, v0
	v_mov_b32_e32 v64, v0
	v_mov_b32_e32 v65, v0
	v_mov_b32_e32 v66, v0
	v_mov_b32_e32 v67, v0
	v_mov_b32_e32 v68, v0
	v_mov_b32_e32 v69, v0
	v_mov_b32_e32 v70, v0
	v_mov_b32_e32 v71, v0
	v_mov_b32_e32 v72, v0
	v_mov_b32_e32 v73, v0
	v_mov_b32_e32 v74, v0
	v_mov_b32_e32 v75, v0
	s_branch .LBB0_482

; __device__ __forceinline__ u32x4 pack8(const float (&f)[8]) { u32x4 w; w.x = cvt_pk_bf16(f[0], f[1]); w.y = cvt_pk_bf16(f[2], f[3]); w.z = cvt_pk_bf16(f[4], f[5]); w.w = cvt_pk_bf16(f[6], f[7]); return w; }
; template <int MODE> __device__ __forceinline__ void ssd_scan_phase(Frame& F, int j, bool ctx_out) {
;     ...
;             if (!(MODE & 4)) {
;                 const float dec = exp2f(tot);
; #pragma unroll
;                 for (int nt = 0; nt < 8; ++nt) { hT[nt][0] *= dec; hT[nt][1] *= dec; }
;                 bf16x8 xw[2][4];
; #pragma unroll
;                 for (int ks = 0; ks < 4; ++ks) { const float sck = __builtin_amdgcn_exp2f(tot - tab[dir == 0 ? 32 * ks + 31 : 32 * ks]);
; #pragma unroll
;                     for (int pt = 0; pt < 2; ++pt) { float xv[8]; unpack8(__builtin_bit_cast(u32x4, xs2[pt][ks]), xv);
; #pragma unroll
;                         for (int e = 0; e < 8; ++e) xv[e] *= sck;
;                         xw[pt][ks] = __builtin_bit_cast(bf16x8, pack8(xv)); } }
.LBB0_481:
	v_mov_b32_e32 v8, 0xc2fc0000
	v_cmp_lt_f32_e32 vcc, s86, v8
	s_and_b64 s[42:43], vcc, exec
	s_cselect_b32 s4, 0xffffffc0, 0
	v_cndmask_b32_e32 v8, 0, v243, vcc
	v_add_f32_e32 v8, s86, v8
	v_exp_f32_e32 v8, v8
	v_lshlrev_b32_e32 v10, 16, v92
	v_and_b32_e32 v11, 0xffff0000, v92
	v_lshlrev_b32_e32 v92, 16, v95
	v_ldexp_f32 v8, v8, s4
	v_pk_mul_f32 v[2:3], v[2:3], v[8:9] op_sel_hi:[1,0]
	v_pk_mul_f32 v[0:1], v[0:1], v[8:9] op_sel_hi:[1,0]
	v_pk_mul_f32 v[6:7], v[6:7], v[8:9] op_sel_hi:[1,0]
	v_pk_mul_f32 v[4:5], v[4:5], v[8:9] op_sel_hi:[1,0]
	v_pk_mul_f32 v[106:107], v[14:15], v[8:9] op_sel_hi:[1,0]
	v_pk_mul_f32 v[104:105], v[12:13], v[8:9] op_sel_hi:[1,0]
	v_pk_mul_f32 v[14:15], v[18:19], v[8:9] op_sel_hi:[1,0]
	v_pk_mul_f32 v[12:13], v[16:17], v[8:9] op_sel_hi:[1,0]
	v_pk_mul_f32 v[22:23], v[22:23], v[8:9] op_sel_hi:[1,0]
	v_pk_mul_f32 v[20:21], v[20:21], v[8:9] op_sel_hi:[1,0]
	v_pk_mul_f32 v[26:27], v[26:27], v[8:9] op_sel_hi:[1,0]
	v_pk_mul_f32 v[24:25], v[24:25], v[8:9] op_sel_hi:[1,0]
	v_pk_mul_f32 v[30:31], v[30:31], v[8:9] op_sel_hi:[1,0]
	v_pk_mul_f32 v[28:29], v[28:29], v[8:9] op_sel_hi:[1,0]
	v_pk_mul_f32 v[34:35], v[34:35], v[8:9] op_sel_hi:[1,0]
	v_pk_mul_f32 v[32:33], v[32:33], v[8:9] op_sel_hi:[1,0]
	v_pk_mul_f32 v[38:39], v[38:39], v[8:9] op_sel_hi:[1,0]
	v_pk_mul_f32 v[36:37], v[36:37], v[8:9] op_sel_hi:[1,0]
	v_pk_mul_f32 v[42:43], v[42:43], v[8:9] op_sel_hi:[1,0]
	v_pk_mul_f32 v[40:41], v[40:41], v[8:9] op_sel_hi:[1,0]
	v_pk_mul_f32 v[54:55], v[54:55], v[8:9] op_sel_hi:[1,0]
	v_pk_mul_f32 v[52:53], v[52:53], v[8:9] op_sel_hi:[1,0]
	v_pk_mul_f32 v[58:59], v[58:59], v[8:9] op_sel_hi:[1,0]
	v_pk_mul_f32 v[56:57], v[56:57], v[8:9] op_sel_hi:[1,0]
	v_pk_mul_f32 v[62:63], v[62:63], v[8:9] op_sel_hi:[1,0]
	v_pk_mul_f32 v[60:61], v[60:61], v[8:9] op_sel_hi:[1,0]
	v_pk_mul_f32 v[66:67], v[66:67], v[8:9] op_sel_hi:[1,0]
	v_pk_mul_f32 v[64:65], v[64:65], v[8:9] op_sel_hi:[1,0]
	v_pk_mul_f32 v[70:71], v[70:71], v[8:9] op_sel_hi:[1,0]
	v_pk_mul_f32 v[68:69], v[68:69], v[8:9] op_sel_hi:[1,0]
	v_pk_mul_f32 v[74:75], v[74:75], v[8:9] op_sel_hi:[1,0]
	v_pk_mul_f32 v[72:73], v[72:73], v[8:9] op_sel_hi:[1,0]
	v_mov_b32_e32 v8, s72
	ds_read_b32 v8, v8
	v_lshlrev_b32_e32 v16, 16, v93
	v_and_b32_e32 v17, 0xffff0000, v93
	v_lshlrev_b32_e32 v18, 16, v94
	v_and_b32_e32 v19, 0xffff0000, v94
	s_waitcnt lgkmcnt(0)
	v_sub_f32_e32 v8, s86, v8
	v_exp_f32_e32 v8, v8
	v_and_b32_e32 v93, 0xffff0000, v95
	s_sub_i32 s17, 17, s5
	v_lshl_add_u32 v120, v176, 8, s26
	v_pk_mul_f32 v[10:11], v[8:9], v[10:11] op_sel_hi:[0,1]
	v_pk_mul_f32 v[16:17], v[8:9], v[16:17] op_sel_hi:[0,1]
	v_pk_mul_f32 v[18:19], v[8:9], v[18:19] op_sel_hi:[0,1]
	v_pk_mul_f32 v[100:101], v[8:9], v[92:93] op_sel_hi:[0,1]
	v_cvt_pk_bf16_f32 v92, v10, v11
	v_cvt_pk_bf16_f32 v93, v16, v17
	v_cvt_pk_bf16_f32 v94, v18, v19
	v_lshlrev_b32_e32 v10, 16, v96
	v_and_b32_e32 v11, 0xffff0000, v96
	v_lshlrev_b32_e32 v16, 16, v97
	v_and_b32_e32 v17, 0xffff0000, v97
	v_lshlrev_b32_e32 v18, 16, v98
	v_and_b32_e32 v19, 0xffff0000, v98
	v_lshlrev_b32_e32 v96, 16, v99
	v_and_b32_e32 v97, 0xffff0000, v99
	v_pk_mul_f32 v[10:11], v[8:9], v[10:11] op_sel_hi:[0,1]
	v_pk_mul_f32 v[16:17], v[8:9], v[16:17] op_sel_hi:[0,1]
	v_pk_mul_f32 v[18:19], v[8:9], v[18:19] op_sel_hi:[0,1]
	v_pk_mul_f32 v[8:9], v[8:9], v[96:97] op_sel_hi:[0,1]
	v_cvt_pk_bf16_f32 v99, v8, v9
	v_mov_b32_e32 v8, s14
	ds_read_b32 v8, v8
	v_cvt_pk_bf16_f32 v96, v10, v11
	v_cvt_pk_bf16_f32 v97, v16, v17
	v_cvt_pk_bf16_f32 v98, v18, v19
	v_lshlrev_b32_e32 v10, 16, v84
	s_waitcnt lgkmcnt(0)
	v_sub_f32_e32 v8, s86, v8
	v_exp_f32_e32 v8, v8
	v_and_b32_e32 v11, 0xffff0000, v84
	v_lshlrev_b32_e32 v16, 16, v85
	v_and_b32_e32 v17, 0xffff0000, v85
	v_lshlrev_b32_e32 v18, 16, v86
	v_and_b32_e32 v19, 0xffff0000, v86
	v_lshlrev_b32_e32 v84, 16, v87
	v_and_b32_e32 v85, 0xffff0000, v87
	v_pk_mul_f32 v[10:11], v[8:9], v[10:11] op_sel_hi:[0,1]
	v_pk_mul_f32 v[16:17], v[8:9], v[16:17] op_sel_hi:[0,1]
	v_pk_mul_f32 v[18:19], v[8:9], v[18:19] op_sel_hi:[0,1]
	v_cvt_pk_bf16_f32 v95, v100, v101
	v_pk_mul_f32 v[100:101], v[8:9], v[84:85] op_sel_hi:[0,1]
	v_cvt_pk_bf16_f32 v84, v10, v11
	v_cvt_pk_bf16_f32 v85, v16, v17
	v_cvt_pk_bf16_f32 v86, v18, v19
	v_lshlrev_b32_e32 v10, 16, v88
	v_and_b32_e32 v11, 0xffff0000, v88
	v_lshlrev_b32_e32 v16, 16, v89
	v_and_b32_e32 v17, 0xffff0000, v89
	v_lshlrev_b32_e32 v18, 16, v90
	v_and_b32_e32 v19, 0xffff0000, v90
	v_lshlrev_b32_e32 v88, 16, v91
	v_and_b32_e32 v89, 0xffff0000, v91
	v_pk_mul_f32 v[10:11], v[8:9], v[10:11] op_sel_hi:[0,1]
	v_pk_mul_f32 v[16:17], v[8:9], v[16:17] op_sel_hi:[0,1]
	v_pk_mul_f32 v[18:19], v[8:9], v[18:19] op_sel_hi:[0,1]
	v_pk_mul_f32 v[8:9], v[8:9], v[88:89] op_sel_hi:[0,1]
	v_cvt_pk_bf16_f32 v91, v8, v9
	v_mov_b32_e32 v8, s15
	ds_read_b32 v8, v8
	v_cvt_pk_bf16_f32 v88, v10, v11
	v_cvt_pk_bf16_f32 v89, v16, v17
	v_cvt_pk_bf16_f32 v90, v18, v19
	v_lshlrev_b32_e32 v10, 16, v80
	s_waitcnt lgkmcnt(0)
	v_sub_f32_e32 v8, s86, v8
	v_exp_f32_e32 v8, v8
	v_and_b32_e32 v11, 0xffff0000, v80
	v_lshlrev_b32_e32 v16, 16, v81
	v_and_b32_e32 v17, 0xffff0000, v81
	v_lshlrev_b32_e32 v18, 16, v82
	v_and_b32_e32 v19, 0xffff0000, v82
	v_lshlrev_b32_e32 v80, 16, v83
	v_and_b32_e32 v81, 0xffff0000, v83
	v_pk_mul_f32 v[10:11], v[8:9], v[10:11] op_sel_hi:[0,1]
	v_pk_mul_f32 v[16:17], v[8:9], v[16:17] op_sel_hi:[0,1]
	v_pk_mul_f32 v[18:19], v[8:9], v[18:19] op_sel_hi:[0,1]
	v_cvt_pk_bf16_f32 v87, v100, v101
	v_pk_mul_f32 v[100:101], v[8:9], v[80:81] op_sel_hi:[0,1]
	v_cvt_pk_bf16_f32 v80, v10, v11
	v_cvt_pk_bf16_f32 v81, v16, v17
	v_cvt_pk_bf16_f32 v82, v18, v19
	v_lshlrev_b32_e32 v10, 16, v76
	v_and_b32_e32 v11, 0xffff0000, v76
	v_lshlrev_b32_e32 v16, 16, v77
	v_and_b32_e32 v17, 0xffff0000, v77
	v_lshlrev_b32_e32 v18, 16, v78
	v_and_b32_e32 v19, 0xffff0000, v78
	v_lshlrev_b32_e32 v76, 16, v79
	v_and_b32_e32 v77, 0xffff0000, v79
	v_pk_mul_f32 v[10:11], v[8:9], v[10:11] op_sel_hi:[0,1]
	v_pk_mul_f32 v[16:17], v[8:9], v[16:17] op_sel_hi:[0,1]
	v_pk_mul_f32 v[18:19], v[8:9], v[18:19] op_sel_hi:[0,1]
	v_pk_mul_f32 v[8:9], v[8:9], v[76:77] op_sel_hi:[0,1]
	v_cvt_pk_bf16_f32 v111, v8, v9
	v_mov_b32_e32 v8, s6
	ds_read_b32 v8, v8
	v_cvt_pk_bf16_f32 v108, v10, v11
	v_cvt_pk_bf16_f32 v109, v16, v17
	v_cvt_pk_bf16_f32 v110, v18, v19
	v_lshlrev_b32_e32 v10, 16, v48
	s_waitcnt lgkmcnt(0)
; #define LAS __attribute__((address_space(3)))
;     __device__ __forceinline__ const char* b(const pg8::Unit& u) const { return (const char*)ws + boff + (size_t)u.pn * 256 * K_ * 2 + (u.kq < 0 ? 0 : u.kq * (K_ / 4) * 2); }
;     __device__ __forceinline__ const char* b(const pg8::Unit& u) const { return (const char*)ws + boff + (size_t)u.pn * 256 * D * 2; }
;     __device__ __forceinline__ const char* b(const pg8::Unit& u) const { return (const char*)ws + boff + (size_t)u.pn * 256 * D * 2; }
; template <int MODE> __device__ __forceinline__ void ssd_scan_phase(Frame& F, int j, bool ctx_out) {
;     ...
;                 bf16x8 xw[2][4];
; #pragma unroll
;                 for (int ks = 0; ks < 4; ++ks) { const float sck = __builtin_amdgcn_exp2f(tot - tab[dir == 0 ? 32 * ks + 31 : 32 * ks]);
; #pragma unroll
;                     for (int pt = 0; pt < 2; ++pt) { float xv[8]; unpack8(__builtin_bit_cast(u32x4, xs2[pt][ks]), xv);
; #pragma unroll
;                         for (int e = 0; e < 8; ++e) xv[e] *= sck;
;                         xw[pt][ks] = __builtin_bit_cast(bf16x8, pack8(xv)); } }
;                 {
;                     const int kn = k + 1 < 18 ? k + 1 : 17; const bool isctxn = kn < 2; const int ccn = isctxn ? (dir == 0 ? kn : 1 - kn) : (dir == 0 ? kn - 2 : 17 - kn); const int Tn = isctxn ? LCTX : LSEQ;
;                     const bf16_t* xln = (isctxn ? xst + (size_t)NB * DI * LSEQ + ((size_t)(b * DI + h * 64 + ph * 32)) * LCTX + ccn * 128 : xst + ((size_t)(b * DI + h * 64 + ph * 32)) * LSEQ + ccn * 128) + (size_t)fr * Tn + 8 * fq;
; #pragma unroll
;                     for (int pt = 0; pt < 2; ++pt)
; #pragma unroll
;                         for (int ks = 0; ks < 4; ++ks) xf[pt][ks] = *(const bf16x8*)(xln + (size_t)(16 * pt) * Tn + 32 * ks); }
; #pragma unroll
;                 for (int nt = 0; nt < 8; ++nt) {
; #pragma unroll
;                     for (int ks = 0; ks < 4; ++ks) { const bf16x8 bfr = *(const LAS bf16x8*)(BS + (16 * nt + fr) * 256 + (((4 * ks + fq) ^ fr) << 4));
;                         hT[nt][0] = __builtin_amdgcn_mfma_f32_16x16x32_bf16(bfr, xw[0][ks], hT[nt][0], 0, 0, 0);
;                         hT[nt][1] = __builtin_amdgcn_mfma_f32_16x16x32_bf16(bfr, xw[1][ks], hT[nt][1], 0, 0, 0); }
;                     if (nt & 1) __builtin_amdgcn_sched_barrier(0);
;                 }
	v_sub_f32_e32 v8, s86, v8
	v_exp_f32_e32 v8, v8
	v_and_b32_e32 v11, 0xffff0000, v48
	v_lshlrev_b32_e32 v16, 16, v49
	v_and_b32_e32 v17, 0xffff0000, v49
	v_lshlrev_b32_e32 v18, 16, v50
	v_and_b32_e32 v19, 0xffff0000, v50
	v_pk_mul_f32 v[10:11], v[8:9], v[10:11] op_sel_hi:[0,1]
	v_pk_mul_f32 v[16:17], v[8:9], v[16:17] op_sel_hi:[0,1]
	v_pk_mul_f32 v[18:19], v[8:9], v[18:19] op_sel_hi:[0,1]
	v_lshlrev_b32_e32 v48, 16, v51
	v_and_b32_e32 v49, 0xffff0000, v51
	v_cvt_pk_bf16_f32 v112, v10, v11
	v_cvt_pk_bf16_f32 v113, v16, v17
	v_cvt_pk_bf16_f32 v114, v18, v19
	v_lshlrev_b32_e32 v10, 16, v44
	v_and_b32_e32 v11, 0xffff0000, v44
	v_lshlrev_b32_e32 v16, 16, v45
	v_and_b32_e32 v17, 0xffff0000, v45
	v_lshlrev_b32_e32 v18, 16, v46
	v_and_b32_e32 v19, 0xffff0000, v46
	v_lshlrev_b32_e32 v44, 16, v47
	v_and_b32_e32 v45, 0xffff0000, v47
	v_pk_mul_f32 v[48:49], v[8:9], v[48:49] op_sel_hi:[0,1]
	v_pk_mul_f32 v[10:11], v[8:9], v[10:11] op_sel_hi:[0,1]
	v_pk_mul_f32 v[16:17], v[8:9], v[16:17] op_sel_hi:[0,1]
	v_pk_mul_f32 v[18:19], v[8:9], v[18:19] op_sel_hi:[0,1]
	v_pk_mul_f32 v[8:9], v[8:9], v[44:45] op_sel_hi:[0,1]
	v_cvt_pk_bf16_f32 v119, v8, v9
	v_sub_co_u32_e64 v8, s[42:43], s5, 2
	s_and_b64 s[4:5], s[38:39], exec
	v_readfirstlane_b32 s4, v8
	s_cselect_b32 s17, s4, s17
	s_and_b64 s[4:5], s[42:43], exec
	s_cselect_b32 s17, s7, s17
	s_cselect_b32 s4, 0x2000, s84
	s_cselect_b32 s27, s31, s97
	s_cselect_b32 s41, s30, s96
	s_lshl_b32 s44, s17, 7
	s_ashr_i32 s45, s44, 31
	s_lshl_b64 s[44:45], s[44:45], 1
	s_add_u32 s44, s41, s44
	s_addc_u32 s45, s27, s45
	s_and_b64 s[42:43], s[42:43], exec
	s_cselect_b32 s17, 8, 11
	v_lshlrev_b64 v[8:9], s17, v[176:177]
	v_lshl_add_u64 v[8:9], v[8:9], 1, s[44:45]
	v_cvt_pk_bf16_f32 v117, v16, v17
	s_mov_b32 s5, s92
	v_lshl_add_u64 v[16:17], v[180:181], 1, v[8:9]
	v_cvt_pk_bf16_f32 v83, v100, v101
	v_cvt_pk_bf16_f32 v116, v10, v11
	global_load_dwordx4 v[140:143], v[16:17], off
	global_load_dwordx4 v[136:139], v[16:17], off offset:64
	global_load_dwordx4 v[100:103], v[16:17], off offset:128
	global_load_dwordx4 v[8:11], v[16:17], off offset:192
	v_lshl_add_u64 v[16:17], v[16:17], 0, s[4:5]
	v_cvt_pk_bf16_f32 v115, v48, v49
	global_load_dwordx4 v[144:147], v[16:17], off
	global_load_dwordx4 v[76:79], v[16:17], off offset:64
	global_load_dwordx4 v[48:51], v[16:17], off offset:128
	global_load_dwordx4 v[44:47], v[16:17], off offset:192
	v_lshl_add_u32 v122, v208, 4, v120
	v_cvt_pk_bf16_f32 v118, v18, v19
	v_lshl_add_u32 v123, v207, 4, v120
	v_lshl_add_u32 v121, v206, 4, v120
	v_lshl_add_u32 v120, v205, 4, v120
	ds_read_b128 v[148:151], v122
	ds_read_b128 v[152:155], v123
	ds_read_b128 v[156:159], v121
	ds_read_b128 v[160:163], v120
	ds_read_b128 v[164:167], v122 offset:4096
	ds_read_b128 v[168:171], v123 offset:4096
	ds_read_b128 v[172:175], v121 offset:4096
	ds_read_b128 v[210:213], v120 offset:4096
	s_waitcnt lgkmcnt(7)
	v_mfma_f32_16x16x32_bf16 v[0:3], v[148:151], v[92:95], v[0:3]
	v_mfma_f32_16x16x32_bf16 v[4:7], v[148:151], v[96:99], v[4:7]
	ds_read_b128 v[148:151], v122 offset:8192
	s_waitcnt lgkmcnt(7)
	v_mfma_f32_16x16x32_bf16 v[0:3], v[152:155], v[84:87], v[0:3]
	v_mfma_f32_16x16x32_bf16 v[4:7], v[152:155], v[88:91], v[4:7]
	ds_read_b128 v[152:155], v123 offset:8192
	s_waitcnt lgkmcnt(7)
	v_mfma_f32_16x16x32_bf16 v[0:3], v[156:159], v[80:83], v[0:3]
	v_mfma_f32_16x16x32_bf16 v[4:7], v[156:159], v[108:111], v[4:7]
	ds_read_b128 v[156:159], v121 offset:8192
	s_waitcnt lgkmcnt(7)
	v_mfma_f32_16x16x32_bf16 v[0:3], v[160:163], v[112:115], v[0:3]
	v_mfma_f32_16x16x32_bf16 v[4:7], v[160:163], v[116:119], v[4:7]
	ds_read_b128 v[160:163], v120 offset:8192
	s_waitcnt lgkmcnt(7)
	v_mfma_f32_16x16x32_bf16 v[16:19], v[164:167], v[96:99], v[12:15]
	v_mfma_f32_16x16x32_bf16 v[12:15], v[164:167], v[92:95], v[104:107]
	ds_read_b128 v[164:167], v122 offset:12288
	s_waitcnt lgkmcnt(7)
	v_mfma_f32_16x16x32_bf16 v[12:15], v[168:171], v[84:87], v[12:15]
	v_mfma_f32_16x16x32_bf16 v[16:19], v[168:171], v[88:91], v[16:19]
	ds_read_b128 v[168:171], v123 offset:12288
	s_waitcnt lgkmcnt(7)
	v_mfma_f32_16x16x32_bf16 v[12:15], v[172:175], v[80:83], v[12:15]
	v_mfma_f32_16x16x32_bf16 v[16:19], v[172:175], v[108:111], v[16:19]
	ds_read_b128 v[172:175], v121 offset:12288
	s_waitcnt lgkmcnt(7)
	v_mfma_f32_16x16x32_bf16 v[12:15], v[210:213], v[112:115], v[12:15]
	v_mfma_f32_16x16x32_bf16 v[16:19], v[210:213], v[116:119], v[16:19]
	ds_read_b128 v[210:213], v120 offset:12288
	s_waitcnt lgkmcnt(7)
; #define LAS __attribute__((address_space(3)))
; template <int MODE> __device__ __forceinline__ void ssd_scan_phase(Frame& F, int j, bool ctx_out) {
;     ...
;                 for (int nt = 0; nt < 8; ++nt) {
; #pragma unroll
;                     for (int ks = 0; ks < 4; ++ks) { const bf16x8 bfr = *(const LAS bf16x8*)(BS + (16 * nt + fr) * 256 + (((4 * ks + fq) ^ fr) << 4));
;                         hT[nt][0] = __builtin_amdgcn_mfma_f32_16x16x32_bf16(bfr, xw[0][ks], hT[nt][0], 0, 0, 0);
;                         hT[nt][1] = __builtin_amdgcn_mfma_f32_16x16x32_bf16(bfr, xw[1][ks], hT[nt][1], 0, 0, 0); }
;                     if (nt & 1) __builtin_amdgcn_sched_barrier(0);
;                 }
	v_mfma_f32_16x16x32_bf16 v[20:23], v[148:151], v[92:95], v[20:23]
	v_mfma_f32_16x16x32_bf16 v[24:27], v[148:151], v[96:99], v[24:27]
	ds_read_b128 v[148:151], v122 offset:16384
	s_waitcnt lgkmcnt(7)
	v_mfma_f32_16x16x32_bf16 v[20:23], v[152:155], v[84:87], v[20:23]
	v_mfma_f32_16x16x32_bf16 v[24:27], v[152:155], v[88:91], v[24:27]
	ds_read_b128 v[152:155], v123 offset:16384
	s_waitcnt lgkmcnt(7)
	v_mfma_f32_16x16x32_bf16 v[20:23], v[156:159], v[80:83], v[20:23]
	v_mfma_f32_16x16x32_bf16 v[24:27], v[156:159], v[108:111], v[24:27]
	ds_read_b128 v[156:159], v121 offset:16384
	s_waitcnt lgkmcnt(7)
	v_mfma_f32_16x16x32_bf16 v[20:23], v[160:163], v[112:115], v[20:23]
	v_mfma_f32_16x16x32_bf16 v[24:27], v[160:163], v[116:119], v[24:27]
	ds_read_b128 v[160:163], v120 offset:16384
	s_waitcnt lgkmcnt(7)
	v_mfma_f32_16x16x32_bf16 v[28:31], v[164:167], v[92:95], v[28:31]
	v_mfma_f32_16x16x32_bf16 v[32:35], v[164:167], v[96:99], v[32:35]
	ds_read_b128 v[164:167], v122 offset:20480
	s_waitcnt lgkmcnt(7)
	v_mfma_f32_16x16x32_bf16 v[28:31], v[168:171], v[84:87], v[28:31]
	v_mfma_f32_16x16x32_bf16 v[32:35], v[168:171], v[88:91], v[32:35]
	ds_read_b128 v[168:171], v123 offset:20480
	s_waitcnt lgkmcnt(7)
	v_mfma_f32_16x16x32_bf16 v[28:31], v[172:175], v[80:83], v[28:31]
	v_mfma_f32_16x16x32_bf16 v[32:35], v[172:175], v[108:111], v[32:35]
	ds_read_b128 v[172:175], v121 offset:20480
	s_waitcnt lgkmcnt(7)
	v_mfma_f32_16x16x32_bf16 v[28:31], v[210:213], v[112:115], v[28:31]
	v_mfma_f32_16x16x32_bf16 v[32:35], v[210:213], v[116:119], v[32:35]
	ds_read_b128 v[210:213], v120 offset:20480
	s_waitcnt lgkmcnt(7)
	v_mfma_f32_16x16x32_bf16 v[36:39], v[148:151], v[92:95], v[36:39]
	v_mfma_f32_16x16x32_bf16 v[40:43], v[148:151], v[96:99], v[40:43]
	ds_read_b128 v[148:151], v122 offset:24576
	s_waitcnt lgkmcnt(7)
	v_mfma_f32_16x16x32_bf16 v[36:39], v[152:155], v[84:87], v[36:39]
	v_mfma_f32_16x16x32_bf16 v[40:43], v[152:155], v[88:91], v[40:43]
	ds_read_b128 v[152:155], v123 offset:24576
	s_waitcnt lgkmcnt(7)
	v_mfma_f32_16x16x32_bf16 v[36:39], v[156:159], v[80:83], v[36:39]
	v_mfma_f32_16x16x32_bf16 v[40:43], v[156:159], v[108:111], v[40:43]
	ds_read_b128 v[156:159], v121 offset:24576
	s_waitcnt lgkmcnt(7)
	v_mfma_f32_16x16x32_bf16 v[36:39], v[160:163], v[112:115], v[36:39]
	v_mfma_f32_16x16x32_bf16 v[40:43], v[160:163], v[116:119], v[40:43]
	ds_read_b128 v[160:163], v120 offset:24576
	s_waitcnt lgkmcnt(7)
	v_mfma_f32_16x16x32_bf16 v[52:55], v[164:167], v[92:95], v[52:55]
	v_mfma_f32_16x16x32_bf16 v[56:59], v[164:167], v[96:99], v[56:59]
	ds_read_b128 v[164:167], v122 offset:28672
	s_waitcnt lgkmcnt(7)
	v_mfma_f32_16x16x32_bf16 v[52:55], v[168:171], v[84:87], v[52:55]
	v_mfma_f32_16x16x32_bf16 v[56:59], v[168:171], v[88:91], v[56:59]
	ds_read_b128 v[168:171], v123 offset:28672
	s_waitcnt lgkmcnt(7)
	v_mfma_f32_16x16x32_bf16 v[52:55], v[172:175], v[80:83], v[52:55]
	v_mfma_f32_16x16x32_bf16 v[56:59], v[172:175], v[108:111], v[56:59]
	ds_read_b128 v[172:175], v121 offset:28672
	s_waitcnt lgkmcnt(7)
	v_mfma_f32_16x16x32_bf16 v[52:55], v[210:213], v[112:115], v[52:55]
	v_mfma_f32_16x16x32_bf16 v[56:59], v[210:213], v[116:119], v[56:59]
	ds_read_b128 v[210:213], v120 offset:28672
	s_waitcnt lgkmcnt(7)
	v_mfma_f32_16x16x32_bf16 v[60:63], v[148:151], v[92:95], v[60:63]
	v_mfma_f32_16x16x32_bf16 v[64:67], v[148:151], v[96:99], v[64:67]
	s_waitcnt lgkmcnt(6)
	v_mfma_f32_16x16x32_bf16 v[60:63], v[152:155], v[84:87], v[60:63]
	v_mfma_f32_16x16x32_bf16 v[64:67], v[152:155], v[88:91], v[64:67]
	s_waitcnt lgkmcnt(5)
	v_mfma_f32_16x16x32_bf16 v[60:63], v[156:159], v[80:83], v[60:63]
	v_mfma_f32_16x16x32_bf16 v[64:67], v[156:159], v[108:111], v[64:67]
	s_waitcnt lgkmcnt(4)
	v_mfma_f32_16x16x32_bf16 v[60:63], v[160:163], v[112:115], v[60:63]
	v_mfma_f32_16x16x32_bf16 v[64:67], v[160:163], v[116:119], v[64:67]
	s_waitcnt lgkmcnt(3)
	v_mfma_f32_16x16x32_bf16 v[68:71], v[164:167], v[92:95], v[68:71]
	v_mfma_f32_16x16x32_bf16 v[72:75], v[164:167], v[96:99], v[72:75]
	s_waitcnt lgkmcnt(2)
	v_mfma_f32_16x16x32_bf16 v[68:71], v[168:171], v[84:87], v[68:71]
	v_mfma_f32_16x16x32_bf16 v[72:75], v[168:171], v[88:91], v[72:75]
	s_waitcnt lgkmcnt(1)
	v_mfma_f32_16x16x32_bf16 v[68:71], v[172:175], v[80:83], v[68:71]
	v_mfma_f32_16x16x32_bf16 v[72:75], v[172:175], v[108:111], v[72:75]
	s_waitcnt lgkmcnt(0)
	v_mfma_f32_16x16x32_bf16 v[68:71], v[210:213], v[112:115], v[68:71]
	v_mfma_f32_16x16x32_bf16 v[72:75], v[210:213], v[116:119], v[72:75]
	s_cmp_eq_u32 s40, 18
	s_mov_b32 s4, s40
	s_cbranch_scc1 .LBB0_471

; #define LAS __attribute__((address_space(3)))
; #define VM_WAIT() asm volatile("s_waitcnt vmcnt(0)" ::: "memory")
; __device__ __forceinline__ float softplus_f(float x) { return x > 15.f ? x : __logf(1.0f + __expf(x)); }
; template <int MODE> __device__ __forceinline__ void ssd_scan_phase(Frame& F, int j, bool ctx_out) {
;     ...
;             if (!(MODE & 16)) {
;                 const float dt0 = softplus_f(dtr0 + dtbias), dt1 = softplus_f(dtr1 + dtbias);
;                 const float dA0 = dt0 * a_h, dA1 = dt1 * a_h;
;                 const float p0 = incl_scan64(dA0, lane), tot0 = __builtin_bit_cast(float, __builtin_amdgcn_readlane(__builtin_bit_cast(int, p0), 63)), p1 = incl_scan64(dA1, lane) + tot0; tot = __builtin_bit_cast(float, __builtin_amdgcn_readlane(__builtin_bit_cast(int, p1), 63));
;                 const float c0 = dir == 0 ? p0 : tot - p0 + dA0, c1 = dir == 0 ? p1 : tot - p1 + dA1;
;                 tab[lane] = c0; tab[64 + lane] = c1; tab[128 + lane] = dt0; tab[192 + lane] = dt1;
;                 tab[256 + lane] = dt0 * exp2f(tot - c0); tab[320 + lane] = dt1 * exp2f(tot - c1);
;                 asm volatile("" ::: "memory");
;                 const int r0 = dir == 0 ? (lane | 31) : (lane & ~31);
;                 tab[384 + lane] = dt0 * __builtin_amdgcn_exp2f(tab[r0] - c0); tab[448 + lane] = dt1 * __builtin_amdgcn_exp2f(tab[64 + r0] - c1);
;             }
;             VM_WAIT(); __syncthreads();
;             bf16x8 xs2[2][4];
; #pragma unroll
;             for (int ks = 0; ks < 4; ++ks) { const f32x4 fa = *(const LAS f32x4*)(tab + 384 + 32 * ks + 8 * fq), fb = *(const LAS f32x4*)(tab + 384 + 32 * ks + 8 * fq + 4);
.LBB0_484:
	s_waitcnt vmcnt(8)
	v_add_f32_e32 v80, v202, v189
	v_mul_f32_e32 v81, 0x3fb8aa3b, v80
	v_exp_f32_e32 v81, v81
	v_mbcnt_lo_u32_b32 v209, -1, 0
	v_mbcnt_hi_u32_b32 v209, -1, v209
	s_and_b64 s[94:95], s[28:29], s[46:47]
	v_ashrrev_i32_e32 v164, 4, v209
	v_add_f32_e32 v81, 1.0, v81
	v_cmp_gt_f32_e32 vcc, s85, v81
	v_lshl_add_u32 v197, v164, 5, s18
	s_add_i32 s27, 0, 0x8000
	v_cndmask_b32_e64 v82, 0, 32, vcc
	v_ldexp_f32 v81, v81, v82
	v_log_f32_e32 v81, v81
	v_add_f32_e32 v82, v202, v193
	v_mul_f32_e32 v83, 0x3fb8aa3b, v82
	v_exp_f32_e32 v83, v83
	v_mul_f32_e32 v84, 0x3f317217, v81
	v_fma_f32 v84, v81, s70, -v84
	v_fmac_f32_e32 v84, 0x3377d1cf, v81
	v_fmac_f32_e32 v84, 0x3f317217, v81
	v_cmp_lt_f32_e64 s[40:41], |v81|, s68
	v_add_f32_e32 v83, 1.0, v83
	s_add_i32 s43, 0, 0x10000
	v_cndmask_b32_e64 v81, v81, v84, s[40:41]
	v_cndmask_b32_e32 v84, 0, v242, vcc
	v_cmp_gt_f32_e32 vcc, s85, v83
	v_sub_f32_e32 v81, v81, v84
	v_cmp_lt_f32_e64 s[40:41], s69, v80
	v_cndmask_b32_e64 v85, 0, 32, vcc
	v_ldexp_f32 v83, v83, v85
	v_log_f32_e32 v83, v83
	v_cndmask_b32_e64 v80, v81, v80, s[40:41]
	v_mov_b32_e32 v84, v177
	v_and_b32_e32 v176, 15, v209
	v_mul_f32_e32 v81, 0x3f317217, v83
	v_fma_f32 v81, v83, s70, -v81
	v_fmac_f32_e32 v81, 0x3377d1cf, v83
	v_fmac_f32_e32 v81, 0x3f317217, v83
	v_cmp_lt_f32_e64 s[40:41], |v83|, s68
	v_lshlrev_b32_e32 v180, 3, v164
	v_add_u32_e32 v92, 4, v164
	v_cndmask_b32_e64 v81, v83, v81, s[40:41]
	v_cndmask_b32_e32 v83, 0, v242, vcc
	v_sub_f32_e32 v81, v81, v83
	v_cmp_lt_f32_e32 vcc, s69, v82
	s_xor_b64 s[40:41], s[94:95], -1
	v_add_u32_e32 v93, 8, v164
	v_cndmask_b32_e32 v81, v81, v82, vcc
	v_mul_f32_e32 v82, v204, v80
	v_mul_f32_e32 v83, v204, v81
	v_add_u32_e32 v94, 12, v164
	v_mov_b32_dpp v82, v82 row_shr:1 row_mask:0xf bank_mask:0xf bound_ctrl:1
	v_fmac_f32_e32 v82, v204, v80
	v_mov_b32_dpp v83, v83 row_shr:1 row_mask:0xf bank_mask:0xf bound_ctrl:1
	v_fmac_f32_e32 v83, v204, v81
	v_add_f32_dpp v82, v82, v82 row_shr:2 row_mask:0xf bank_mask:0xf bound_ctrl:1
	v_ashrrev_i32_e32 v181, 31, v180
	v_add_f32_dpp v83, v83, v83 row_shr:2 row_mask:0xf bank_mask:0xf bound_ctrl:1
	v_add_f32_dpp v82, v82, v82 row_shr:4 row_mask:0xf bank_mask:0xf bound_ctrl:1
	v_ashrrev_i32_e32 v165, 5, v209
	v_add_f32_dpp v83, v83, v83 row_shr:4 row_mask:0xf bank_mask:0xf bound_ctrl:1
	v_add_f32_dpp v82, v82, v82 row_shr:8 row_mask:0xf bank_mask:0xf bound_ctrl:1
	v_lshlrev_b32_e32 v132, 8, v176
	v_add_f32_dpp v83, v83, v83 row_shr:8 row_mask:0xf bank_mask:0xf bound_ctrl:1
	v_mov_b32_dpp v84, v82 row_bcast:15 row_mask:0xa bank_mask:0xf
	v_add_f32_e32 v82, v82, v84
	v_mov_b32_e32 v84, v177
	v_xor_b32_e32 v208, v164, v176
	v_xor_b32_e32 v207, v92, v176
	v_mov_b32_dpp v84, v82 row_bcast:31 row_mask:0xc bank_mask:0xf
	v_add_f32_e32 v82, v82, v84
	v_mov_b32_e32 v84, v177
	v_readlane_b32 s17, v82, 63
	v_xor_b32_e32 v206, v93, v176
	v_mov_b32_dpp v84, v83 row_bcast:15 row_mask:0xa bank_mask:0xf
	v_add_f32_e32 v83, v83, v84
	v_mov_b32_e32 v84, v177
	v_xor_b32_e32 v205, v94, v176
	v_and_b32_e32 v195, 8, v180
	v_mov_b32_dpp v84, v83 row_bcast:31 row_mask:0xc bank_mask:0xf
	v_add_f32_e32 v83, v83, v84
	v_add_f32_e32 v83, s17, v83
	s_and_b32 s17, s4, 1
	v_readlane_b32 s86, v83, 63
	s_cmp_eq_u32 s17, 0
	s_cselect_b32 s26, s27, s43
	v_sub_f32_e32 v84, s86, v82
	v_fmac_f32_e32 v84, v204, v80
	v_cndmask_b32_e64 v82, v84, v82, s[38:39]
	v_sub_f32_e32 v84, s86, v83
	v_fmac_f32_e32 v84, v204, v81
	v_sub_f32_e32 v85, s86, v82
	v_cndmask_b32_e64 v83, v84, v83, s[38:39]
	v_cmp_gt_f32_e32 vcc, s71, v85
	v_sub_f32_e32 v87, s86, v83
	v_lshl_add_u32 v84, v209, 2, s18
	v_cndmask_b32_e32 v86, 0, v243, vcc
	v_add_f32_e32 v85, v85, v86
	v_cndmask_b32_e32 v86, 0, v244, vcc
	v_cmp_gt_f32_e32 vcc, s71, v87
	v_exp_f32_e32 v85, v85
	ds_write2st64_b32 v84, v82, v83 offset1:1
	ds_write2st64_b32 v84, v80, v81 offset0:2 offset1:3
	v_cndmask_b32_e32 v88, 0, v243, vcc
	v_add_f32_e32 v87, v87, v88
	v_exp_f32_e32 v87, v87
	v_ldexp_f32 v85, v85, v86
	v_cndmask_b32_e32 v86, 0, v244, vcc
	v_mul_f32_e32 v85, v80, v85
	v_ldexp_f32 v86, v87, v86
	v_mul_f32_e32 v86, v81, v86
	ds_write2st64_b32 v84, v85, v86 offset0:4 offset1:5
	v_and_b32_e32 v85, 0x3fffffe0, v209
	v_lshl_add_u32 v85, v85, 2, s72
	ds_read_b32 v86, v85
	s_cselect_b32 s87, s43, s27
	s_and_b64 vcc, exec, s[94:95]
	s_waitcnt lgkmcnt(0)
	v_sub_f32_e32 v82, v86, v82
	v_exp_f32_e32 v82, v82
	s_nop 0
	v_mul_f32_e32 v80, v80, v82
	ds_write_b32 v84, v80 offset:1536
	ds_read_b32 v80, v85 offset:256
	s_waitcnt lgkmcnt(0)
	v_sub_f32_e32 v80, v80, v83
	v_exp_f32_e32 v80, v80
	s_nop 0
	v_mul_f32_e32 v80, v81, v80
	ds_write_b32 v84, v80 offset:1792
	s_waitcnt vmcnt(0)
	s_waitcnt lgkmcnt(0)
	s_barrier
	ds_read_b128 v[96:99], v197 offset:1536
	ds_read_b128 v[84:87], v197 offset:1552
	ds_read_b128 v[88:91], v197 offset:1664
	ds_read_b128 v[80:83], v197 offset:1680
	ds_read_b128 v[116:119], v197 offset:1792
	ds_read_b128 v[112:115], v197 offset:1808
	ds_read_b128 v[108:111], v197 offset:1920
	ds_read_b128 v[104:107], v197 offset:1936
	s_cbranch_vccnz .LBB0_487
; #define LAS __attribute__((address_space(3)))
; __device__ __forceinline__ unsigned cvt_pk_bf16(float lo, float hi) { const f32x2 v = {lo, hi}; return __builtin_bit_cast(unsigned, __builtin_convertvector(v, bf16x2_t)); }
; template <int MODE> __device__ __forceinline__ void ssd_scan_phase(Frame& F, int j, bool ctx_out) {
;     ...
;             if (need_y && !(MODE & 2)) {
;                 bf16x8 cf[4];
; #pragma unroll
;                 for (int ks = 0; ks < 4; ++ks) cf[ks] = *(const LAS bf16x8*)(CS + (16 * w + fr) * 256 + (((4 * ks + fq) ^ fr) << 4));
; #pragma unroll 2
;                 for (int st = 0; st < 8; ++st) { f32x4 acc = (f32x4){0.f, 0.f, 0.f, 0.f};
; #pragma unroll
;                     for (int ks = 0; ks < 4; ++ks) { const bf16x8 bfr = *(const LAS bf16x8*)(BS + (16 * st + fr) * 256 + (((4 * ks + fq) ^ fr) << 4)); acc = __builtin_amdgcn_mfma_f32_16x16x32_bf16(bfr, cf[ks], acc, 0, 0, 0); }
;                     u32x2 o; o.x = cvt_pk_bf16(acc[0], acc[1]); o.y = cvt_pk_bf16(acc[2], acc[3]);
;                     *(LAS u32x2*)(GS + (16 * w + fr) * 256 + (((2 * st + (fq >> 1)) ^ fr) << 4) + (fq & 1) * 8) = o; }
;             }
	v_add_u32_e32 v124, s88, v132
	v_lshlrev_b32_e32 v149, 4, v208
	v_lshlrev_b32_e32 v148, 4, v207
	v_lshlrev_b32_e32 v135, 4, v206
	v_lshlrev_b32_e32 v134, 4, v205
	v_add_u32_e32 v92, v124, v149
	v_add_u32_e32 v120, v124, v148
	v_add_u32_e32 v125, v124, v135
	v_add_u32_e32 v128, v124, v134
	ds_read_b128 v[92:95], v92
	ds_read_b128 v[120:123], v120
	ds_read_b128 v[124:127], v125
	ds_read_b128 v[128:131], v128
	s_add_i32 s17, s87, s19
	v_add3_u32 v133, s17, v132, v195
	v_add3_u32 v134, v132, v134, s26
	v_add3_u32 v135, v132, v135, s26
	v_add3_u32 v148, v132, v148, s26
	v_add3_u32 v149, v132, v149, s26
	s_movk_i32 s43, 0x8000
	v_mov_b32_e32 v150, v165
	ds_read_b128 v[210:213], v149
	ds_read_b128 v[214:217], v148
	ds_read_b128 v[218:221], v135
	ds_read_b128 v[222:225], v134
	ds_read_b128 v[226:229], v149 offset:4096
	ds_read_b128 v[230:233], v148 offset:4096
	ds_read_b128 v[234:237], v135 offset:4096
	ds_read_b128 v[246:249], v134 offset:4096
	s_waitcnt lgkmcnt(4)
	v_mfma_f32_16x16x32_bf16 v[182:185], v[210:213], v[92:95], 0
	v_mfma_f32_16x16x32_bf16 v[182:185], v[214:217], v[120:123], v[182:185]
	v_mfma_f32_16x16x32_bf16 v[182:185], v[218:221], v[124:127], v[182:185]
	v_mfma_f32_16x16x32_bf16 v[182:185], v[222:225], v[128:131], v[182:185]
	ds_read_b128 v[210:213], v149 offset:8192
	ds_read_b128 v[214:217], v148 offset:8192
	ds_read_b128 v[218:221], v135 offset:8192
	ds_read_b128 v[222:225], v134 offset:8192
	s_waitcnt lgkmcnt(4)
	v_mfma_f32_16x16x32_bf16 v[198:201], v[226:229], v[92:95], 0
	v_mfma_f32_16x16x32_bf16 v[198:201], v[230:233], v[120:123], v[198:201]
	v_mfma_f32_16x16x32_bf16 v[198:201], v[234:237], v[124:127], v[198:201]
	v_mfma_f32_16x16x32_bf16 v[198:201], v[246:249], v[128:131], v[198:201]
	v_xor_b32_e32 v186, v165, v176
	s_nop 0
	v_lshl_add_u32 v186, v186, 4, v133
	v_cvt_pk_bf16_f32 v182, v182, v183
	v_cvt_pk_bf16_f32 v183, v184, v185
	ds_write_b64 v186, v[182:183]
	ds_read_b128 v[226:229], v149 offset:12288
	ds_read_b128 v[230:233], v148 offset:12288
	ds_read_b128 v[234:237], v135 offset:12288
	ds_read_b128 v[246:249], v134 offset:12288
	s_waitcnt lgkmcnt(4)
	v_mfma_f32_16x16x32_bf16 v[182:185], v[210:213], v[92:95], 0
	v_mfma_f32_16x16x32_bf16 v[182:185], v[214:217], v[120:123], v[182:185]
	v_mfma_f32_16x16x32_bf16 v[182:185], v[218:221], v[124:127], v[182:185]
	v_mfma_f32_16x16x32_bf16 v[182:185], v[222:225], v[128:131], v[182:185]
	v_add_u32_e32 v186, 2, v165
	v_xor_b32_e32 v186, v186, v176
	v_lshl_add_u32 v186, v186, 4, v133
	v_cvt_pk_bf16_f32 v198, v198, v199
	v_cvt_pk_bf16_f32 v199, v200, v201
	ds_write_b64 v186, v[198:199]
	ds_read_b128 v[210:213], v149 offset:16384
	ds_read_b128 v[214:217], v148 offset:16384
	ds_read_b128 v[218:221], v135 offset:16384
	ds_read_b128 v[222:225], v134 offset:16384
	s_waitcnt lgkmcnt(4)
	v_mfma_f32_16x16x32_bf16 v[198:201], v[226:229], v[92:95], 0
	v_mfma_f32_16x16x32_bf16 v[198:201], v[230:233], v[120:123], v[198:201]
	v_mfma_f32_16x16x32_bf16 v[198:201], v[234:237], v[124:127], v[198:201]
	v_mfma_f32_16x16x32_bf16 v[198:201], v[246:249], v[128:131], v[198:201]
	v_add_u32_e32 v186, 4, v165
	v_xor_b32_e32 v186, v186, v176
	v_lshl_add_u32 v186, v186, 4, v133
	v_cvt_pk_bf16_f32 v182, v182, v183
	v_cvt_pk_bf16_f32 v183, v184, v185
	ds_write_b64 v186, v[182:183]
	ds_read_b128 v[226:229], v149 offset:20480
	ds_read_b128 v[230:233], v148 offset:20480
	ds_read_b128 v[234:237], v135 offset:20480
	ds_read_b128 v[246:249], v134 offset:20480
	s_waitcnt lgkmcnt(4)
	v_mfma_f32_16x16x32_bf16 v[182:185], v[210:213], v[92:95], 0
	v_mfma_f32_16x16x32_bf16 v[182:185], v[214:217], v[120:123], v[182:185]
	v_mfma_f32_16x16x32_bf16 v[182:185], v[218:221], v[124:127], v[182:185]
	v_mfma_f32_16x16x32_bf16 v[182:185], v[222:225], v[128:131], v[182:185]
	v_add_u32_e32 v186, 6, v165
	v_xor_b32_e32 v186, v186, v176
	v_lshl_add_u32 v186, v186, 4, v133
	v_cvt_pk_bf16_f32 v198, v198, v199
	v_cvt_pk_bf16_f32 v199, v200, v201
	ds_write_b64 v186, v[198:199]
	ds_read_b128 v[210:213], v149 offset:24576
	ds_read_b128 v[214:217], v148 offset:24576
	ds_read_b128 v[218:221], v135 offset:24576
	ds_read_b128 v[222:225], v134 offset:24576
	s_waitcnt lgkmcnt(4)
	v_mfma_f32_16x16x32_bf16 v[198:201], v[226:229], v[92:95], 0
	v_mfma_f32_16x16x32_bf16 v[198:201], v[230:233], v[120:123], v[198:201]
	v_mfma_f32_16x16x32_bf16 v[198:201], v[234:237], v[124:127], v[198:201]
	v_mfma_f32_16x16x32_bf16 v[198:201], v[246:249], v[128:131], v[198:201]
	v_add_u32_e32 v186, 8, v165
	v_xor_b32_e32 v186, v186, v176
	v_lshl_add_u32 v186, v186, 4, v133
	v_cvt_pk_bf16_f32 v182, v182, v183
	v_cvt_pk_bf16_f32 v183, v184, v185
	ds_write_b64 v186, v[182:183]
	ds_read_b128 v[226:229], v149 offset:28672
	ds_read_b128 v[230:233], v148 offset:28672
	ds_read_b128 v[234:237], v135 offset:28672
	ds_read_b128 v[246:249], v134 offset:28672
	s_waitcnt lgkmcnt(4)
	v_mfma_f32_16x16x32_bf16 v[182:185], v[210:213], v[92:95], 0
	v_mfma_f32_16x16x32_bf16 v[182:185], v[214:217], v[120:123], v[182:185]
	v_mfma_f32_16x16x32_bf16 v[182:185], v[218:221], v[124:127], v[182:185]
	v_mfma_f32_16x16x32_bf16 v[182:185], v[222:225], v[128:131], v[182:185]
	v_add_u32_e32 v186, 10, v165
	v_xor_b32_e32 v186, v186, v176
	v_lshl_add_u32 v186, v186, 4, v133
	v_cvt_pk_bf16_f32 v198, v198, v199
	v_cvt_pk_bf16_f32 v199, v200, v201
	ds_write_b64 v186, v[198:199]
	s_waitcnt lgkmcnt(0)
	v_mfma_f32_16x16x32_bf16 v[198:201], v[226:229], v[92:95], 0
	v_mfma_f32_16x16x32_bf16 v[198:201], v[230:233], v[120:123], v[198:201]
	v_mfma_f32_16x16x32_bf16 v[198:201], v[234:237], v[124:127], v[198:201]
	v_mfma_f32_16x16x32_bf16 v[198:201], v[246:249], v[128:131], v[198:201]
	v_add_u32_e32 v186, 12, v165
	v_xor_b32_e32 v186, v186, v176
	v_lshl_add_u32 v186, v186, 4, v133
	v_cvt_pk_bf16_f32 v182, v182, v183
	v_cvt_pk_bf16_f32 v183, v184, v185
	ds_write_b64 v186, v[182:183]
	v_add_u32_e32 v186, 14, v165
	v_xor_b32_e32 v186, v186, v176
	v_lshl_add_u32 v186, v186, 4, v133
	s_nop 4
	v_cvt_pk_bf16_f32 v198, v198, v199
	v_cvt_pk_bf16_f32 v199, v200, v201
	ds_write_b64 v186, v[198:199]

; #define LAS __attribute__((address_space(3)))
; template <int MODE> __device__ __forceinline__ void ssd_scan_phase(Frame& F, int j, bool ctx_out) {
;     ...
; #pragma unroll
;                     for (int q = 0; q < 4; ++q) {
;                         const u32x2 lo = *(const LAS u32x2*)(CS + l * 256 + (((4 * q + (fq >> 1)) ^ fr) << 4) + (fq & 1) * 8), hi = *(const LAS u32x2*)(CS + l * 256 + (((4 * q + 2 + (fq >> 1)) ^ fr) << 4) + (fq & 1) * 8);
;                         u32x4 c4; c4.x = lo.x; c4.y = lo.y; c4.z = hi.x; c4.w = hi.y; const bf16x8 cfr = __builtin_bit_cast(bf16x8, c4);
;                         acco[0] = __builtin_amdgcn_mfma_f32_16x16x32_bf16(hf[0][q], cfr, acco[0], 0, 0, 0);
;                         acco[1] = __builtin_amdgcn_mfma_f32_16x16x32_bf16(hf[1][q], cfr, acco[1], 0, 0, 0);
;                     }
;                     {
;                         float gg[8]; unpack8(*(const LAS u32x4*)(GS + l * 256 + (((4 * kd + fq) ^ fr) << 4)), gg);
;                         const f32x4 ca = *(const LAS f32x4*)(tab + 32 * kd + 8 * fq), cb = *(const LAS f32x4*)(tab + 32 * kd + 8 * fq + 4);
;                         const f32x4 da = *(const LAS f32x4*)(tab + 128 + 32 * kd + 8 * fq), db = *(const LAS f32x4*)(tab + 128 + 32 * kd + 8 * fq + 4);
;                         const float cs[8] = {ca.x, ca.y, ca.z, ca.w, cb.x, cb.y, cb.z, cb.w}, ds[8] = {da.x, da.y, da.z, da.w, db.x, db.y, db.z, db.w};
;                         float m[8];
; #pragma unroll
;                         for (int jj = 0; jj < 8; ++jj) { const int s = 32 * kd + 8 * fq + jj; const bool valid = dir == 0 ? (s <= l) : (s >= l);
;                             const float e = valid ? __builtin_amdgcn_exp2f(cl - cs[jj]) : 0.f; m[jj] = gg[jj] * e * ds[jj]; if (dir == 0 && s == l) m[jj] += dsk; }
.LBB0_502:
	v_add3_u32 v161, 0, v156, v195
	v_add_u32_e32 v156, v161, v185
	v_add_u32_e32 v157, v161, v183
	ds_read_b64 v[162:163], v156
	ds_read_b64 v[164:165], v157
	v_add_u32_e32 v156, v161, v187
	v_add_u32_e32 v158, v161, v213
	ds_read_b64 v[156:157], v156
	ds_read_b32 v175, v214 offset:192
	ds_read_b64 v[158:159], v158
	s_waitcnt lgkmcnt(0)
	v_mfma_f32_16x16x32_bf16 v[166:169], v[116:119], v[162:165], 0
	v_add_u32_e32 v170, v161, v212
	v_add_u32_e32 v171, v161, v211
	v_add_u32_e32 v172, v161, v191
	v_mfma_f32_16x16x32_bf16 v[162:165], v[124:127], v[162:165], 0
	ds_read_b64 v[216:217], v170
	ds_read_b64 v[218:219], v171
	ds_read_b64 v[220:221], v172
	v_add_u32_e32 v161, v161, v210
	v_lshlrev_b32_e32 v172, 4, v207
	v_mfma_f32_16x16x32_bf16 v[166:169], v[112:115], v[156:159], v[166:169]
	ds_read_b64 v[222:223], v161
	v_add_u32_e32 v160, v160, v172
	s_mov_b32 s94, s92
	v_mfma_f32_16x16x32_bf16 v[156:159], v[120:123], v[156:159], v[162:165]
	s_mov_b32 s95, s92
	s_mov_b32 s93, s92
	s_waitcnt lgkmcnt(0)
	v_mfma_f32_16x16x32_bf16 v[162:165], v[108:111], v[216:219], v[166:169]
	s_nop 2
	ds_read_b128 v[168:171], v197 offset:128
	v_mfma_f32_16x16x32_bf16 v[156:159], v[128:131], v[216:219], v[156:159]
	ds_read_b128 v[216:219], v160
	s_waitcnt lgkmcnt(0)
	v_sub_f32_e32 v234, v174, v170
	v_mfma_f32_16x16x32_bf16 v[228:231], v[132:135], v[220:223], v[156:159]
	v_lshlrev_b32_e32 v178, 16, v216
	v_and_b32_e32 v179, 0xffff0000, v216
	v_lshlrev_b32_e32 v232, 16, v219
	s_nop 0
	v_sub_f32_e32 v156, v174, v168
	v_exp_f32_e32 v216, v156
	v_mfma_f32_16x16x32_bf16 v[224:227], v[104:107], v[220:223], v[162:165]
	v_lshlrev_b32_e32 v220, 16, v217
	v_and_b32_e32 v221, 0xffff0000, v217
	v_cndmask_b32_e64 v216, 0, v216, s[40:41]
	ds_read_b128 v[160:163], v197 offset:144
	ds_read_b128 v[164:167], v197 offset:640
	v_mul_f32_e32 v178, v216, v178
	v_and_b32_e32 v233, 0xffff0000, v219
	v_sub_f32_e32 v219, v174, v169
	v_lshlrev_b32_e32 v222, 16, v218
	s_waitcnt lgkmcnt(0)
	v_mul_f32_e32 v216, v164, v178
	v_fma_f32 v178, v164, v178, v203
	v_cndmask_b32_e64 v178, v216, v178, s[42:43]
	v_add_u32_e32 v216, 33, v180
	v_cmp_le_i32_e32 vcc, v216, v173
	v_and_b32_e32 v223, 0xffff0000, v218
	v_exp_f32_e32 v219, v219
	v_cndmask_b32_e64 v217, 0, 1, vcc
	v_cmp_ge_i32_e32 vcc, v216, v173
	v_exp_f32_e32 v234, v234
	v_sub_f32_e32 v235, v174, v171
	v_cndmask_b32_e64 v218, 0, 1, vcc
	v_cndmask_b32_e64 v217, v218, v217, s[38:39]
	v_and_b32_e32 v217, 1, v217
	v_cmp_eq_u32_e32 vcc, 1, v217
	v_exp_f32_e32 v235, v235
	v_sub_f32_e32 v236, v174, v160
	v_cndmask_b32_e32 v217, 0, v219, vcc
	v_mul_f32_e32 v179, v217, v179
	v_cmp_eq_u32_e32 vcc, v216, v173
	v_mul_f32_e32 v217, v165, v179
	v_fma_f32 v179, v165, v179, v203
	s_and_b64 vcc, s[38:39], vcc
	v_cndmask_b32_e32 v179, v217, v179, vcc
	v_add_u32_e32 v217, 34, v180
	v_cmp_le_i32_e32 vcc, v217, v173
	v_exp_f32_e32 v236, v236
	ds_read_b128 v[156:159], v197 offset:656
	v_cndmask_b32_e64 v218, 0, 1, vcc
	v_cmp_ge_i32_e32 vcc, v217, v173
	v_sub_f32_e32 v237, v174, v161
	v_exp_f32_e32 v237, v237
	v_cndmask_b32_e64 v219, 0, 1, vcc
	v_cndmask_b32_e64 v218, v219, v218, s[38:39]
	v_and_b32_e32 v218, 1, v218
	v_cmp_eq_u32_e32 vcc, 1, v218
	v_sub_f32_e32 v240, v174, v162
	v_exp_f32_e32 v240, v240
	v_cndmask_b32_e32 v218, 0, v234, vcc
	v_mul_f32_e32 v218, v218, v220
	v_cmp_eq_u32_e32 vcc, v217, v173
	v_mul_f32_e32 v219, v166, v218
	v_fma_f32 v218, v166, v218, v203
	s_and_b64 vcc, s[38:39], vcc
	v_cndmask_b32_e32 v234, v219, v218, vcc
	v_add_u32_e32 v218, 35, v180
	v_cmp_le_i32_e32 vcc, v218, v173
	v_sub_f32_e32 v246, v174, v163
	v_exp_f32_e32 v246, v246
	v_cndmask_b32_e64 v219, 0, 1, vcc
	v_cmp_ge_i32_e32 vcc, v218, v173
	v_exp_f32_e32 v174, v174
	s_nop 0
	v_cndmask_b32_e64 v220, 0, 1, vcc
	v_cndmask_b32_e64 v219, v220, v219, s[38:39]
	v_and_b32_e32 v219, 1, v219
	v_cmp_eq_u32_e32 vcc, 1, v219
	s_nop 1
	v_cndmask_b32_e32 v219, 0, v235, vcc
	v_mul_f32_e32 v219, v219, v221
	v_cmp_eq_u32_e32 vcc, v218, v173
	v_mul_f32_e32 v220, v167, v219
	v_fma_f32 v219, v167, v219, v203
	s_and_b64 vcc, s[38:39], vcc
	v_cndmask_b32_e32 v235, v220, v219, vcc
	v_add_u32_e32 v219, 36, v180
	v_cmp_le_i32_e32 vcc, v219, v173
	s_nop 1
	v_cndmask_b32_e64 v220, 0, 1, vcc
	v_cmp_ge_i32_e32 vcc, v219, v173
	s_nop 1
	v_cndmask_b32_e64 v221, 0, 1, vcc
	v_cndmask_b32_e64 v220, v221, v220, s[38:39]
	v_and_b32_e32 v220, 1, v220
	v_cmp_eq_u32_e32 vcc, 1, v220
	s_nop 1
	v_cndmask_b32_e32 v220, 0, v236, vcc
	v_mul_f32_e32 v220, v220, v222
	v_cmp_eq_u32_e32 vcc, v219, v173
	s_waitcnt lgkmcnt(0)
; __device__ __forceinline__ unsigned cvt_pk_bf16(float lo, float hi) { const f32x2 v = {lo, hi}; return __builtin_bit_cast(unsigned, __builtin_convertvector(v, bf16x2_t)); }
; __device__ __forceinline__ u32x4 pack8(const float (&f)[8]) { u32x4 w; w.x = cvt_pk_bf16(f[0], f[1]); w.y = cvt_pk_bf16(f[2], f[3]); w.z = cvt_pk_bf16(f[4], f[5]); w.w = cvt_pk_bf16(f[6], f[7]); return w; }
; template <int MODE> __device__ __forceinline__ void ssd_scan_phase(Frame& F, int j, bool ctx_out) {
;     ...
;                         const float cs[8] = {ca.x, ca.y, ca.z, ca.w, cb.x, cb.y, cb.z, cb.w}, ds[8] = {da.x, da.y, da.z, da.w, db.x, db.y, db.z, db.w};
;                         float m[8];
; #pragma unroll
;                         for (int jj = 0; jj < 8; ++jj) { const int s = 32 * kd + 8 * fq + jj; const bool valid = dir == 0 ? (s <= l) : (s >= l);
;                             const float e = valid ? __builtin_amdgcn_exp2f(cl - cs[jj]) : 0.f; m[jj] = gg[jj] * e * ds[jj]; if (dir == 0 && s == l) m[jj] += dsk; }
;                         const bf16x8 mf = __builtin_bit_cast(bf16x8, pack8(m));
;                         accd[0] = __builtin_amdgcn_mfma_f32_16x16x32_bf16(xa, mf, accd[0], 0, 0, 0);
;                         accd[1] = __builtin_amdgcn_mfma_f32_16x16x32_bf16(xb, mf, accd[1], 0, 0, 0);
;                     }
;                     const float el = __builtin_amdgcn_exp2f(cl);
; #pragma unroll
;                     for (int pt = 0; pt < 2; ++pt) { const f32x4 y = accd[pt] + acco[pt] * el; u32x2 o; o.x = cvt_pk_bf16(y[0], y[1]); o.y = cvt_pk_bf16(y[2], y[3]);
;                         *(u32x2*)(yout + (size_t)(row0 + l) * DI + h * 64 + ph * 32 + 16 * pt + 4 * fq) = o; }
	v_mul_f32_e32 v221, v156, v220
	v_fma_f32 v220, v156, v220, v203
	s_and_b64 vcc, s[38:39], vcc
	v_cndmask_b32_e32 v236, v221, v220, vcc
	v_add_u32_e32 v220, 37, v180
	v_cmp_le_i32_e32 vcc, v220, v173
	s_nop 1
	v_cndmask_b32_e64 v221, 0, 1, vcc
	v_cmp_ge_i32_e32 vcc, v220, v173
	s_nop 1
	v_cndmask_b32_e64 v222, 0, 1, vcc
	v_cndmask_b32_e64 v221, v222, v221, s[38:39]
	v_and_b32_e32 v221, 1, v221
	v_cmp_eq_u32_e32 vcc, 1, v221
	s_nop 1
	v_cndmask_b32_e32 v221, 0, v237, vcc
	v_mul_f32_e32 v221, v221, v223
	v_cmp_eq_u32_e32 vcc, v220, v173
	v_mul_f32_e32 v222, v157, v221
	v_fma_f32 v221, v157, v221, v203
	s_and_b64 vcc, s[38:39], vcc
	v_cndmask_b32_e32 v223, v222, v221, vcc
	v_add_u32_e32 v221, 38, v180
	v_cmp_le_i32_e32 vcc, v221, v173
	s_nop 1
	v_cndmask_b32_e64 v222, 0, 1, vcc
	v_cmp_ge_i32_e32 vcc, v221, v173
	s_nop 1
	v_cndmask_b32_e64 v237, 0, 1, vcc
	v_cndmask_b32_e64 v222, v237, v222, s[38:39]
	v_and_b32_e32 v222, 1, v222
	v_cmp_eq_u32_e32 vcc, 1, v222
	s_nop 1
	v_cndmask_b32_e32 v222, 0, v240, vcc
	v_mul_f32_e32 v222, v222, v232
	v_cmp_eq_u32_e32 vcc, v221, v173
	v_mul_f32_e32 v232, v158, v222
	v_fma_f32 v222, v158, v222, v203
	s_and_b64 vcc, s[38:39], vcc
	v_cndmask_b32_e32 v237, v232, v222, vcc
	v_add_u32_e32 v222, 39, v180
	v_cmp_le_i32_e32 vcc, v222, v173
	s_nop 1
	v_cndmask_b32_e64 v232, 0, 1, vcc
	v_cmp_ge_i32_e32 vcc, v222, v173
	s_nop 1
	v_cndmask_b32_e64 v240, 0, 1, vcc
	v_cndmask_b32_e64 v232, v240, v232, s[38:39]
	v_and_b32_e32 v232, 1, v232
	v_cmp_eq_u32_e32 vcc, 1, v232
	s_nop 1
	v_cndmask_b32_e32 v232, 0, v246, vcc
	v_mul_f32_e32 v232, v232, v233
	v_cmp_eq_u32_e32 vcc, v222, v173
	v_mul_f32_e32 v233, v159, v232
	v_fma_f32 v232, v159, v232, v203
	s_and_b64 vcc, s[38:39], vcc
	v_cndmask_b32_e32 v240, v233, v232, vcc
	v_cvt_pk_bf16_f32 v232, v178, v179
	v_cvt_pk_bf16_f32 v233, v234, v235
	v_cvt_pk_bf16_f32 v234, v236, v223
	v_cvt_pk_bf16_f32 v235, v237, v240
	s_and_b64 vcc, exec, s[46:47]
	s_waitcnt vmcnt(5)
	v_mfma_f32_16x16x32_bf16 v[144:147], v[148:151], v[232:235], v[144:147]
	v_mfma_f32_16x16x32_bf16 v[246:249], v[136:139], v[232:235], v[152:155]
	v_add_u32_e32 v232, s5, v173
	v_ashrrev_i32_e32 v233, 31, v232
	v_lshlrev_b64 v[232:233], 13, v[232:233]
	s_nop 3
	v_pk_fma_f32 v[146:147], v[174:175], v[230:231], v[146:147] op_sel_hi:[0,1,1]
	v_pk_fma_f32 v[144:145], v[174:175], v[228:229], v[144:145] op_sel_hi:[0,1,1]
	v_lshl_add_u64 v[232:233], v[198:199], 0, v[232:233]
	v_cvt_pk_bf16_f32 v144, v144, v145
	v_cvt_pk_bf16_f32 v145, v146, v147
	v_or_b32_e32 v173, 48, v176
	v_mov_b64_e32 v[154:155], s[94:95]
	v_pk_fma_f32 v[226:227], v[174:175], v[226:227], v[248:249] op_sel_hi:[0,1,1]
	v_pk_fma_f32 v[224:225], v[174:175], v[224:225], v[246:247] op_sel_hi:[0,1,1]
	global_store_dwordx2 v[232:233], v[144:145], off offset:32
	v_lshlrev_b32_e32 v223, 8, v173
	v_mov_b64_e32 v[146:147], s[94:95]
	v_mov_b64_e32 v[152:153], s[92:93]
	v_cvt_pk_bf16_f32 v224, v224, v225
	v_cvt_pk_bf16_f32 v225, v226, v227
	v_add_u32_e32 v174, s87, v223
	v_mov_b64_e32 v[144:145], s[92:93]
	global_store_dwordx2 v[232:233], v[224:225], off
	s_cbranch_vccz .LBB0_530
	s_and_b64 vcc, exec, s[44:45]
	s_cbranch_vccz .LBB0_531

; template <int MODE> __device__ __forceinline__ void ssd_scan_phase(Frame& F, int j, bool ctx_out) {
;     ...
;                     if ((lt & 1) == 0) { xb_cur = xb_nxt; if (kd + 1 < 4) xb_nxt = *(const bf16x8*)(xl + (size_t)16 * T + 32 * (kd + 1)); }
;                     const bf16x8 xa = xf[0][kd], xb = xb_cur;
; #pragma unroll
;                     for (int ks = 0; ks < 4; ++ks) {
;                         const bool full = dir == 0 ? (ks < kd) : (ks > kd);
;                         if (full) {
;                             const bf16x8 gf = *(const LAS bf16x8*)(GS + l * 256 + (((4 * ks + fq) ^ fr) << 4));
;                             const float f1 = __builtin_amdgcn_exp2f(cl - tab[dir == 0 ? 32 * ks + 31 : 32 * ks]);
;                             const f32x4 z4 = (f32x4){0.f, 0.f, 0.f, 0.f};
;                             const f32x4 t0 = __builtin_amdgcn_mfma_f32_16x16x32_bf16(xs2[0][ks], gf, z4, 0, 0, 0), t1 = __builtin_amdgcn_mfma_f32_16x16x32_bf16(xs2[1][ks], gf, z4, 0, 0, 0);
;                             accd[0] += t0 * f1; accd[1] += t1 * f1;
;                         }
;                     }
; #pragma unroll
;                     for (int q = 0; q < 4; ++q) {
;                         const u32x2 lo = *(const LAS u32x2*)(CS + l * 256 + (((4 * q + (fq >> 1)) ^ fr) << 4) + (fq & 1) * 8), hi = *(const LAS u32x2*)(CS + l * 256 + (((4 * q + 2 + (fq >> 1)) ^ fr) << 4) + (fq & 1) * 8);
;                         u32x4 c4; c4.x = lo.x; c4.y = lo.y; c4.z = hi.x; c4.w = hi.y; const bf16x8 cfr = __builtin_bit_cast(bf16x8, c4);
;                         acco[0] = __builtin_amdgcn_mfma_f32_16x16x32_bf16(hf[0][q], cfr, acco[0], 0, 0, 0);
;                         acco[1] = __builtin_amdgcn_mfma_f32_16x16x32_bf16(hf[1][q], cfr, acco[1], 0, 0, 0);
;                     }
;                     {
;                         float gg[8]; unpack8(*(const LAS u32x4*)(GS + l * 256 + (((4 * kd + fq) ^ fr) << 4)), gg);
;                         const f32x4 ca = *(const LAS f32x4*)(tab + 32 * kd + 8 * fq), cb = *(const LAS f32x4*)(tab + 32 * kd + 8 * fq + 4);
;                         const f32x4 da = *(const LAS f32x4*)(tab + 128 + 32 * kd + 8 * fq), db = *(const LAS f32x4*)(tab + 128 + 32 * kd + 8 * fq + 4);
;                         const float cs[8] = {ca.x, ca.y, ca.z, ca.w, cb.x, cb.y, cb.z, cb.w}, ds[8] = {da.x, da.y, da.z, da.w, db.x, db.y, db.z, db.w};
.LBB0_510:
	v_add3_u32 v157, 0, v152, v195
	v_add_u32_e32 v152, v157, v185
	v_add_u32_e32 v153, v157, v183
	ds_read_b64 v[158:159], v152
	ds_read_b64 v[160:161], v153
	v_add_u32_e32 v152, v157, v187
	v_add_u32_e32 v154, v157, v213
	ds_read_b64 v[152:153], v152
	ds_read_b32 v171, v214 offset:320
	ds_read_b64 v[154:155], v154
	s_waitcnt lgkmcnt(3)
	v_mfma_f32_16x16x32_bf16 v[162:165], v[116:119], v[158:161], 0
	v_add_u32_e32 v166, v157, v212
	v_add_u32_e32 v167, v157, v211
	v_add_u32_e32 v168, v157, v191
	v_mfma_f32_16x16x32_bf16 v[158:161], v[124:127], v[158:161], 0
	ds_read_b64 v[216:217], v166
	ds_read_b64 v[218:219], v167
	ds_read_b64 v[220:221], v168
	v_add_u32_e32 v157, v157, v210
	ds_read_b64 v[222:223], v157
	s_waitcnt lgkmcnt(4)
	v_mfma_f32_16x16x32_bf16 v[162:165], v[112:115], v[152:155], v[162:165]
	v_lshlrev_b32_e32 v168, 4, v206
	v_add_u32_e32 v156, v156, v168
	s_mov_b32 s94, s92
	v_mfma_f32_16x16x32_bf16 v[152:155], v[120:123], v[152:155], v[158:161]
	s_mov_b32 s95, s92
	s_mov_b32 s93, s92
	s_waitcnt lgkmcnt(2)
	v_mfma_f32_16x16x32_bf16 v[158:161], v[108:111], v[216:219], v[162:165]
	s_nop 2
	ds_read_b128 v[164:167], v197 offset:256
	v_mfma_f32_16x16x32_bf16 v[152:155], v[128:131], v[216:219], v[152:155]
	ds_read_b128 v[216:219], v156
	s_waitcnt lgkmcnt(1)
	v_sub_f32_e32 v228, v170, v165
	v_mfma_f32_16x16x32_bf16 v[224:227], v[104:107], v[220:223], v[158:161]
	s_waitcnt lgkmcnt(0)
	v_lshlrev_b32_e32 v173, 16, v216
	v_and_b32_e32 v174, 0xffff0000, v216
	v_lshlrev_b32_e32 v175, 16, v217
	v_mfma_f32_16x16x32_bf16 v[220:223], v[132:135], v[220:223], v[152:155]
	ds_read_b128 v[156:159], v197 offset:272
	ds_read_b128 v[160:163], v197 offset:768
	v_and_b32_e32 v178, 0xffff0000, v217
	v_sub_f32_e32 v152, v170, v164
	v_exp_f32_e32 v200, v152
	v_lshlrev_b32_e32 v179, 16, v218
	v_and_b32_e32 v216, 0xffff0000, v218
	v_lshlrev_b32_e32 v217, 16, v219
	v_cndmask_b32_e64 v200, 0, v200, s[40:41]
	v_mul_f32_e32 v173, v200, v173
	s_waitcnt lgkmcnt(0)
	v_mul_f32_e32 v200, v160, v173
	v_fma_f32 v173, v160, v173, v203
	v_and_b32_e32 v218, 0xffff0000, v219
	v_cndmask_b32_e64 v219, v200, v173, s[42:43]
	v_add_u32_e32 v173, 0x41, v180
	v_cmp_le_i32_e32 vcc, v173, v169
	v_exp_f32_e32 v228, v228
	v_sub_f32_e32 v229, v170, v166
	v_cndmask_b32_e64 v200, 0, 1, vcc
	v_cmp_ge_i32_e32 vcc, v173, v169
	v_exp_f32_e32 v229, v229
	v_sub_f32_e32 v230, v170, v167
	v_cndmask_b32_e64 v201, 0, 1, vcc
	v_cndmask_b32_e64 v200, v201, v200, s[38:39]
	v_and_b32_e32 v200, 1, v200
	v_cmp_eq_u32_e32 vcc, 1, v200
	v_exp_f32_e32 v230, v230
	v_sub_f32_e32 v231, v170, v156
	v_cndmask_b32_e32 v200, 0, v228, vcc
	v_mul_f32_e32 v174, v200, v174
	v_cmp_eq_u32_e32 vcc, v173, v169
	v_mul_f32_e32 v200, v161, v174
	v_fma_f32 v174, v161, v174, v203
	s_and_b64 vcc, s[38:39], vcc
	v_cndmask_b32_e32 v228, v200, v174, vcc
	v_add_u32_e32 v174, 0x42, v180
	v_cmp_le_i32_e32 vcc, v174, v169
	v_exp_f32_e32 v231, v231
	ds_read_b128 v[152:155], v197 offset:784
	v_cndmask_b32_e64 v200, 0, 1, vcc
	v_cmp_ge_i32_e32 vcc, v174, v169
	v_sub_f32_e32 v232, v170, v157
	v_exp_f32_e32 v232, v232
	v_cndmask_b32_e64 v201, 0, 1, vcc
	v_cndmask_b32_e64 v200, v201, v200, s[38:39]
	v_and_b32_e32 v200, 1, v200
	v_cmp_eq_u32_e32 vcc, 1, v200
	v_sub_f32_e32 v233, v170, v158
	v_exp_f32_e32 v233, v233
	v_cndmask_b32_e32 v200, 0, v229, vcc
	v_mul_f32_e32 v175, v200, v175
	v_cmp_eq_u32_e32 vcc, v174, v169
	v_mul_f32_e32 v200, v162, v175
	v_fma_f32 v175, v162, v175, v203
	s_and_b64 vcc, s[38:39], vcc
	v_cndmask_b32_e32 v229, v200, v175, vcc
	v_add_u32_e32 v175, 0x43, v180
	v_cmp_le_i32_e32 vcc, v175, v169
	v_sub_f32_e32 v234, v170, v159
	v_exp_f32_e32 v234, v234
	v_cndmask_b32_e64 v200, 0, 1, vcc
	v_cmp_ge_i32_e32 vcc, v175, v169
	v_cvt_pk_bf16_f32 v228, v219, v228
	v_exp_f32_e32 v170, v170
	v_cndmask_b32_e64 v201, 0, 1, vcc
	v_cndmask_b32_e64 v200, v201, v200, s[38:39]
	v_and_b32_e32 v200, 1, v200
	v_cmp_eq_u32_e32 vcc, 1, v200
	s_nop 1
	v_cndmask_b32_e32 v200, 0, v230, vcc
	v_mul_f32_e32 v178, v200, v178
	v_cmp_eq_u32_e32 vcc, v175, v169
	v_mul_f32_e32 v200, v163, v178
	v_fma_f32 v178, v163, v178, v203
	s_and_b64 vcc, s[38:39], vcc
	v_cndmask_b32_e32 v178, v200, v178, vcc
	v_add_u32_e32 v200, 0x44, v180
	v_cmp_le_i32_e32 vcc, v200, v169
	v_cvt_pk_bf16_f32 v229, v229, v178
	s_nop 0
	v_cndmask_b32_e64 v201, 0, 1, vcc
	v_cmp_ge_i32_e32 vcc, v200, v169
	s_nop 1
	v_cndmask_b32_e64 v230, 0, 1, vcc
	v_cndmask_b32_e64 v201, v230, v201, s[38:39]
	v_and_b32_e32 v201, 1, v201
	v_cmp_eq_u32_e32 vcc, 1, v201
	s_nop 1
	v_cndmask_b32_e32 v201, 0, v231, vcc
	v_mul_f32_e32 v179, v201, v179
	v_cmp_eq_u32_e32 vcc, v200, v169
	s_waitcnt lgkmcnt(0)
; __device__ __forceinline__ unsigned cvt_pk_bf16(float lo, float hi) { const f32x2 v = {lo, hi}; return __builtin_bit_cast(unsigned, __builtin_convertvector(v, bf16x2_t)); }
; __device__ __forceinline__ u32x4 pack8(const float (&f)[8]) { u32x4 w; w.x = cvt_pk_bf16(f[0], f[1]); w.y = cvt_pk_bf16(f[2], f[3]); w.z = cvt_pk_bf16(f[4], f[5]); w.w = cvt_pk_bf16(f[6], f[7]); return w; }
; template <int MODE> __device__ __forceinline__ void ssd_scan_phase(Frame& F, int j, bool ctx_out) {
;     ...
;                         const float cs[8] = {ca.x, ca.y, ca.z, ca.w, cb.x, cb.y, cb.z, cb.w}, ds[8] = {da.x, da.y, da.z, da.w, db.x, db.y, db.z, db.w};
;                         float m[8];
; #pragma unroll
;                         for (int jj = 0; jj < 8; ++jj) { const int s = 32 * kd + 8 * fq + jj; const bool valid = dir == 0 ? (s <= l) : (s >= l);
;                             const float e = valid ? __builtin_amdgcn_exp2f(cl - cs[jj]) : 0.f; m[jj] = gg[jj] * e * ds[jj]; if (dir == 0 && s == l) m[jj] += dsk; }
;                         const bf16x8 mf = __builtin_bit_cast(bf16x8, pack8(m));
;                         accd[0] = __builtin_amdgcn_mfma_f32_16x16x32_bf16(xa, mf, accd[0], 0, 0, 0);
;                         accd[1] = __builtin_amdgcn_mfma_f32_16x16x32_bf16(xb, mf, accd[1], 0, 0, 0);
;                     }
;                     const float el = __builtin_amdgcn_exp2f(cl);
; #pragma unroll
;                     for (int pt = 0; pt < 2; ++pt) { const f32x4 y = accd[pt] + acco[pt] * el; u32x2 o; o.x = cvt_pk_bf16(y[0], y[1]); o.y = cvt_pk_bf16(y[2], y[3]);
;                         *(u32x2*)(yout + (size_t)(row0 + l) * DI + h * 64 + ph * 32 + 16 * pt + 4 * fq) = o; }
	v_mul_f32_e32 v201, v152, v179
	v_fma_f32 v179, v152, v179, v203
	s_and_b64 vcc, s[38:39], vcc
	v_cndmask_b32_e32 v179, v201, v179, vcc
	v_add_u32_e32 v201, 0x45, v180
	v_cmp_le_i32_e32 vcc, v201, v169
	s_nop 1
	v_cndmask_b32_e64 v230, 0, 1, vcc
	v_cmp_ge_i32_e32 vcc, v201, v169
	s_nop 1
	v_cndmask_b32_e64 v231, 0, 1, vcc
	v_cndmask_b32_e64 v230, v231, v230, s[38:39]
	v_and_b32_e32 v230, 1, v230
	v_cmp_eq_u32_e32 vcc, 1, v230
	s_nop 1
	v_cndmask_b32_e32 v230, 0, v232, vcc
	v_mul_f32_e32 v216, v230, v216
	v_cmp_eq_u32_e32 vcc, v201, v169
	v_mul_f32_e32 v230, v153, v216
	v_fma_f32 v216, v153, v216, v203
	s_and_b64 vcc, s[38:39], vcc
	v_cndmask_b32_e32 v230, v230, v216, vcc
	v_add_u32_e32 v216, 0x46, v180
	v_cmp_le_i32_e32 vcc, v216, v169
	v_cvt_pk_bf16_f32 v230, v179, v230
	s_nop 0
	v_cndmask_b32_e64 v231, 0, 1, vcc
	v_cmp_ge_i32_e32 vcc, v216, v169
	s_nop 1
	v_cndmask_b32_e64 v232, 0, 1, vcc
	v_cndmask_b32_e64 v231, v232, v231, s[38:39]
	v_and_b32_e32 v231, 1, v231
	v_cmp_eq_u32_e32 vcc, 1, v231
	s_nop 1
	v_cndmask_b32_e32 v231, 0, v233, vcc
	v_mul_f32_e32 v217, v231, v217
	v_cmp_eq_u32_e32 vcc, v216, v169
	v_mul_f32_e32 v231, v154, v217
	v_fma_f32 v217, v154, v217, v203
	s_and_b64 vcc, s[38:39], vcc
	v_cndmask_b32_e32 v231, v231, v217, vcc
	v_add_u32_e32 v217, 0x47, v180
	v_cmp_le_i32_e32 vcc, v217, v169
	s_nop 1
	v_cndmask_b32_e64 v232, 0, 1, vcc
	v_cmp_ge_i32_e32 vcc, v217, v169
	s_nop 1
	v_cndmask_b32_e64 v233, 0, 1, vcc
	v_cndmask_b32_e64 v232, v233, v232, s[38:39]
	v_and_b32_e32 v232, 1, v232
	v_cmp_eq_u32_e32 vcc, 1, v232
	s_nop 1
	v_cndmask_b32_e32 v232, 0, v234, vcc
	v_mul_f32_e32 v218, v232, v218
	v_cmp_eq_u32_e32 vcc, v217, v169
	v_mul_f32_e32 v232, v155, v218
	v_fma_f32 v218, v155, v218, v203
	s_and_b64 vcc, s[38:39], vcc
	v_cndmask_b32_e32 v218, v232, v218, vcc
	v_cvt_pk_bf16_f32 v231, v231, v218
	v_add_u32_e32 v218, s5, v169
	v_ashrrev_i32_e32 v219, 31, v218
	v_mfma_f32_16x16x32_bf16 v[232:235], v[100:103], v[228:231], v[148:151]
	v_lshlrev_b64 v[218:219], 13, v[218:219]
	v_lshl_add_u64 v[218:219], v[198:199], 0, v[218:219]
	v_or_b32_e32 v169, 0x50, v176
	s_waitcnt vmcnt(5)
	v_mfma_f32_16x16x32_bf16 v[144:147], v[140:143], v[228:231], v[144:147]
	v_mov_b64_e32 v[150:151], s[94:95]
	s_nop 2
	v_pk_fma_f32 v[226:227], v[170:171], v[226:227], v[234:235] op_sel_hi:[0,1,1]
	v_pk_fma_f32 v[224:225], v[170:171], v[224:225], v[232:233] op_sel_hi:[0,1,1]
	v_cvt_pk_bf16_f32 v224, v224, v225
	v_cvt_pk_bf16_f32 v225, v226, v227
	v_pk_fma_f32 v[146:147], v[170:171], v[222:223], v[146:147] op_sel_hi:[0,1,1]
	v_pk_fma_f32 v[144:145], v[170:171], v[220:221], v[144:145] op_sel_hi:[0,1,1]
	v_cvt_pk_bf16_f32 v144, v144, v145
	v_cvt_pk_bf16_f32 v145, v146, v147
	global_store_dwordx2 v[218:219], v[224:225], off
	global_store_dwordx2 v[218:219], v[144:145], off offset:32
	v_lshlrev_b32_e32 v218, 8, v169
	v_mov_b64_e32 v[146:147], s[94:95]
	v_mov_b64_e32 v[148:149], s[92:93]
	v_add_u32_e32 v170, s87, v218
	s_and_b64 vcc, exec, s[46:47]
	v_mov_b64_e32 v[144:145], s[92:93]
	s_cbranch_vccz .LBB0_534
	s_and_b64 vcc, exec, s[46:47]
	s_cbranch_vccz .LBB0_535

; #define LAS __attribute__((address_space(3)))
; __device__ __forceinline__ u32x4 pack8(const float (&f)[8]) { u32x4 w; w.x = cvt_pk_bf16(f[0], f[1]); w.y = cvt_pk_bf16(f[2], f[3]); w.z = cvt_pk_bf16(f[4], f[5]); w.w = cvt_pk_bf16(f[6], f[7]); return w; }
; template <int MODE> __device__ __forceinline__ void ssd_scan_phase(Frame& F, int j, bool ctx_out) {
;     ...
; #pragma unroll
;                     for (int q = 0; q < 4; ++q) {
;                         const u32x2 lo = *(const LAS u32x2*)(CS + l * 256 + (((4 * q + (fq >> 1)) ^ fr) << 4) + (fq & 1) * 8), hi = *(const LAS u32x2*)(CS + l * 256 + (((4 * q + 2 + (fq >> 1)) ^ fr) << 4) + (fq & 1) * 8);
;                         u32x4 c4; c4.x = lo.x; c4.y = lo.y; c4.z = hi.x; c4.w = hi.y; const bf16x8 cfr = __builtin_bit_cast(bf16x8, c4);
;                         acco[0] = __builtin_amdgcn_mfma_f32_16x16x32_bf16(hf[0][q], cfr, acco[0], 0, 0, 0);
;                         acco[1] = __builtin_amdgcn_mfma_f32_16x16x32_bf16(hf[1][q], cfr, acco[1], 0, 0, 0);
;                     }
;                     {
;                         float gg[8]; unpack8(*(const LAS u32x4*)(GS + l * 256 + (((4 * kd + fq) ^ fr) << 4)), gg);
;                         const f32x4 ca = *(const LAS f32x4*)(tab + 32 * kd + 8 * fq), cb = *(const LAS f32x4*)(tab + 32 * kd + 8 * fq + 4);
;                         const f32x4 da = *(const LAS f32x4*)(tab + 128 + 32 * kd + 8 * fq), db = *(const LAS f32x4*)(tab + 128 + 32 * kd + 8 * fq + 4);
;                         const float cs[8] = {ca.x, ca.y, ca.z, ca.w, cb.x, cb.y, cb.z, cb.w}, ds[8] = {da.x, da.y, da.z, da.w, db.x, db.y, db.z, db.w};
;                         float m[8];
; #pragma unroll
;                         for (int jj = 0; jj < 8; ++jj) { const int s = 32 * kd + 8 * fq + jj; const bool valid = dir == 0 ? (s <= l) : (s >= l);
;                             const float e = valid ? __builtin_amdgcn_exp2f(cl - cs[jj]) : 0.f; m[jj] = gg[jj] * e * ds[jj]; if (dir == 0 && s == l) m[jj] += dsk; }
;                         const bf16x8 mf = __builtin_bit_cast(bf16x8, pack8(m));
;                         accd[0] = __builtin_amdgcn_mfma_f32_16x16x32_bf16(xa, mf, accd[0], 0, 0, 0);
;                         accd[1] = __builtin_amdgcn_mfma_f32_16x16x32_bf16(xb, mf, accd[1], 0, 0, 0);
.LBB0_522:
	v_add3_u32 v168, 0, v173, v195
	v_add_u32_e32 v172, v168, v185
	v_add_u32_e32 v174, v168, v183
	ds_read_b64 v[172:173], v172
	ds_read_b64 v[174:175], v174
	v_add_u32_e32 v178, v168, v187
	s_waitcnt lgkmcnt(0)
	v_mfma_f32_16x16x32_bf16 v[116:119], v[116:119], v[172:175], 0
	v_mfma_f32_16x16x32_bf16 v[124:127], v[124:127], v[172:175], 0
	v_add_u32_e32 v174, v168, v213
	ds_read_b64 v[172:173], v178
	ds_read_b64 v[174:175], v174
	s_waitcnt lgkmcnt(0)
	v_mfma_f32_16x16x32_bf16 v[112:115], v[112:115], v[172:175], v[116:119]
	s_nop 2
	v_add_u32_e32 v116, v168, v212
	v_add_u32_e32 v118, v168, v211
	ds_read_b64 v[116:117], v116
	ds_read_b64 v[118:119], v118
	v_mfma_f32_16x16x32_bf16 v[120:123], v[120:123], v[172:175], v[124:127]
	s_nop 2
	v_add_u32_e32 v124, v168, v191
	s_waitcnt lgkmcnt(0)
	v_mfma_f32_16x16x32_bf16 v[108:111], v[108:111], v[116:119], v[112:115]
	s_nop 2
	v_add_u32_e32 v114, v168, v210
	ds_read_b64 v[112:113], v124
	ds_read_b64 v[114:115], v114
	v_mfma_f32_16x16x32_bf16 v[116:119], v[128:131], v[116:119], v[120:123]
	v_add_u32_e32 v124, 0x60, v180
	v_cmp_le_i32_e32 vcc, v124, v160
	v_cmp_ge_i32_e64 s[40:41], v124, v160
	v_add_u32_e32 v120, v161, v171
	ds_read_b128 v[120:123], v120
	s_waitcnt lgkmcnt(1)
	v_mfma_f32_16x16x32_bf16 v[108:111], v[104:107], v[112:115], v[108:111]
	s_waitcnt lgkmcnt(0)
; #define LAS __attribute__((address_space(3)))
; __device__ __forceinline__ unsigned cvt_pk_bf16(float lo, float hi) { const f32x2 v = {lo, hi}; return __builtin_bit_cast(unsigned, __builtin_convertvector(v, bf16x2_t)); }
; __device__ __forceinline__ u32x4 pack8(const float (&f)[8]) { u32x4 w; w.x = cvt_pk_bf16(f[0], f[1]); w.y = cvt_pk_bf16(f[2], f[3]); w.z = cvt_pk_bf16(f[4], f[5]); w.w = cvt_pk_bf16(f[6], f[7]); return w; }
; template <int MODE> __device__ __forceinline__ void ssd_scan_phase(Frame& F, int j, bool ctx_out) {
;     ...
;                     {
;                         float gg[8]; unpack8(*(const LAS u32x4*)(GS + l * 256 + (((4 * kd + fq) ^ fr) << 4)), gg);
;                         const f32x4 ca = *(const LAS f32x4*)(tab + 32 * kd + 8 * fq), cb = *(const LAS f32x4*)(tab + 32 * kd + 8 * fq + 4);
;                         const f32x4 da = *(const LAS f32x4*)(tab + 128 + 32 * kd + 8 * fq), db = *(const LAS f32x4*)(tab + 128 + 32 * kd + 8 * fq + 4);
;                         const float cs[8] = {ca.x, ca.y, ca.z, ca.w, cb.x, cb.y, cb.z, cb.w}, ds[8] = {da.x, da.y, da.z, da.w, db.x, db.y, db.z, db.w};
;                         float m[8];
; #pragma unroll
;                         for (int jj = 0; jj < 8; ++jj) { const int s = 32 * kd + 8 * fq + jj; const bool valid = dir == 0 ? (s <= l) : (s >= l);
;                             const float e = valid ? __builtin_amdgcn_exp2f(cl - cs[jj]) : 0.f; m[jj] = gg[jj] * e * ds[jj]; if (dir == 0 && s == l) m[jj] += dsk; }
;                         const bf16x8 mf = __builtin_bit_cast(bf16x8, pack8(m));
;                         accd[0] = __builtin_amdgcn_mfma_f32_16x16x32_bf16(xa, mf, accd[0], 0, 0, 0);
;                         accd[1] = __builtin_amdgcn_mfma_f32_16x16x32_bf16(xb, mf, accd[1], 0, 0, 0);
;                     }
;                     const float el = __builtin_amdgcn_exp2f(cl);
; #pragma unroll
;                     for (int pt = 0; pt < 2; ++pt) { const f32x4 y = accd[pt] + acco[pt] * el; u32x2 o; o.x = cvt_pk_bf16(y[0], y[1]); o.y = cvt_pk_bf16(y[2], y[3]);
;                         *(u32x2*)(yout + (size_t)(row0 + l) * DI + h * 64 + ph * 32 + 16 * pt + 4 * fq) = o; }
	v_lshlrev_b32_e32 v125, 16, v120
	v_mfma_f32_16x16x32_bf16 v[104:107], v[132:135], v[112:115], v[116:119]
	v_lshlrev_b32_e32 v126, 16, v121
	v_and_b32_e32 v112, 0xffff0000, v121
	v_sub_f32_e32 v121, v162, v157
	v_sub_f32_e32 v119, v162, v156
	v_cndmask_b32_e64 v117, 0, 1, vcc
	v_cndmask_b32_e64 v118, 0, 1, s[40:41]
	v_exp_f32_e32 v119, v119
	v_cndmask_b32_e64 v117, v118, v117, s[38:39]
	v_and_b32_e32 v117, 1, v117
	v_cmp_eq_u32_e32 vcc, 1, v117
	v_cmp_ge_i32_e64 s[40:41], v170, v160
	v_exp_f32_e32 v121, v121
	v_cndmask_b32_e32 v117, 0, v119, vcc
	v_mul_f32_e32 v117, v117, v125
	v_cmp_eq_u32_e32 vcc, v124, v160
	v_mul_f32_e32 v118, v152, v117
	s_and_b64 vcc, s[38:39], vcc
	v_fma_f32 v117, v152, v117, v203
	v_cndmask_b32_e32 v117, v118, v117, vcc
	v_cmp_le_i32_e32 vcc, v170, v160
	v_cndmask_b32_e64 v119, 0, 1, s[40:41]
	v_and_b32_e32 v120, 0xffff0000, v120
	v_cndmask_b32_e64 v118, 0, 1, vcc
	v_cndmask_b32_e64 v118, v119, v118, s[38:39]
	v_and_b32_e32 v118, 1, v118
	v_cmp_eq_u32_e32 vcc, 1, v118
	v_cmp_ge_i32_e64 s[40:41], v169, v160
	v_lshlrev_b32_e32 v113, 16, v122
	v_cndmask_b32_e32 v118, 0, v121, vcc
	v_mul_f32_e32 v118, v118, v120
	v_cmp_eq_u32_e32 vcc, v170, v160
	v_mul_f32_e32 v119, v153, v118
	s_and_b64 vcc, s[38:39], vcc
	v_fma_f32 v118, v153, v118, v203
	v_cndmask_b32_e32 v118, v119, v118, vcc
	v_cmp_le_i32_e32 vcc, v169, v160
	v_sub_f32_e32 v121, v162, v158
	v_cndmask_b32_e64 v120, 0, 1, s[40:41]
	v_cndmask_b32_e64 v119, 0, 1, vcc
	v_exp_f32_e32 v121, v121
	v_cndmask_b32_e64 v119, v120, v119, s[38:39]
	v_and_b32_e32 v119, 1, v119
	v_cmp_eq_u32_e32 vcc, 1, v119
	v_and_b32_e32 v114, 0xffff0000, v122
	v_cmp_ge_i32_e64 s[40:41], v167, v160
	v_cndmask_b32_e32 v119, 0, v121, vcc
	v_mul_f32_e32 v119, v119, v126
	v_cmp_eq_u32_e32 vcc, v169, v160
	v_mul_f32_e32 v120, v154, v119
	s_and_b64 vcc, s[38:39], vcc
	v_fma_f32 v119, v154, v119, v203
	v_cndmask_b32_e32 v119, v120, v119, vcc
	v_cmp_le_i32_e32 vcc, v167, v160
	v_sub_f32_e32 v122, v162, v159
	v_cndmask_b32_e64 v121, 0, 1, s[40:41]
	v_cndmask_b32_e64 v120, 0, 1, vcc
	v_exp_f32_e32 v122, v122
	v_cndmask_b32_e64 v120, v121, v120, s[38:39]
	v_and_b32_e32 v120, 1, v120
	v_cmp_eq_u32_e32 vcc, 1, v120
	v_cmp_ge_i32_e64 s[40:41], v166, v160
	v_lshlrev_b32_e32 v115, 16, v123
	v_cndmask_b32_e32 v120, 0, v122, vcc
	v_mul_f32_e32 v112, v120, v112
	v_cmp_eq_u32_e32 vcc, v167, v160
	v_mul_f32_e32 v120, v155, v112
	s_and_b64 vcc, s[38:39], vcc
	v_fma_f32 v112, v155, v112, v203
	v_cndmask_b32_e32 v120, v120, v112, vcc
	v_cmp_le_i32_e32 vcc, v166, v160
	v_sub_f32_e32 v122, v162, v144
	v_cndmask_b32_e64 v121, 0, 1, s[40:41]
	v_cndmask_b32_e64 v112, 0, 1, vcc
	v_exp_f32_e32 v122, v122
	v_cndmask_b32_e64 v112, v121, v112, s[38:39]
	v_and_b32_e32 v112, 1, v112
	v_cmp_eq_u32_e32 vcc, 1, v112
	v_cmp_ge_i32_e64 s[40:41], v165, v160
	v_and_b32_e32 v116, 0xffff0000, v123
	v_cndmask_b32_e32 v112, 0, v122, vcc
	v_mul_f32_e32 v112, v112, v113
	v_cmp_eq_u32_e32 vcc, v166, v160
	v_mul_f32_e32 v113, v140, v112
	s_and_b64 vcc, s[38:39], vcc
	v_fma_f32 v112, v140, v112, v203
	v_cndmask_b32_e32 v121, v113, v112, vcc
	v_cmp_le_i32_e32 vcc, v165, v160
	v_sub_f32_e32 v122, v162, v145
	v_cndmask_b32_e64 v113, 0, 1, s[40:41]
	v_cndmask_b32_e64 v112, 0, 1, vcc
	v_exp_f32_e32 v122, v122
	v_cndmask_b32_e64 v112, v113, v112, s[38:39]
	v_and_b32_e32 v112, 1, v112
	v_cmp_eq_u32_e32 vcc, 1, v112
	v_cmp_ge_i32_e64 s[40:41], v164, v160
	s_nop 0
	v_cndmask_b32_e32 v112, 0, v122, vcc
	v_mul_f32_e32 v112, v112, v114
	v_cmp_eq_u32_e32 vcc, v165, v160
	v_mul_f32_e32 v113, v141, v112
	s_and_b64 vcc, s[38:39], vcc
	v_fma_f32 v112, v141, v112, v203
	v_cndmask_b32_e32 v114, v113, v112, vcc
	v_cmp_le_i32_e32 vcc, v164, v160
	v_sub_f32_e32 v122, v162, v146
	v_cndmask_b32_e64 v113, 0, 1, s[40:41]
	v_cndmask_b32_e64 v112, 0, 1, vcc
	v_exp_f32_e32 v122, v122
	v_cndmask_b32_e64 v112, v113, v112, s[38:39]
	v_and_b32_e32 v112, 1, v112
	v_cmp_eq_u32_e32 vcc, 1, v112
	v_cmp_ge_i32_e64 s[40:41], v163, v160
	v_cvt_pk_bf16_f32 v114, v121, v114
	v_cndmask_b32_e32 v112, 0, v122, vcc
	v_mul_f32_e32 v112, v112, v115
	v_cmp_eq_u32_e32 vcc, v164, v160
	v_mul_f32_e32 v113, v142, v112
	s_and_b64 vcc, s[38:39], vcc
	v_fma_f32 v112, v142, v112, v203
	v_cndmask_b32_e32 v115, v113, v112, vcc
	v_cmp_le_i32_e32 vcc, v163, v160
	v_sub_f32_e32 v122, v162, v147
	v_cndmask_b32_e64 v113, 0, 1, s[40:41]
	v_cndmask_b32_e64 v112, 0, 1, vcc
	v_exp_f32_e32 v122, v122
	v_cndmask_b32_e64 v112, v113, v112, s[38:39]
	v_and_b32_e32 v112, 1, v112
	v_cmp_eq_u32_e32 vcc, 1, v112
	s_nop 1
	v_cndmask_b32_e32 v112, 0, v122, vcc
	v_mul_f32_e32 v112, v112, v116
	v_cmp_eq_u32_e32 vcc, v163, v160
	v_mul_f32_e32 v113, v143, v112
	s_and_b64 vcc, s[38:39], vcc
	v_fma_f32 v112, v143, v112, v203
	v_cndmask_b32_e32 v116, v113, v112, vcc
	v_cvt_pk_bf16_f32 v112, v117, v118
	v_cvt_pk_bf16_f32 v113, v119, v120
	v_cvt_pk_bf16_f32 v115, v115, v116
	s_nop 1
	v_mfma_f32_16x16x32_bf16 v[8:11], v[8:11], v[112:115], v[100:103]
	v_mfma_f32_16x16x32_bf16 v[100:103], v[136:139], v[112:115], v[148:151]
	v_exp_f32_e32 v112, v162
	v_add_u32_e32 v114, s5, v160
	v_ashrrev_i32_e32 v115, 31, v114
	v_lshlrev_b64 v[114:115], 13, v[114:115]
	s_nop 2
	v_pk_fma_f32 v[10:11], v[112:113], v[110:111], v[10:11] op_sel_hi:[0,1,1]
	v_pk_fma_f32 v[8:9], v[112:113], v[108:109], v[8:9] op_sel_hi:[0,1,1]
	v_lshl_add_u64 v[114:115], v[198:199], 0, v[114:115]
	v_cvt_pk_bf16_f32 v8, v8, v9
	v_cvt_pk_bf16_f32 v9, v10, v11
	global_store_dwordx2 v[114:115], v[8:9], off
	v_pk_fma_f32 v[8:9], v[112:113], v[106:107], v[102:103] op_sel_hi:[0,1,1]
	v_pk_fma_f32 v[10:11], v[112:113], v[104:105], v[100:101] op_sel_hi:[0,1,1]
	v_cvt_pk_bf16_f32 v10, v10, v11
	v_cvt_pk_bf16_f32 v11, v8, v9
	global_store_dwordx2 v[114:115], v[10:11], off offset:32
	s_branch .Lscan_b4_y

; #define VM_WAIT() asm volatile("s_waitcnt vmcnt(0)" ::: "memory")
;     __device__ __forceinline__ const char* b(const pg8::Unit& u) const { return (const char*)ws + boff + (size_t)u.pn * 256 * K_ * 2 + (u.kq < 0 ? 0 : u.kq * (K_ / 4) * 2); }
;     __device__ __forceinline__ const char* b(const pg8::Unit& u) const { return (const char*)ws + boff + (size_t)u.pn * 256 * D * 2; }
;     __device__ __forceinline__ const char* b(const pg8::Unit& u) const { return (const char*)ws + boff + (size_t)u.pn * 256 * D * 2; }
;     __device__ __forceinline__ const char* b(const pg8::Unit& u) const { return (const char*)ws + WS_A + ((size_t)u.pn * 256 * D + (size_t)(u.pm >> 1) * 256) * 2; }
; #define SCAN_DMA(dstbase, srcptr_row0, pitch_elems) do { _Pragma("unroll") for (int q_ = 0; q_ < 4; ++q_) { const int idx_ = tid + 512 * q_, row_ = idx_ >> 4, c16_ = (idx_ & 15) ^ (row_ & 15); \
;         __builtin_amdgcn_global_load_lds((const unsigned*)((srcptr_row0) + (size_t)row_ * (pitch_elems) + c16_ * 8), (LAS unsigned*)((dstbase) + (w * 64 + 512 * q_) * 16), 16, 0, 0); } } while (0)
; template <int MODE> __device__ __forceinline__ void ssd_scan_phase(Frame& F, int j, bool ctx_out) {
;     ...
;             VM_WAIT(); __syncthreads();
;             if (k + 1 < 18) {
;                 const int kn = k + 1; const bool isctxn = kn < 2; const int ccn = isctxn ? (dir == 0 ? kn : 1 - kn) : (dir == 0 ? kn - 2 : 17 - kn);
;                 const int row0n = isctxn ? MLAT + b * LCTX + ccn * 128 : b * LSEQ + ccn * 128;
;                 if ((ctx_out || !isctxn) && !(MODE & 8)) { SCAN_DMA(CS, cm + (size_t)row0n * GNW + g * 128, GNW); SCAN_DMA(GS, bm + (size_t)row0n * GNW + g * 128, GNW); }
;                 dtr0 = dtb[(size_t)(row0n + lane) * 128 + dir * 64 + h]; dtr1 = dtb[(size_t)(row0n + 64 + lane) * 128 + dir * 64 + h];
.Lscan_b4_y:
	s_add_i32 s40, s4, 1
	s_cmp_eq_u32 s4, 17
	s_mov_b32 s5, 17
	s_waitcnt lgkmcnt(0)
	s_barrier
	s_cbranch_scc1 .LBB0_481
	s_sub_i32 s17, 16, s4
	v_sub_co_u32_e64 v8, s[42:43], s4, 1
	s_and_b64 s[4:5], s[38:39], exec
	v_readfirstlane_b32 s4, v8
	s_cselect_b32 s4, s4, s17
	s_lshl_b32 s4, s4, 7
	s_add_i32 s17, s4, s81
	s_and_b64 s[4:5], s[42:43], exec
	s_cselect_b32 s4, s76, s17
	s_and_b64 s[42:43], s[28:29], s[42:43]
	s_and_b64 vcc, exec, s[42:43]
	s_cbranch_vccnz .LBB0_480
	s_ashr_i32 s5, s4, 31
	s_lshl_b64 s[42:43], s[4:5], 11
	v_ashrrev_i32_e32 v189, 31, v188
	s_add_u32 s44, s77, s42
	s_addc_u32 s45, s73, s43
	v_lshlrev_b64 v[8:9], 11, v[188:189]
	v_lshl_add_u64 v[10:11], s[44:45], 0, v[8:9]
	v_mov_b32_e32 v183, v177
	s_mov_b32 m0, s16
	v_ashrrev_i32_e32 v193, 31, v192
	v_lshl_add_u64 v[10:11], v[10:11], 0, v[182:183]
	global_load_lds_dwordx4 v[10:11], off
	v_lshlrev_b64 v[10:11], 11, v[192:193]
	v_lshl_add_u64 v[100:101], s[44:45], 0, v[10:11]
	v_mov_b32_e32 v185, v177
	v_ashrrev_i32_e32 v195, 31, v194
	v_lshl_add_u64 v[100:101], v[100:101], 0, v[184:185]
	s_add_i32 m0, s16, 0x2000
	v_mov_b32_e32 v187, v177
	global_load_lds_dwordx4 v[100:101], off
	v_lshlrev_b64 v[100:101], 11, v[194:195]
	v_lshl_add_u64 v[102:103], s[44:45], 0, v[100:101]
	v_lshl_add_u64 v[102:103], v[102:103], 0, v[186:187]
	s_add_i32 m0, s16, 0x4000
	v_ashrrev_i32_e32 v197, 31, v196
	global_load_lds_dwordx4 v[102:103], off
	s_add_i32 m0, s16, 0x6000
	v_lshlrev_b64 v[102:103], 11, v[196:197]
	s_add_u32 s42, s74, s42
	v_lshl_add_u64 v[104:105], s[44:45], 0, v[102:103]
	v_mov_b32_e32 v191, v177
	s_addc_u32 s43, s75, s43
	v_lshl_add_u64 v[104:105], v[104:105], 0, v[190:191]
	v_lshl_add_u64 v[8:9], s[42:43], 0, v[8:9]
	s_add_i32 s5, s87, s3
	global_load_lds_dwordx4 v[104:105], off
	v_lshl_add_u64 v[8:9], v[8:9], 0, v[182:183]
	s_mov_b32 m0, s5
	s_nop 0
	global_load_lds_dwordx4 v[8:9], off
	v_lshl_add_u64 v[8:9], s[42:43], 0, v[10:11]
	v_lshl_add_u64 v[8:9], v[8:9], 0, v[184:185]
	s_add_i32 m0, s5, 0x2000
	s_nop 0
	global_load_lds_dwordx4 v[8:9], off
	v_lshl_add_u64 v[8:9], s[42:43], 0, v[100:101]
	v_lshl_add_u64 v[8:9], v[8:9], 0, v[186:187]
	s_add_i32 m0, s5, 0x4000
	s_nop 0
	global_load_lds_dwordx4 v[8:9], off
	v_lshl_add_u64 v[8:9], s[42:43], 0, v[102:103]
	v_lshl_add_u64 v[8:9], v[8:9], 0, v[190:191]
	s_add_i32 m0, s5, 0x6000
	s_nop 0
	global_load_lds_dwordx4 v[8:9], off
	s_branch .LBB0_480

; __device__ __forceinline__ void fresh_ids(Frame& F) { F.lane = fresh_lane(); F.tid = F.wave * 64 + F.lane; }
;     __device__ __forceinline__ const char* a(const pg8::Unit& u) const { return (const char*)ws + aoff + (size_t)u.pm * 256 * K_ * 2 + (u.kq < 0 ? 0 : u.kq * (K_ / 4) * 2); }
;     __device__ __forceinline__ const char* b(const pg8::Unit& u) const { return (const char*)ws + boff + (size_t)u.pn * 256 * K_ * 2 + (u.kq < 0 ? 0 : u.kq * (K_ / 4) * 2); }
;     __device__ __forceinline__ const char* a(const pg8::Unit& u) const { return (const char*)ws + WS_A + (size_t)u.pm * 256 * D * 2; }
;     __device__ __forceinline__ const char* b(const pg8::Unit& u) const { return (const char*)ws + boff + (size_t)u.pn * 256 * D * 2; }
;     __device__ __forceinline__ const char* a(const pg8::Unit& u) const { return (const char*)ws + WS_A + (size_t)u.pm * 256 * D * 2; }
;     __device__ __forceinline__ const char* b(const pg8::Unit& u) const { return (const char*)ws + boff + (size_t)u.pn * 256 * D * 2; }
;     __device__ __forceinline__ const char* a(const pg8::Unit& u) const { return (const char*)ws + WS_W1 + (size_t)(u.pm & 1) * 256 * 256 * 2; }
;     __device__ __forceinline__ const char* b(const pg8::Unit& u) const { return (const char*)ws + WS_A + ((size_t)u.pn * 256 * D + (size_t)(u.pm >> 1) * 256) * 2; }
;     __device__ __forceinline__ const char* a(const pg8::Unit& u) const { return (const char*)ws + (u.pm < 64 ? WS_W2 : WS_W2C); }
; __device__ __forceinline__ void ssd_gate_norm_phase(Frame& F, int j, int nrows) {
;     fresh_ids(F);
;     const int gw = blockIdx.x * NWAVES + F.wave, NGW = F.G * NWAVES, lane = F.lane;
;     bf16_t* yf = (bf16_t*)(F.ws + WS_XBCP); const bf16_t* yb = (const bf16_t*)(F.ws + WS_YB); const bf16_t* z = (const bf16_t*)(F.ws + WS_Z);
;     const float* ng = F.in[I_SNG] + (size_t)j * DI;
;     for (int r = gw; r < nrows; r += NGW) {
; #pragma unroll 4
;         for (int g = 0; g < 8; ++g) { const size_t off = (size_t)r * DI + g * 512 + lane * 8;
;             float a[8], b[8], zz[8]; unpack8(__builtin_nontemporal_load((const u32x4*)(yf + off)), a); unpack8(__builtin_nontemporal_load((const u32x4*)(yb + off)), b); unpack8(__builtin_nontemporal_load((const u32x4*)(z + off)), zz);
.LBB0_595:
	s_andn2_b64 vcc, exec, s[0:1]
	s_cbranch_vccnz .LBB0_653
	v_readlane_b32 s0, v255, 4
	v_readlane_b32 s1, v255, 5
	v_readlane_b32 s1, v255, 35
	s_cmp_ge_i32 s0, s1
	s_waitcnt vmcnt(0)
	v_mbcnt_lo_u32_b32 v0, -1, 0
	v_mbcnt_hi_u32_b32 v0, -1, v0
	s_cbranch_scc1 .LBB0_601
	s_lshl_b64 s[0:1], s[82:83], 13
	s_and_b32 s0, s0, 0xffffc000
	v_readlane_b32 s4, v255, 2
	v_lshlrev_b32_e32 v0, 3, v0
	s_add_u32 s0, s4, s0
	v_readlane_b32 s4, v255, 3
	v_ashrrev_i32_e32 v1, 31, v0
	s_addc_u32 s1, s4, s1
	v_lshl_add_u64 v[8:9], v[0:1], 2, s[0:1]
	v_readlane_b32 s0, v255, 12
	v_readlane_b32 s1, v255, 13
	s_nop 1
	v_lshl_add_u64 v[10:11], v[0:1], 1, s[0:1]
	v_readlane_b32 s0, v255, 4
	s_mov_b32 s4, s0
	v_readlane_b32 s1, v255, 5
	v_readlane_b32 s7, v255, 35
	v_readlane_b32 s0, v255, 10
	v_readlane_b32 s1, v255, 11
	s_mov_b32 s101, 0
	s_mov_b32 s100, 0x1f600000
	v_lshl_add_u64 v[168:169], v[10:11], 0, s[100:101]
	s_mov_b32 s100, 0x46300000
	v_lshl_add_u64 v[172:173], v[10:11], 0, s[100:101]
	s_mov_b32 s100, 0x2ce00000
	v_lshl_add_u64 v[178:179], v[10:11], 0, s[100:101]
	s_movk_i32 s100, 0x1000
	v_lshl_add_u64 v[170:171], v[168:169], 0, s[100:101]
	v_lshl_add_u64 v[174:175], v[172:173], 0, s[100:101]
	v_lshl_add_u64 v[180:181], v[178:179], 0, s[100:101]
	s_mov_b32 s100, 0xffffe7f0
	s_mov_b32 s101, -1
	v_lshl_add_u64 v[182:183], v[8:9], 0, s[100:101]
	s_movk_i32 s100, 0x1000
	s_mov_b32 s101, 0
	global_load_dwordx4 v[100:103], v[182:183], off
	global_load_dwordx4 v[104:107], v[182:183], off offset:16
	global_load_dwordx4 v[108:111], v[182:183], off offset:2048
	global_load_dwordx4 v[112:115], v[182:183], off offset:2064
	v_lshl_add_u64 v[182:183], v[182:183], 0, s[100:101]
	global_load_dwordx4 v[116:119], v[182:183], off
	global_load_dwordx4 v[120:123], v[182:183], off offset:16
	global_load_dwordx4 v[124:127], v[182:183], off offset:2048
	global_load_dwordx4 v[128:131], v[182:183], off offset:2064
	v_lshl_add_u64 v[182:183], v[182:183], 0, s[100:101]
	global_load_dwordx4 v[132:135], v[182:183], off
	global_load_dwordx4 v[136:139], v[182:183], off offset:16
	global_load_dwordx4 v[140:143], v[182:183], off offset:2048
	global_load_dwordx4 v[144:147], v[182:183], off offset:2064
	v_lshl_add_u64 v[182:183], v[182:183], 0, s[100:101]
	global_load_dwordx4 v[148:151], v[182:183], off
	global_load_dwordx4 v[152:155], v[182:183], off offset:16
	global_load_dwordx4 v[156:159], v[182:183], off offset:2048
	global_load_dwordx4 v[160:163], v[182:183], off offset:2064
	global_load_dwordx4 v[4:7], v[168:169], off nt
	global_load_dwordx4 v[8:11], v[172:173], off nt
	global_load_dwordx4 v[12:15], v[178:179], off nt
	global_load_dwordx4 v[16:19], v[168:169], off offset:1024 nt
	global_load_dwordx4 v[20:23], v[172:173], off offset:1024 nt
	global_load_dwordx4 v[24:27], v[178:179], off offset:1024 nt
	global_load_dwordx4 v[28:31], v[168:169], off offset:2048 nt
	global_load_dwordx4 v[32:35], v[172:173], off offset:2048 nt
	global_load_dwordx4 v[36:39], v[178:179], off offset:2048 nt
	global_load_dwordx4 v[40:43], v[168:169], off offset:3072 nt
	global_load_dwordx4 v[44:47], v[172:173], off offset:3072 nt
	global_load_dwordx4 v[48:51], v[178:179], off offset:3072 nt
	global_load_dwordx4 v[52:55], v[170:171], off nt
	global_load_dwordx4 v[56:59], v[174:175], off nt
	global_load_dwordx4 v[60:63], v[180:181], off nt
	global_load_dwordx4 v[64:67], v[170:171], off offset:1024 nt
	global_load_dwordx4 v[68:71], v[174:175], off offset:1024 nt
	global_load_dwordx4 v[72:75], v[180:181], off offset:1024 nt
	global_load_dwordx4 v[76:79], v[170:171], off offset:2048 nt
	global_load_dwordx4 v[80:83], v[174:175], off offset:2048 nt
	global_load_dwordx4 v[84:87], v[180:181], off offset:2048 nt
	global_load_dwordx4 v[88:91], v[170:171], off offset:3072 nt
	global_load_dwordx4 v[92:95], v[174:175], off offset:3072 nt
	global_load_dwordx4 v[96:99], v[180:181], off offset:3072 nt
	v_mov_b32_e32 v164, v168
	v_mov_b32_e32 v165, v169
	v_mov_b32_e32 v166, v170
	v_mov_b32_e32 v167, v171
	v_lshl_add_u64 v[168:169], v[168:169], 0, s[0:1]
	v_lshl_add_u64 v[170:171], v[170:171], 0, s[0:1]
	v_lshl_add_u64 v[172:173], v[172:173], 0, s[0:1]
	v_lshl_add_u64 v[174:175], v[174:175], 0, s[0:1]
	v_lshl_add_u64 v[178:179], v[178:179], 0, s[0:1]
	v_lshl_add_u64 v[180:181], v[180:181], 0, s[0:1]
; __device__ __forceinline__ float silu_f(float v) { return v * __builtin_amdgcn_rcpf(1.0f + __expf(-v)); }
;     __device__ __forceinline__ const char* a(const pg8::Unit& u) const { return (const char*)ws + aoff + (size_t)u.pm * 256 * K_ * 2 + (u.kq < 0 ? 0 : u.kq * (K_ / 4) * 2); }
;     __device__ __forceinline__ const char* b(const pg8::Unit& u) const { return (const char*)ws + boff + (size_t)u.pn * 256 * K_ * 2 + (u.kq < 0 ? 0 : u.kq * (K_ / 4) * 2); }
;     __device__ __forceinline__ const char* a(const pg8::Unit& u) const { return (const char*)ws + WS_A + (size_t)u.pm * 256 * D * 2; }
;     __device__ __forceinline__ const char* b(const pg8::Unit& u) const { return (const char*)ws + boff + (size_t)u.pn * 256 * D * 2; }
;     __device__ __forceinline__ const char* a(const pg8::Unit& u) const { return (const char*)ws + WS_A + (size_t)u.pm * 256 * D * 2; }
;     __device__ __forceinline__ const char* b(const pg8::Unit& u) const { return (const char*)ws + boff + (size_t)u.pn * 256 * D * 2; }
;     __device__ __forceinline__ const char* a(const pg8::Unit& u) const { return (const char*)ws + WS_W1 + (size_t)(u.pm & 1) * 256 * 256 * 2; }
;     __device__ __forceinline__ const char* b(const pg8::Unit& u) const { return (const char*)ws + WS_A + ((size_t)u.pn * 256 * D + (size_t)(u.pm >> 1) * 256) * 2; }
; __device__ __forceinline__ void ssd_gate_norm_phase(Frame& F, int j, int nrows) {
;     ...
;     for (int r = gw; r < nrows; r += NGW) {
; #pragma unroll 4
;         for (int g = 0; g < 8; ++g) { const size_t off = (size_t)r * DI + g * 512 + lane * 8;
;             float a[8], b[8], zz[8]; unpack8(__builtin_nontemporal_load((const u32x4*)(yf + off)), a); unpack8(__builtin_nontemporal_load((const u32x4*)(yb + off)), b); unpack8(__builtin_nontemporal_load((const u32x4*)(z + off)), zz);
;             float ss = 0.f;
; #pragma unroll
;             for (int c = 0; c < 8; ++c) { a[c] = (a[c] + b[c]) * silu_f(zz[c]); ss += a[c] * a[c]; }
;             const float rs = rsqrtf(wave_sum(ss, lane) * (1.0f / 512.0f) + EPS);
;             const f32x4* gp = (const f32x4*)(ng + g * 512 + lane * 8); const f32x4 g0 = gp[0], g1 = gp[1];
;             a[0] *= rs * g0.x; a[1] *= rs * g0.y; a[2] *= rs * g0.z; a[3] *= rs * g0.w; a[4] *= rs * g1.x; a[5] *= rs * g1.y; a[6] *= rs * g1.z; a[7] *= rs * g1.w;
;             *(u32x4*)(yf + off) = pack8(a); }
.Lgn_row:
	s_add_i32 s5, s4, s72
	s_cmp_ge_i32 s5, s7
	s_cbranch_scc1 .Lgn_last
	s_waitcnt vmcnt(21)
	v_lshlrev_b32_e32 v198, 16, v4
	v_and_b32_e32 v199, 0xffff0000, v4
	v_lshlrev_b32_e32 v206, 16, v8
	v_and_b32_e32 v207, 0xffff0000, v8
	v_lshlrev_b32_e32 v214, 16, v12
	v_and_b32_e32 v215, 0xffff0000, v12
	v_lshlrev_b32_e32 v200, 16, v5
	v_and_b32_e32 v201, 0xffff0000, v5
	v_lshlrev_b32_e32 v208, 16, v9
	v_and_b32_e32 v209, 0xffff0000, v9
	v_lshlrev_b32_e32 v216, 16, v13
	v_and_b32_e32 v217, 0xffff0000, v13
	v_lshlrev_b32_e32 v202, 16, v6
	v_and_b32_e32 v203, 0xffff0000, v6
	v_lshlrev_b32_e32 v210, 16, v10
	v_and_b32_e32 v211, 0xffff0000, v10
	v_lshlrev_b32_e32 v218, 16, v14
	v_and_b32_e32 v219, 0xffff0000, v14
	v_lshlrev_b32_e32 v204, 16, v7
	v_and_b32_e32 v205, 0xffff0000, v7
	v_lshlrev_b32_e32 v212, 16, v11
	v_and_b32_e32 v213, 0xffff0000, v11
	v_lshlrev_b32_e32 v220, 16, v15
	v_and_b32_e32 v221, 0xffff0000, v15
	global_load_dwordx4 v[4:7], v[168:169], off nt
	global_load_dwordx4 v[8:11], v[172:173], off nt
	global_load_dwordx4 v[12:15], v[178:179], off nt
	v_pk_add_f32 v[198:199], v[198:199], v[206:207]
	v_pk_add_f32 v[200:201], v[200:201], v[208:209]
	v_pk_add_f32 v[202:203], v[202:203], v[210:211]
	v_pk_add_f32 v[204:205], v[204:205], v[212:213]
	v_mul_f32_e32 v206, 0xbfb8aa3b, v214
	v_mul_f32_e32 v207, 0xbfb8aa3b, v215
	v_mul_f32_e32 v208, 0xbfb8aa3b, v216
	v_mul_f32_e32 v209, 0xbfb8aa3b, v217
	v_mul_f32_e32 v210, 0xbfb8aa3b, v218
	v_mul_f32_e32 v211, 0xbfb8aa3b, v219
	v_mul_f32_e32 v212, 0xbfb8aa3b, v220
	v_mul_f32_e32 v213, 0xbfb8aa3b, v221
	v_exp_f32_e32 v206, v206
	v_exp_f32_e32 v207, v207
	v_exp_f32_e32 v208, v208
	v_exp_f32_e32 v209, v209
	v_exp_f32_e32 v210, v210
	v_exp_f32_e32 v211, v211
	v_exp_f32_e32 v212, v212
	v_exp_f32_e32 v213, v213
	v_add_f32_e32 v206, 1.0, v206
	v_add_f32_e32 v207, 1.0, v207
	v_add_f32_e32 v208, 1.0, v208
	v_add_f32_e32 v209, 1.0, v209
	v_add_f32_e32 v210, 1.0, v210
	v_add_f32_e32 v211, 1.0, v211
	v_add_f32_e32 v212, 1.0, v212
	v_add_f32_e32 v213, 1.0, v213
	v_rcp_f32_e32 v206, v206
	v_rcp_f32_e32 v207, v207
	v_rcp_f32_e32 v208, v208
	v_rcp_f32_e32 v209, v209
	v_rcp_f32_e32 v210, v210
	v_rcp_f32_e32 v211, v211
	v_rcp_f32_e32 v212, v212
	v_rcp_f32_e32 v213, v213
	s_nop 0
	v_pk_mul_f32 v[206:207], v[206:207], v[214:215]
	v_pk_mul_f32 v[208:209], v[208:209], v[216:217]
	v_pk_mul_f32 v[210:211], v[210:211], v[218:219]
	v_pk_mul_f32 v[212:213], v[212:213], v[220:221]
	v_pk_mul_f32 v[198:199], v[198:199], v[206:207]
	v_pk_mul_f32 v[200:201], v[200:201], v[208:209]
	v_pk_mul_f32 v[202:203], v[202:203], v[210:211]
	v_pk_mul_f32 v[204:205], v[204:205], v[212:213]
	v_pk_mul_f32 v[214:215], v[198:199], v[198:199]
	v_pk_mul_f32 v[216:217], v[200:201], v[200:201]
	v_pk_mul_f32 v[218:219], v[202:203], v[202:203]
	v_pk_mul_f32 v[220:221], v[204:205], v[204:205]
	v_add_f32_e32 v230, v214, v215
	v_add_f32_e32 v230, v216, v230
	v_add_f32_e32 v230, v217, v230
	v_add_f32_e32 v230, v218, v230
	v_add_f32_e32 v230, v219, v230
	v_add_f32_e32 v230, v220, v230
	v_add_f32_e32 v230, v221, v230
	v_mov_b32_e32 v231, v177
	s_nop 0
	v_add_f32_dpp v230, v230, v230 row_shr:1 row_mask:0xf bank_mask:0xf bound_ctrl:1
	s_nop 1
	v_add_f32_dpp v230, v230, v230 row_shr:2 row_mask:0xf bank_mask:0xf bound_ctrl:1
	s_nop 1
	v_add_f32_dpp v230, v230, v230 row_shr:4 row_mask:0xf bank_mask:0xf bound_ctrl:1
	s_nop 1
	v_add_f32_dpp v230, v230, v230 row_shr:8 row_mask:0xf bank_mask:0xf bound_ctrl:1
	s_nop 1
	v_mov_b32_dpp v231, v230 row_bcast:15 row_mask:0xa bank_mask:0xf
	v_add_f32_e32 v230, v230, v231
	v_mov_b32_e32 v231, v177
	s_nop 1
	v_mov_b32_dpp v231, v230 row_bcast:31 row_mask:0xc bank_mask:0xf
	v_add_f32_e32 v230, v230, v231
	s_nop 0
	v_readlane_b32 s6, v230, 63
	s_nop 1
	v_fma_f32 v232, s6, v245, v238
	v_cmp_gt_f32_e32 vcc, s85, v232
	v_mul_f32_e32 v231, 0x4b800000, v232
	s_nop 0
	v_cndmask_b32_e32 v232, v232, v231, vcc
	v_rsq_f32_e32 v232, v232
	s_nop 0
	v_mul_f32_e32 v231, 0x45800000, v232
	v_cndmask_b32_e32 v232, v232, v231, vcc
	v_pk_mul_f32 v[222:223], v[100:101], v[232:233] op_sel_hi:[1,0]
	v_pk_mul_f32 v[224:225], v[102:103], v[232:233] op_sel_hi:[1,0]
	v_pk_mul_f32 v[226:227], v[104:105], v[232:233] op_sel_hi:[1,0]
	v_pk_mul_f32 v[228:229], v[106:107], v[232:233] op_sel_hi:[1,0]
	v_pk_mul_f32 v[222:223], v[198:199], v[222:223]
	v_pk_mul_f32 v[224:225], v[200:201], v[224:225]
	v_pk_mul_f32 v[226:227], v[202:203], v[226:227]
	v_pk_mul_f32 v[228:229], v[204:205], v[228:229]
	v_cvt_pk_bf16_f32 v234, v222, v223
	v_cvt_pk_bf16_f32 v235, v224, v225
	v_cvt_pk_bf16_f32 v236, v226, v227
	v_cvt_pk_bf16_f32 v237, v228, v229
	global_store_dwordx4 v[164:165], v[234:237], off
	s_waitcnt vmcnt(22)
; __device__ __forceinline__ float silu_f(float v) { return v * __builtin_amdgcn_rcpf(1.0f + __expf(-v)); }
;     __device__ __forceinline__ const char* a(const pg8::Unit& u) const { return (const char*)ws + aoff + (size_t)u.pm * 256 * K_ * 2 + (u.kq < 0 ? 0 : u.kq * (K_ / 4) * 2); }
;     __device__ __forceinline__ const char* b(const pg8::Unit& u) const { return (const char*)ws + boff + (size_t)u.pn * 256 * K_ * 2 + (u.kq < 0 ? 0 : u.kq * (K_ / 4) * 2); }
;     __device__ __forceinline__ const char* a(const pg8::Unit& u) const { return (const char*)ws + WS_A + (size_t)u.pm * 256 * D * 2; }
;     __device__ __forceinline__ const char* b(const pg8::Unit& u) const { return (const char*)ws + boff + (size_t)u.pn * 256 * D * 2; }
;     __device__ __forceinline__ const char* a(const pg8::Unit& u) const { return (const char*)ws + WS_A + (size_t)u.pm * 256 * D * 2; }
;     __device__ __forceinline__ const char* b(const pg8::Unit& u) const { return (const char*)ws + boff + (size_t)u.pn * 256 * D * 2; }
;     __device__ __forceinline__ const char* a(const pg8::Unit& u) const { return (const char*)ws + WS_W1 + (size_t)(u.pm & 1) * 256 * 256 * 2; }
;     __device__ __forceinline__ const char* b(const pg8::Unit& u) const { return (const char*)ws + WS_A + ((size_t)u.pn * 256 * D + (size_t)(u.pm >> 1) * 256) * 2; }
; __device__ __forceinline__ void ssd_gate_norm_phase(Frame& F, int j, int nrows) {
;     ...
;     for (int r = gw; r < nrows; r += NGW) {
; #pragma unroll 4
;         for (int g = 0; g < 8; ++g) { const size_t off = (size_t)r * DI + g * 512 + lane * 8;
;             float a[8], b[8], zz[8]; unpack8(__builtin_nontemporal_load((const u32x4*)(yf + off)), a); unpack8(__builtin_nontemporal_load((const u32x4*)(yb + off)), b); unpack8(__builtin_nontemporal_load((const u32x4*)(z + off)), zz);
;             float ss = 0.f;
; #pragma unroll
;             for (int c = 0; c < 8; ++c) { a[c] = (a[c] + b[c]) * silu_f(zz[c]); ss += a[c] * a[c]; }
;             const float rs = rsqrtf(wave_sum(ss, lane) * (1.0f / 512.0f) + EPS);
;             const f32x4* gp = (const f32x4*)(ng + g * 512 + lane * 8); const f32x4 g0 = gp[0], g1 = gp[1];
;             a[0] *= rs * g0.x; a[1] *= rs * g0.y; a[2] *= rs * g0.z; a[3] *= rs * g0.w; a[4] *= rs * g1.x; a[5] *= rs * g1.y; a[6] *= rs * g1.z; a[7] *= rs * g1.w;
;             *(u32x4*)(yf + off) = pack8(a); }
	v_lshlrev_b32_e32 v198, 16, v16
	v_and_b32_e32 v199, 0xffff0000, v16
	v_lshlrev_b32_e32 v206, 16, v20
	v_and_b32_e32 v207, 0xffff0000, v20
	v_lshlrev_b32_e32 v214, 16, v24
	v_and_b32_e32 v215, 0xffff0000, v24
	v_lshlrev_b32_e32 v200, 16, v17
	v_and_b32_e32 v201, 0xffff0000, v17
	v_lshlrev_b32_e32 v208, 16, v21
	v_and_b32_e32 v209, 0xffff0000, v21
	v_lshlrev_b32_e32 v216, 16, v25
	v_and_b32_e32 v217, 0xffff0000, v25
	v_lshlrev_b32_e32 v202, 16, v18
	v_and_b32_e32 v203, 0xffff0000, v18
	v_lshlrev_b32_e32 v210, 16, v22
	v_and_b32_e32 v211, 0xffff0000, v22
	v_lshlrev_b32_e32 v218, 16, v26
	v_and_b32_e32 v219, 0xffff0000, v26
	v_lshlrev_b32_e32 v204, 16, v19
	v_and_b32_e32 v205, 0xffff0000, v19
	v_lshlrev_b32_e32 v212, 16, v23
	v_and_b32_e32 v213, 0xffff0000, v23
	v_lshlrev_b32_e32 v220, 16, v27
	v_and_b32_e32 v221, 0xffff0000, v27
	global_load_dwordx4 v[16:19], v[168:169], off offset:1024 nt
	global_load_dwordx4 v[20:23], v[172:173], off offset:1024 nt
	global_load_dwordx4 v[24:27], v[178:179], off offset:1024 nt
	v_pk_add_f32 v[198:199], v[198:199], v[206:207]
	v_pk_add_f32 v[200:201], v[200:201], v[208:209]
	v_pk_add_f32 v[202:203], v[202:203], v[210:211]
	v_pk_add_f32 v[204:205], v[204:205], v[212:213]
	v_mul_f32_e32 v206, 0xbfb8aa3b, v214
	v_mul_f32_e32 v207, 0xbfb8aa3b, v215
	v_mul_f32_e32 v208, 0xbfb8aa3b, v216
	v_mul_f32_e32 v209, 0xbfb8aa3b, v217
	v_mul_f32_e32 v210, 0xbfb8aa3b, v218
	v_mul_f32_e32 v211, 0xbfb8aa3b, v219
	v_mul_f32_e32 v212, 0xbfb8aa3b, v220
	v_mul_f32_e32 v213, 0xbfb8aa3b, v221
	v_exp_f32_e32 v206, v206
	v_exp_f32_e32 v207, v207
	v_exp_f32_e32 v208, v208
	v_exp_f32_e32 v209, v209
	v_exp_f32_e32 v210, v210
	v_exp_f32_e32 v211, v211
	v_exp_f32_e32 v212, v212
	v_exp_f32_e32 v213, v213
	v_add_f32_e32 v206, 1.0, v206
	v_add_f32_e32 v207, 1.0, v207
	v_add_f32_e32 v208, 1.0, v208
	v_add_f32_e32 v209, 1.0, v209
	v_add_f32_e32 v210, 1.0, v210
	v_add_f32_e32 v211, 1.0, v211
	v_add_f32_e32 v212, 1.0, v212
	v_add_f32_e32 v213, 1.0, v213
	v_rcp_f32_e32 v206, v206
	v_rcp_f32_e32 v207, v207
	v_rcp_f32_e32 v208, v208
	v_rcp_f32_e32 v209, v209
	v_rcp_f32_e32 v210, v210
	v_rcp_f32_e32 v211, v211
	v_rcp_f32_e32 v212, v212
	v_rcp_f32_e32 v213, v213
	s_nop 0
	v_pk_mul_f32 v[206:207], v[206:207], v[214:215]
	v_pk_mul_f32 v[208:209], v[208:209], v[216:217]
	v_pk_mul_f32 v[210:211], v[210:211], v[218:219]
	v_pk_mul_f32 v[212:213], v[212:213], v[220:221]
	v_pk_mul_f32 v[198:199], v[198:199], v[206:207]
	v_pk_mul_f32 v[200:201], v[200:201], v[208:209]
	v_pk_mul_f32 v[202:203], v[202:203], v[210:211]
	v_pk_mul_f32 v[204:205], v[204:205], v[212:213]
	v_pk_mul_f32 v[214:215], v[198:199], v[198:199]
	v_pk_mul_f32 v[216:217], v[200:201], v[200:201]
	v_pk_mul_f32 v[218:219], v[202:203], v[202:203]
	v_pk_mul_f32 v[220:221], v[204:205], v[204:205]
	v_add_f32_e32 v230, v214, v215
	v_add_f32_e32 v230, v216, v230
	v_add_f32_e32 v230, v217, v230
	v_add_f32_e32 v230, v218, v230
	v_add_f32_e32 v230, v219, v230
	v_add_f32_e32 v230, v220, v230
	v_add_f32_e32 v230, v221, v230
	v_mov_b32_e32 v231, v177
	s_nop 0
	v_add_f32_dpp v230, v230, v230 row_shr:1 row_mask:0xf bank_mask:0xf bound_ctrl:1
	s_nop 1
	v_add_f32_dpp v230, v230, v230 row_shr:2 row_mask:0xf bank_mask:0xf bound_ctrl:1
	s_nop 1
	v_add_f32_dpp v230, v230, v230 row_shr:4 row_mask:0xf bank_mask:0xf bound_ctrl:1
	s_nop 1
	v_add_f32_dpp v230, v230, v230 row_shr:8 row_mask:0xf bank_mask:0xf bound_ctrl:1
	s_nop 1
	v_mov_b32_dpp v231, v230 row_bcast:15 row_mask:0xa bank_mask:0xf
	v_add_f32_e32 v230, v230, v231
	v_mov_b32_e32 v231, v177
	s_nop 1
	v_mov_b32_dpp v231, v230 row_bcast:31 row_mask:0xc bank_mask:0xf
	v_add_f32_e32 v230, v230, v231
	s_nop 0
	v_readlane_b32 s6, v230, 63
	s_nop 1
	v_fma_f32 v232, s6, v245, v238
	v_cmp_gt_f32_e32 vcc, s85, v232
	v_mul_f32_e32 v231, 0x4b800000, v232
	s_nop 0
	v_cndmask_b32_e32 v232, v232, v231, vcc
	v_rsq_f32_e32 v232, v232
	s_nop 0
	v_mul_f32_e32 v231, 0x45800000, v232
	v_cndmask_b32_e32 v232, v232, v231, vcc
	v_pk_mul_f32 v[222:223], v[108:109], v[232:233] op_sel_hi:[1,0]
	v_pk_mul_f32 v[224:225], v[110:111], v[232:233] op_sel_hi:[1,0]
	v_pk_mul_f32 v[226:227], v[112:113], v[232:233] op_sel_hi:[1,0]
	v_pk_mul_f32 v[228:229], v[114:115], v[232:233] op_sel_hi:[1,0]
	v_pk_mul_f32 v[222:223], v[198:199], v[222:223]
	v_pk_mul_f32 v[224:225], v[200:201], v[224:225]
	v_pk_mul_f32 v[226:227], v[202:203], v[226:227]
	v_pk_mul_f32 v[228:229], v[204:205], v[228:229]
	v_cvt_pk_bf16_f32 v234, v222, v223
	v_cvt_pk_bf16_f32 v235, v224, v225
	v_cvt_pk_bf16_f32 v236, v226, v227
	v_cvt_pk_bf16_f32 v237, v228, v229
	global_store_dwordx4 v[164:165], v[234:237], off offset:1024
	s_waitcnt vmcnt(23)
; __device__ __forceinline__ float silu_f(float v) { return v * __builtin_amdgcn_rcpf(1.0f + __expf(-v)); }
;     __device__ __forceinline__ const char* a(const pg8::Unit& u) const { return (const char*)ws + aoff + (size_t)u.pm * 256 * K_ * 2 + (u.kq < 0 ? 0 : u.kq * (K_ / 4) * 2); }
;     __device__ __forceinline__ const char* b(const pg8::Unit& u) const { return (const char*)ws + boff + (size_t)u.pn * 256 * K_ * 2 + (u.kq < 0 ? 0 : u.kq * (K_ / 4) * 2); }
;     __device__ __forceinline__ const char* a(const pg8::Unit& u) const { return (const char*)ws + WS_A + (size_t)u.pm * 256 * D * 2; }
;     __device__ __forceinline__ const char* b(const pg8::Unit& u) const { return (const char*)ws + boff + (size_t)u.pn * 256 * D * 2; }
;     __device__ __forceinline__ const char* a(const pg8::Unit& u) const { return (const char*)ws + WS_A + (size_t)u.pm * 256 * D * 2; }
;     __device__ __forceinline__ const char* b(const pg8::Unit& u) const { return (const char*)ws + boff + (size_t)u.pn * 256 * D * 2; }
;     __device__ __forceinline__ const char* a(const pg8::Unit& u) const { return (const char*)ws + WS_W1 + (size_t)(u.pm & 1) * 256 * 256 * 2; }
;     __device__ __forceinline__ const char* b(const pg8::Unit& u) const { return (const char*)ws + WS_A + ((size_t)u.pn * 256 * D + (size_t)(u.pm >> 1) * 256) * 2; }
; __device__ __forceinline__ void ssd_gate_norm_phase(Frame& F, int j, int nrows) {
;     ...
;     for (int r = gw; r < nrows; r += NGW) {
; #pragma unroll 4
;         for (int g = 0; g < 8; ++g) { const size_t off = (size_t)r * DI + g * 512 + lane * 8;
;             float a[8], b[8], zz[8]; unpack8(__builtin_nontemporal_load((const u32x4*)(yf + off)), a); unpack8(__builtin_nontemporal_load((const u32x4*)(yb + off)), b); unpack8(__builtin_nontemporal_load((const u32x4*)(z + off)), zz);
;             float ss = 0.f;
; #pragma unroll
;             for (int c = 0; c < 8; ++c) { a[c] = (a[c] + b[c]) * silu_f(zz[c]); ss += a[c] * a[c]; }
;             const float rs = rsqrtf(wave_sum(ss, lane) * (1.0f / 512.0f) + EPS);
;             const f32x4* gp = (const f32x4*)(ng + g * 512 + lane * 8); const f32x4 g0 = gp[0], g1 = gp[1];
;             a[0] *= rs * g0.x; a[1] *= rs * g0.y; a[2] *= rs * g0.z; a[3] *= rs * g0.w; a[4] *= rs * g1.x; a[5] *= rs * g1.y; a[6] *= rs * g1.z; a[7] *= rs * g1.w;
;             *(u32x4*)(yf + off) = pack8(a); }
	v_lshlrev_b32_e32 v198, 16, v28
	v_and_b32_e32 v199, 0xffff0000, v28
	v_lshlrev_b32_e32 v206, 16, v32
	v_and_b32_e32 v207, 0xffff0000, v32
	v_lshlrev_b32_e32 v214, 16, v36
	v_and_b32_e32 v215, 0xffff0000, v36
	v_lshlrev_b32_e32 v200, 16, v29
	v_and_b32_e32 v201, 0xffff0000, v29
	v_lshlrev_b32_e32 v208, 16, v33
	v_and_b32_e32 v209, 0xffff0000, v33
	v_lshlrev_b32_e32 v216, 16, v37
	v_and_b32_e32 v217, 0xffff0000, v37
	v_lshlrev_b32_e32 v202, 16, v30
	v_and_b32_e32 v203, 0xffff0000, v30
	v_lshlrev_b32_e32 v210, 16, v34
	v_and_b32_e32 v211, 0xffff0000, v34
	v_lshlrev_b32_e32 v218, 16, v38
	v_and_b32_e32 v219, 0xffff0000, v38
	v_lshlrev_b32_e32 v204, 16, v31
	v_and_b32_e32 v205, 0xffff0000, v31
	v_lshlrev_b32_e32 v212, 16, v35
	v_and_b32_e32 v213, 0xffff0000, v35
	v_lshlrev_b32_e32 v220, 16, v39
	v_and_b32_e32 v221, 0xffff0000, v39
	global_load_dwordx4 v[28:31], v[168:169], off offset:2048 nt
	global_load_dwordx4 v[32:35], v[172:173], off offset:2048 nt
	global_load_dwordx4 v[36:39], v[178:179], off offset:2048 nt
	v_pk_add_f32 v[198:199], v[198:199], v[206:207]
	v_pk_add_f32 v[200:201], v[200:201], v[208:209]
	v_pk_add_f32 v[202:203], v[202:203], v[210:211]
	v_pk_add_f32 v[204:205], v[204:205], v[212:213]
	v_mul_f32_e32 v206, 0xbfb8aa3b, v214
	v_mul_f32_e32 v207, 0xbfb8aa3b, v215
	v_mul_f32_e32 v208, 0xbfb8aa3b, v216
	v_mul_f32_e32 v209, 0xbfb8aa3b, v217
	v_mul_f32_e32 v210, 0xbfb8aa3b, v218
	v_mul_f32_e32 v211, 0xbfb8aa3b, v219
	v_mul_f32_e32 v212, 0xbfb8aa3b, v220
	v_mul_f32_e32 v213, 0xbfb8aa3b, v221
	v_exp_f32_e32 v206, v206
	v_exp_f32_e32 v207, v207
	v_exp_f32_e32 v208, v208
	v_exp_f32_e32 v209, v209
	v_exp_f32_e32 v210, v210
	v_exp_f32_e32 v211, v211
	v_exp_f32_e32 v212, v212
	v_exp_f32_e32 v213, v213
	v_add_f32_e32 v206, 1.0, v206
	v_add_f32_e32 v207, 1.0, v207
	v_add_f32_e32 v208, 1.0, v208
	v_add_f32_e32 v209, 1.0, v209
	v_add_f32_e32 v210, 1.0, v210
	v_add_f32_e32 v211, 1.0, v211
	v_add_f32_e32 v212, 1.0, v212
	v_add_f32_e32 v213, 1.0, v213
	v_rcp_f32_e32 v206, v206
	v_rcp_f32_e32 v207, v207
	v_rcp_f32_e32 v208, v208
	v_rcp_f32_e32 v209, v209
	v_rcp_f32_e32 v210, v210
	v_rcp_f32_e32 v211, v211
	v_rcp_f32_e32 v212, v212
	v_rcp_f32_e32 v213, v213
	s_nop 0
	v_pk_mul_f32 v[206:207], v[206:207], v[214:215]
	v_pk_mul_f32 v[208:209], v[208:209], v[216:217]
	v_pk_mul_f32 v[210:211], v[210:211], v[218:219]
	v_pk_mul_f32 v[212:213], v[212:213], v[220:221]
	v_pk_mul_f32 v[198:199], v[198:199], v[206:207]
	v_pk_mul_f32 v[200:201], v[200:201], v[208:209]
	v_pk_mul_f32 v[202:203], v[202:203], v[210:211]
	v_pk_mul_f32 v[204:205], v[204:205], v[212:213]
	v_pk_mul_f32 v[214:215], v[198:199], v[198:199]
	v_pk_mul_f32 v[216:217], v[200:201], v[200:201]
	v_pk_mul_f32 v[218:219], v[202:203], v[202:203]
	v_pk_mul_f32 v[220:221], v[204:205], v[204:205]
	v_add_f32_e32 v230, v214, v215
	v_add_f32_e32 v230, v216, v230
	v_add_f32_e32 v230, v217, v230
	v_add_f32_e32 v230, v218, v230
	v_add_f32_e32 v230, v219, v230
	v_add_f32_e32 v230, v220, v230
	v_add_f32_e32 v230, v221, v230
	v_mov_b32_e32 v231, v177
	s_nop 0
	v_add_f32_dpp v230, v230, v230 row_shr:1 row_mask:0xf bank_mask:0xf bound_ctrl:1
	s_nop 1
	v_add_f32_dpp v230, v230, v230 row_shr:2 row_mask:0xf bank_mask:0xf bound_ctrl:1
	s_nop 1
	v_add_f32_dpp v230, v230, v230 row_shr:4 row_mask:0xf bank_mask:0xf bound_ctrl:1
	s_nop 1
	v_add_f32_dpp v230, v230, v230 row_shr:8 row_mask:0xf bank_mask:0xf bound_ctrl:1
	s_nop 1
	v_mov_b32_dpp v231, v230 row_bcast:15 row_mask:0xa bank_mask:0xf
	v_add_f32_e32 v230, v230, v231
	v_mov_b32_e32 v231, v177
	s_nop 1
	v_mov_b32_dpp v231, v230 row_bcast:31 row_mask:0xc bank_mask:0xf
	v_add_f32_e32 v230, v230, v231
	s_nop 0
	v_readlane_b32 s6, v230, 63
	s_nop 1
	v_fma_f32 v232, s6, v245, v238
	v_cmp_gt_f32_e32 vcc, s85, v232
	v_mul_f32_e32 v231, 0x4b800000, v232
	s_nop 0
	v_cndmask_b32_e32 v232, v232, v231, vcc
	v_rsq_f32_e32 v232, v232
	s_nop 0
	v_mul_f32_e32 v231, 0x45800000, v232
	v_cndmask_b32_e32 v232, v232, v231, vcc
	v_pk_mul_f32 v[222:223], v[116:117], v[232:233] op_sel_hi:[1,0]
	v_pk_mul_f32 v[224:225], v[118:119], v[232:233] op_sel_hi:[1,0]
	v_pk_mul_f32 v[226:227], v[120:121], v[232:233] op_sel_hi:[1,0]
	v_pk_mul_f32 v[228:229], v[122:123], v[232:233] op_sel_hi:[1,0]
	v_pk_mul_f32 v[222:223], v[198:199], v[222:223]
	v_pk_mul_f32 v[224:225], v[200:201], v[224:225]
	v_pk_mul_f32 v[226:227], v[202:203], v[226:227]
	v_pk_mul_f32 v[228:229], v[204:205], v[228:229]
	v_cvt_pk_bf16_f32 v234, v222, v223
	v_cvt_pk_bf16_f32 v235, v224, v225
	v_cvt_pk_bf16_f32 v236, v226, v227
	v_cvt_pk_bf16_f32 v237, v228, v229
	global_store_dwordx4 v[164:165], v[234:237], off offset:2048
	s_waitcnt vmcnt(24)
; __device__ __forceinline__ float silu_f(float v) { return v * __builtin_amdgcn_rcpf(1.0f + __expf(-v)); }
;     __device__ __forceinline__ const char* a(const pg8::Unit& u) const { return (const char*)ws + aoff + (size_t)u.pm * 256 * K_ * 2 + (u.kq < 0 ? 0 : u.kq * (K_ / 4) * 2); }
;     __device__ __forceinline__ const char* b(const pg8::Unit& u) const { return (const char*)ws + boff + (size_t)u.pn * 256 * K_ * 2 + (u.kq < 0 ? 0 : u.kq * (K_ / 4) * 2); }
;     __device__ __forceinline__ const char* a(const pg8::Unit& u) const { return (const char*)ws + WS_A + (size_t)u.pm * 256 * D * 2; }
;     __device__ __forceinline__ const char* b(const pg8::Unit& u) const { return (const char*)ws + boff + (size_t)u.pn * 256 * D * 2; }
;     __device__ __forceinline__ const char* a(const pg8::Unit& u) const { return (const char*)ws + WS_A + (size_t)u.pm * 256 * D * 2; }
;     __device__ __forceinline__ const char* b(const pg8::Unit& u) const { return (const char*)ws + boff + (size_t)u.pn * 256 * D * 2; }
;     __device__ __forceinline__ const char* a(const pg8::Unit& u) const { return (const char*)ws + WS_W1 + (size_t)(u.pm & 1) * 256 * 256 * 2; }
;     __device__ __forceinline__ const char* b(const pg8::Unit& u) const { return (const char*)ws + WS_A + ((size_t)u.pn * 256 * D + (size_t)(u.pm >> 1) * 256) * 2; }
; __device__ __forceinline__ void ssd_gate_norm_phase(Frame& F, int j, int nrows) {
;     ...
;     for (int r = gw; r < nrows; r += NGW) {
; #pragma unroll 4
;         for (int g = 0; g < 8; ++g) { const size_t off = (size_t)r * DI + g * 512 + lane * 8;
;             float a[8], b[8], zz[8]; unpack8(__builtin_nontemporal_load((const u32x4*)(yf + off)), a); unpack8(__builtin_nontemporal_load((const u32x4*)(yb + off)), b); unpack8(__builtin_nontemporal_load((const u32x4*)(z + off)), zz);
;             float ss = 0.f;
; #pragma unroll
;             for (int c = 0; c < 8; ++c) { a[c] = (a[c] + b[c]) * silu_f(zz[c]); ss += a[c] * a[c]; }
;             const float rs = rsqrtf(wave_sum(ss, lane) * (1.0f / 512.0f) + EPS);
;             const f32x4* gp = (const f32x4*)(ng + g * 512 + lane * 8); const f32x4 g0 = gp[0], g1 = gp[1];
;             a[0] *= rs * g0.x; a[1] *= rs * g0.y; a[2] *= rs * g0.z; a[3] *= rs * g0.w; a[4] *= rs * g1.x; a[5] *= rs * g1.y; a[6] *= rs * g1.z; a[7] *= rs * g1.w;
;             *(u32x4*)(yf + off) = pack8(a); }
	v_lshlrev_b32_e32 v198, 16, v40
	v_and_b32_e32 v199, 0xffff0000, v40
	v_lshlrev_b32_e32 v206, 16, v44
	v_and_b32_e32 v207, 0xffff0000, v44
	v_lshlrev_b32_e32 v214, 16, v48
	v_and_b32_e32 v215, 0xffff0000, v48
	v_lshlrev_b32_e32 v200, 16, v41
	v_and_b32_e32 v201, 0xffff0000, v41
	v_lshlrev_b32_e32 v208, 16, v45
	v_and_b32_e32 v209, 0xffff0000, v45
	v_lshlrev_b32_e32 v216, 16, v49
	v_and_b32_e32 v217, 0xffff0000, v49
	v_lshlrev_b32_e32 v202, 16, v42
	v_and_b32_e32 v203, 0xffff0000, v42
	v_lshlrev_b32_e32 v210, 16, v46
	v_and_b32_e32 v211, 0xffff0000, v46
	v_lshlrev_b32_e32 v218, 16, v50
	v_and_b32_e32 v219, 0xffff0000, v50
	v_lshlrev_b32_e32 v204, 16, v43
	v_and_b32_e32 v205, 0xffff0000, v43
	v_lshlrev_b32_e32 v212, 16, v47
	v_and_b32_e32 v213, 0xffff0000, v47
	v_lshlrev_b32_e32 v220, 16, v51
	v_and_b32_e32 v221, 0xffff0000, v51
	global_load_dwordx4 v[40:43], v[168:169], off offset:3072 nt
	global_load_dwordx4 v[44:47], v[172:173], off offset:3072 nt
	global_load_dwordx4 v[48:51], v[178:179], off offset:3072 nt
	v_pk_add_f32 v[198:199], v[198:199], v[206:207]
	v_pk_add_f32 v[200:201], v[200:201], v[208:209]
	v_pk_add_f32 v[202:203], v[202:203], v[210:211]
	v_pk_add_f32 v[204:205], v[204:205], v[212:213]
	v_mul_f32_e32 v206, 0xbfb8aa3b, v214
	v_mul_f32_e32 v207, 0xbfb8aa3b, v215
	v_mul_f32_e32 v208, 0xbfb8aa3b, v216
	v_mul_f32_e32 v209, 0xbfb8aa3b, v217
	v_mul_f32_e32 v210, 0xbfb8aa3b, v218
	v_mul_f32_e32 v211, 0xbfb8aa3b, v219
	v_mul_f32_e32 v212, 0xbfb8aa3b, v220
	v_mul_f32_e32 v213, 0xbfb8aa3b, v221
	v_exp_f32_e32 v206, v206
	v_exp_f32_e32 v207, v207
	v_exp_f32_e32 v208, v208
	v_exp_f32_e32 v209, v209
	v_exp_f32_e32 v210, v210
	v_exp_f32_e32 v211, v211
	v_exp_f32_e32 v212, v212
	v_exp_f32_e32 v213, v213
	v_add_f32_e32 v206, 1.0, v206
	v_add_f32_e32 v207, 1.0, v207
	v_add_f32_e32 v208, 1.0, v208
	v_add_f32_e32 v209, 1.0, v209
	v_add_f32_e32 v210, 1.0, v210
	v_add_f32_e32 v211, 1.0, v211
	v_add_f32_e32 v212, 1.0, v212
	v_add_f32_e32 v213, 1.0, v213
	v_rcp_f32_e32 v206, v206
	v_rcp_f32_e32 v207, v207
	v_rcp_f32_e32 v208, v208
	v_rcp_f32_e32 v209, v209
	v_rcp_f32_e32 v210, v210
	v_rcp_f32_e32 v211, v211
	v_rcp_f32_e32 v212, v212
	v_rcp_f32_e32 v213, v213
	s_nop 0
	v_pk_mul_f32 v[206:207], v[206:207], v[214:215]
	v_pk_mul_f32 v[208:209], v[208:209], v[216:217]
	v_pk_mul_f32 v[210:211], v[210:211], v[218:219]
	v_pk_mul_f32 v[212:213], v[212:213], v[220:221]
	v_pk_mul_f32 v[198:199], v[198:199], v[206:207]
	v_pk_mul_f32 v[200:201], v[200:201], v[208:209]
	v_pk_mul_f32 v[202:203], v[202:203], v[210:211]
	v_pk_mul_f32 v[204:205], v[204:205], v[212:213]
	v_pk_mul_f32 v[214:215], v[198:199], v[198:199]
	v_pk_mul_f32 v[216:217], v[200:201], v[200:201]
	v_pk_mul_f32 v[218:219], v[202:203], v[202:203]
	v_pk_mul_f32 v[220:221], v[204:205], v[204:205]
	v_add_f32_e32 v230, v214, v215
	v_add_f32_e32 v230, v216, v230
	v_add_f32_e32 v230, v217, v230
	v_add_f32_e32 v230, v218, v230
	v_add_f32_e32 v230, v219, v230
	v_add_f32_e32 v230, v220, v230
	v_add_f32_e32 v230, v221, v230
	v_mov_b32_e32 v231, v177
	s_nop 0
	v_add_f32_dpp v230, v230, v230 row_shr:1 row_mask:0xf bank_mask:0xf bound_ctrl:1
	s_nop 1
	v_add_f32_dpp v230, v230, v230 row_shr:2 row_mask:0xf bank_mask:0xf bound_ctrl:1
	s_nop 1
	v_add_f32_dpp v230, v230, v230 row_shr:4 row_mask:0xf bank_mask:0xf bound_ctrl:1
	s_nop 1
	v_add_f32_dpp v230, v230, v230 row_shr:8 row_mask:0xf bank_mask:0xf bound_ctrl:1
	s_nop 1
	v_mov_b32_dpp v231, v230 row_bcast:15 row_mask:0xa bank_mask:0xf
	v_add_f32_e32 v230, v230, v231
	v_mov_b32_e32 v231, v177
	s_nop 1
	v_mov_b32_dpp v231, v230 row_bcast:31 row_mask:0xc bank_mask:0xf
	v_add_f32_e32 v230, v230, v231
	s_nop 0
	v_readlane_b32 s6, v230, 63
	s_nop 1
	v_fma_f32 v232, s6, v245, v238
	v_cmp_gt_f32_e32 vcc, s85, v232
	v_mul_f32_e32 v231, 0x4b800000, v232
	s_nop 0
	v_cndmask_b32_e32 v232, v232, v231, vcc
	v_rsq_f32_e32 v232, v232
	s_nop 0
	v_mul_f32_e32 v231, 0x45800000, v232
	v_cndmask_b32_e32 v232, v232, v231, vcc
	v_pk_mul_f32 v[222:223], v[124:125], v[232:233] op_sel_hi:[1,0]
	v_pk_mul_f32 v[224:225], v[126:127], v[232:233] op_sel_hi:[1,0]
	v_pk_mul_f32 v[226:227], v[128:129], v[232:233] op_sel_hi:[1,0]
	v_pk_mul_f32 v[228:229], v[130:131], v[232:233] op_sel_hi:[1,0]
	v_pk_mul_f32 v[222:223], v[198:199], v[222:223]
	v_pk_mul_f32 v[224:225], v[200:201], v[224:225]
	v_pk_mul_f32 v[226:227], v[202:203], v[226:227]
	v_pk_mul_f32 v[228:229], v[204:205], v[228:229]
	v_cvt_pk_bf16_f32 v234, v222, v223
	v_cvt_pk_bf16_f32 v235, v224, v225
	v_cvt_pk_bf16_f32 v236, v226, v227
	v_cvt_pk_bf16_f32 v237, v228, v229
	global_store_dwordx4 v[164:165], v[234:237], off offset:3072
	s_waitcnt vmcnt(25)
; __device__ __forceinline__ float silu_f(float v) { return v * __builtin_amdgcn_rcpf(1.0f + __expf(-v)); }
;     __device__ __forceinline__ const char* a(const pg8::Unit& u) const { return (const char*)ws + aoff + (size_t)u.pm * 256 * K_ * 2 + (u.kq < 0 ? 0 : u.kq * (K_ / 4) * 2); }
;     __device__ __forceinline__ const char* b(const pg8::Unit& u) const { return (const char*)ws + boff + (size_t)u.pn * 256 * K_ * 2 + (u.kq < 0 ? 0 : u.kq * (K_ / 4) * 2); }
;     __device__ __forceinline__ const char* a(const pg8::Unit& u) const { return (const char*)ws + WS_A + (size_t)u.pm * 256 * D * 2; }
;     __device__ __forceinline__ const char* b(const pg8::Unit& u) const { return (const char*)ws + boff + (size_t)u.pn * 256 * D * 2; }
;     __device__ __forceinline__ const char* a(const pg8::Unit& u) const { return (const char*)ws + WS_A + (size_t)u.pm * 256 * D * 2; }
;     __device__ __forceinline__ const char* b(const pg8::Unit& u) const { return (const char*)ws + boff + (size_t)u.pn * 256 * D * 2; }
;     __device__ __forceinline__ const char* a(const pg8::Unit& u) const { return (const char*)ws + WS_W1 + (size_t)(u.pm & 1) * 256 * 256 * 2; }
;     __device__ __forceinline__ const char* b(const pg8::Unit& u) const { return (const char*)ws + WS_A + ((size_t)u.pn * 256 * D + (size_t)(u.pm >> 1) * 256) * 2; }
; __device__ __forceinline__ void ssd_gate_norm_phase(Frame& F, int j, int nrows) {
;     ...
;     for (int r = gw; r < nrows; r += NGW) {
; #pragma unroll 4
;         for (int g = 0; g < 8; ++g) { const size_t off = (size_t)r * DI + g * 512 + lane * 8;
;             float a[8], b[8], zz[8]; unpack8(__builtin_nontemporal_load((const u32x4*)(yf + off)), a); unpack8(__builtin_nontemporal_load((const u32x4*)(yb + off)), b); unpack8(__builtin_nontemporal_load((const u32x4*)(z + off)), zz);
;             float ss = 0.f;
; #pragma unroll
;             for (int c = 0; c < 8; ++c) { a[c] = (a[c] + b[c]) * silu_f(zz[c]); ss += a[c] * a[c]; }
;             const float rs = rsqrtf(wave_sum(ss, lane) * (1.0f / 512.0f) + EPS);
;             const f32x4* gp = (const f32x4*)(ng + g * 512 + lane * 8); const f32x4 g0 = gp[0], g1 = gp[1];
;             a[0] *= rs * g0.x; a[1] *= rs * g0.y; a[2] *= rs * g0.z; a[3] *= rs * g0.w; a[4] *= rs * g1.x; a[5] *= rs * g1.y; a[6] *= rs * g1.z; a[7] *= rs * g1.w;
;             *(u32x4*)(yf + off) = pack8(a); }
	v_lshlrev_b32_e32 v198, 16, v52
	v_and_b32_e32 v199, 0xffff0000, v52
	v_lshlrev_b32_e32 v206, 16, v56
	v_and_b32_e32 v207, 0xffff0000, v56
	v_lshlrev_b32_e32 v214, 16, v60
	v_and_b32_e32 v215, 0xffff0000, v60
	v_lshlrev_b32_e32 v200, 16, v53
	v_and_b32_e32 v201, 0xffff0000, v53
	v_lshlrev_b32_e32 v208, 16, v57
	v_and_b32_e32 v209, 0xffff0000, v57
	v_lshlrev_b32_e32 v216, 16, v61
	v_and_b32_e32 v217, 0xffff0000, v61
	v_lshlrev_b32_e32 v202, 16, v54
	v_and_b32_e32 v203, 0xffff0000, v54
	v_lshlrev_b32_e32 v210, 16, v58
	v_and_b32_e32 v211, 0xffff0000, v58
	v_lshlrev_b32_e32 v218, 16, v62
	v_and_b32_e32 v219, 0xffff0000, v62
	v_lshlrev_b32_e32 v204, 16, v55
	v_and_b32_e32 v205, 0xffff0000, v55
	v_lshlrev_b32_e32 v212, 16, v59
	v_and_b32_e32 v213, 0xffff0000, v59
	v_lshlrev_b32_e32 v220, 16, v63
	v_and_b32_e32 v221, 0xffff0000, v63
	global_load_dwordx4 v[52:55], v[170:171], off nt
	global_load_dwordx4 v[56:59], v[174:175], off nt
	global_load_dwordx4 v[60:63], v[180:181], off nt
	v_pk_add_f32 v[198:199], v[198:199], v[206:207]
	v_pk_add_f32 v[200:201], v[200:201], v[208:209]
	v_pk_add_f32 v[202:203], v[202:203], v[210:211]
	v_pk_add_f32 v[204:205], v[204:205], v[212:213]
	v_mul_f32_e32 v206, 0xbfb8aa3b, v214
	v_mul_f32_e32 v207, 0xbfb8aa3b, v215
	v_mul_f32_e32 v208, 0xbfb8aa3b, v216
	v_mul_f32_e32 v209, 0xbfb8aa3b, v217
	v_mul_f32_e32 v210, 0xbfb8aa3b, v218
	v_mul_f32_e32 v211, 0xbfb8aa3b, v219
	v_mul_f32_e32 v212, 0xbfb8aa3b, v220
	v_mul_f32_e32 v213, 0xbfb8aa3b, v221
	v_exp_f32_e32 v206, v206
	v_exp_f32_e32 v207, v207
	v_exp_f32_e32 v208, v208
	v_exp_f32_e32 v209, v209
	v_exp_f32_e32 v210, v210
	v_exp_f32_e32 v211, v211
	v_exp_f32_e32 v212, v212
	v_exp_f32_e32 v213, v213
	v_add_f32_e32 v206, 1.0, v206
	v_add_f32_e32 v207, 1.0, v207
	v_add_f32_e32 v208, 1.0, v208
	v_add_f32_e32 v209, 1.0, v209
	v_add_f32_e32 v210, 1.0, v210
	v_add_f32_e32 v211, 1.0, v211
	v_add_f32_e32 v212, 1.0, v212
	v_add_f32_e32 v213, 1.0, v213
	v_rcp_f32_e32 v206, v206
	v_rcp_f32_e32 v207, v207
	v_rcp_f32_e32 v208, v208
	v_rcp_f32_e32 v209, v209
	v_rcp_f32_e32 v210, v210
	v_rcp_f32_e32 v211, v211
	v_rcp_f32_e32 v212, v212
	v_rcp_f32_e32 v213, v213
	s_nop 0
	v_pk_mul_f32 v[206:207], v[206:207], v[214:215]
	v_pk_mul_f32 v[208:209], v[208:209], v[216:217]
	v_pk_mul_f32 v[210:211], v[210:211], v[218:219]
	v_pk_mul_f32 v[212:213], v[212:213], v[220:221]
	v_pk_mul_f32 v[198:199], v[198:199], v[206:207]
	v_pk_mul_f32 v[200:201], v[200:201], v[208:209]
	v_pk_mul_f32 v[202:203], v[202:203], v[210:211]
	v_pk_mul_f32 v[204:205], v[204:205], v[212:213]
	v_pk_mul_f32 v[214:215], v[198:199], v[198:199]
	v_pk_mul_f32 v[216:217], v[200:201], v[200:201]
	v_pk_mul_f32 v[218:219], v[202:203], v[202:203]
	v_pk_mul_f32 v[220:221], v[204:205], v[204:205]
	v_add_f32_e32 v230, v214, v215
	v_add_f32_e32 v230, v216, v230
	v_add_f32_e32 v230, v217, v230
	v_add_f32_e32 v230, v218, v230
	v_add_f32_e32 v230, v219, v230
	v_add_f32_e32 v230, v220, v230
	v_add_f32_e32 v230, v221, v230
	v_mov_b32_e32 v231, v177
	s_nop 0
	v_add_f32_dpp v230, v230, v230 row_shr:1 row_mask:0xf bank_mask:0xf bound_ctrl:1
	s_nop 1
	v_add_f32_dpp v230, v230, v230 row_shr:2 row_mask:0xf bank_mask:0xf bound_ctrl:1
	s_nop 1
	v_add_f32_dpp v230, v230, v230 row_shr:4 row_mask:0xf bank_mask:0xf bound_ctrl:1
	s_nop 1
	v_add_f32_dpp v230, v230, v230 row_shr:8 row_mask:0xf bank_mask:0xf bound_ctrl:1
	s_nop 1
	v_mov_b32_dpp v231, v230 row_bcast:15 row_mask:0xa bank_mask:0xf
	v_add_f32_e32 v230, v230, v231
	v_mov_b32_e32 v231, v177
	s_nop 1
	v_mov_b32_dpp v231, v230 row_bcast:31 row_mask:0xc bank_mask:0xf
	v_add_f32_e32 v230, v230, v231
	s_nop 0
	v_readlane_b32 s6, v230, 63
	s_nop 1
	v_fma_f32 v232, s6, v245, v238
	v_cmp_gt_f32_e32 vcc, s85, v232
	v_mul_f32_e32 v231, 0x4b800000, v232
	s_nop 0
	v_cndmask_b32_e32 v232, v232, v231, vcc
	v_rsq_f32_e32 v232, v232
	s_nop 0
	v_mul_f32_e32 v231, 0x45800000, v232
	v_cndmask_b32_e32 v232, v232, v231, vcc
	v_pk_mul_f32 v[222:223], v[132:133], v[232:233] op_sel_hi:[1,0]
	v_pk_mul_f32 v[224:225], v[134:135], v[232:233] op_sel_hi:[1,0]
	v_pk_mul_f32 v[226:227], v[136:137], v[232:233] op_sel_hi:[1,0]
	v_pk_mul_f32 v[228:229], v[138:139], v[232:233] op_sel_hi:[1,0]
	v_pk_mul_f32 v[222:223], v[198:199], v[222:223]
	v_pk_mul_f32 v[224:225], v[200:201], v[224:225]
	v_pk_mul_f32 v[226:227], v[202:203], v[226:227]
	v_pk_mul_f32 v[228:229], v[204:205], v[228:229]
	v_cvt_pk_bf16_f32 v234, v222, v223
	v_cvt_pk_bf16_f32 v235, v224, v225
	v_cvt_pk_bf16_f32 v236, v226, v227
	v_cvt_pk_bf16_f32 v237, v228, v229
	global_store_dwordx4 v[166:167], v[234:237], off
	s_waitcnt vmcnt(26)
; __device__ __forceinline__ float silu_f(float v) { return v * __builtin_amdgcn_rcpf(1.0f + __expf(-v)); }
;     __device__ __forceinline__ const char* a(const pg8::Unit& u) const { return (const char*)ws + aoff + (size_t)u.pm * 256 * K_ * 2 + (u.kq < 0 ? 0 : u.kq * (K_ / 4) * 2); }
;     __device__ __forceinline__ const char* b(const pg8::Unit& u) const { return (const char*)ws + boff + (size_t)u.pn * 256 * K_ * 2 + (u.kq < 0 ? 0 : u.kq * (K_ / 4) * 2); }
;     __device__ __forceinline__ const char* a(const pg8::Unit& u) const { return (const char*)ws + WS_A + (size_t)u.pm * 256 * D * 2; }
;     __device__ __forceinline__ const char* b(const pg8::Unit& u) const { return (const char*)ws + boff + (size_t)u.pn * 256 * D * 2; }
;     __device__ __forceinline__ const char* a(const pg8::Unit& u) const { return (const char*)ws + WS_A + (size_t)u.pm * 256 * D * 2; }
;     __device__ __forceinline__ const char* b(const pg8::Unit& u) const { return (const char*)ws + boff + (size_t)u.pn * 256 * D * 2; }
;     __device__ __forceinline__ const char* a(const pg8::Unit& u) const { return (const char*)ws + WS_W1 + (size_t)(u.pm & 1) * 256 * 256 * 2; }
;     __device__ __forceinline__ const char* b(const pg8::Unit& u) const { return (const char*)ws + WS_A + ((size_t)u.pn * 256 * D + (size_t)(u.pm >> 1) * 256) * 2; }
; __device__ __forceinline__ void ssd_gate_norm_phase(Frame& F, int j, int nrows) {
;     ...
;     for (int r = gw; r < nrows; r += NGW) {
; #pragma unroll 4
;         for (int g = 0; g < 8; ++g) { const size_t off = (size_t)r * DI + g * 512 + lane * 8;
;             float a[8], b[8], zz[8]; unpack8(__builtin_nontemporal_load((const u32x4*)(yf + off)), a); unpack8(__builtin_nontemporal_load((const u32x4*)(yb + off)), b); unpack8(__builtin_nontemporal_load((const u32x4*)(z + off)), zz);
;             float ss = 0.f;
; #pragma unroll
;             for (int c = 0; c < 8; ++c) { a[c] = (a[c] + b[c]) * silu_f(zz[c]); ss += a[c] * a[c]; }
;             const float rs = rsqrtf(wave_sum(ss, lane) * (1.0f / 512.0f) + EPS);
;             const f32x4* gp = (const f32x4*)(ng + g * 512 + lane * 8); const f32x4 g0 = gp[0], g1 = gp[1];
;             a[0] *= rs * g0.x; a[1] *= rs * g0.y; a[2] *= rs * g0.z; a[3] *= rs * g0.w; a[4] *= rs * g1.x; a[5] *= rs * g1.y; a[6] *= rs * g1.z; a[7] *= rs * g1.w;
;             *(u32x4*)(yf + off) = pack8(a); }
	v_lshlrev_b32_e32 v198, 16, v64
	v_and_b32_e32 v199, 0xffff0000, v64
	v_lshlrev_b32_e32 v206, 16, v68
	v_and_b32_e32 v207, 0xffff0000, v68
	v_lshlrev_b32_e32 v214, 16, v72
	v_and_b32_e32 v215, 0xffff0000, v72
	v_lshlrev_b32_e32 v200, 16, v65
	v_and_b32_e32 v201, 0xffff0000, v65
	v_lshlrev_b32_e32 v208, 16, v69
	v_and_b32_e32 v209, 0xffff0000, v69
	v_lshlrev_b32_e32 v216, 16, v73
	v_and_b32_e32 v217, 0xffff0000, v73
	v_lshlrev_b32_e32 v202, 16, v66
	v_and_b32_e32 v203, 0xffff0000, v66
	v_lshlrev_b32_e32 v210, 16, v70
	v_and_b32_e32 v211, 0xffff0000, v70
	v_lshlrev_b32_e32 v218, 16, v74
	v_and_b32_e32 v219, 0xffff0000, v74
	v_lshlrev_b32_e32 v204, 16, v67
	v_and_b32_e32 v205, 0xffff0000, v67
	v_lshlrev_b32_e32 v212, 16, v71
	v_and_b32_e32 v213, 0xffff0000, v71
	v_lshlrev_b32_e32 v220, 16, v75
	v_and_b32_e32 v221, 0xffff0000, v75
	global_load_dwordx4 v[64:67], v[170:171], off offset:1024 nt
	global_load_dwordx4 v[68:71], v[174:175], off offset:1024 nt
	global_load_dwordx4 v[72:75], v[180:181], off offset:1024 nt
	v_pk_add_f32 v[198:199], v[198:199], v[206:207]
	v_pk_add_f32 v[200:201], v[200:201], v[208:209]
	v_pk_add_f32 v[202:203], v[202:203], v[210:211]
	v_pk_add_f32 v[204:205], v[204:205], v[212:213]
	v_mul_f32_e32 v206, 0xbfb8aa3b, v214
	v_mul_f32_e32 v207, 0xbfb8aa3b, v215
	v_mul_f32_e32 v208, 0xbfb8aa3b, v216
	v_mul_f32_e32 v209, 0xbfb8aa3b, v217
	v_mul_f32_e32 v210, 0xbfb8aa3b, v218
	v_mul_f32_e32 v211, 0xbfb8aa3b, v219
	v_mul_f32_e32 v212, 0xbfb8aa3b, v220
	v_mul_f32_e32 v213, 0xbfb8aa3b, v221
	v_exp_f32_e32 v206, v206
	v_exp_f32_e32 v207, v207
	v_exp_f32_e32 v208, v208
	v_exp_f32_e32 v209, v209
	v_exp_f32_e32 v210, v210
	v_exp_f32_e32 v211, v211
	v_exp_f32_e32 v212, v212
	v_exp_f32_e32 v213, v213
	v_add_f32_e32 v206, 1.0, v206
	v_add_f32_e32 v207, 1.0, v207
	v_add_f32_e32 v208, 1.0, v208
	v_add_f32_e32 v209, 1.0, v209
	v_add_f32_e32 v210, 1.0, v210
	v_add_f32_e32 v211, 1.0, v211
	v_add_f32_e32 v212, 1.0, v212
	v_add_f32_e32 v213, 1.0, v213
	v_rcp_f32_e32 v206, v206
	v_rcp_f32_e32 v207, v207
	v_rcp_f32_e32 v208, v208
	v_rcp_f32_e32 v209, v209
	v_rcp_f32_e32 v210, v210
	v_rcp_f32_e32 v211, v211
	v_rcp_f32_e32 v212, v212
	v_rcp_f32_e32 v213, v213
	s_nop 0
	v_pk_mul_f32 v[206:207], v[206:207], v[214:215]
	v_pk_mul_f32 v[208:209], v[208:209], v[216:217]
	v_pk_mul_f32 v[210:211], v[210:211], v[218:219]
	v_pk_mul_f32 v[212:213], v[212:213], v[220:221]
	v_pk_mul_f32 v[198:199], v[198:199], v[206:207]
	v_pk_mul_f32 v[200:201], v[200:201], v[208:209]
	v_pk_mul_f32 v[202:203], v[202:203], v[210:211]
	v_pk_mul_f32 v[204:205], v[204:205], v[212:213]
	v_pk_mul_f32 v[214:215], v[198:199], v[198:199]
	v_pk_mul_f32 v[216:217], v[200:201], v[200:201]
	v_pk_mul_f32 v[218:219], v[202:203], v[202:203]
	v_pk_mul_f32 v[220:221], v[204:205], v[204:205]
	v_add_f32_e32 v230, v214, v215
	v_add_f32_e32 v230, v216, v230
	v_add_f32_e32 v230, v217, v230
	v_add_f32_e32 v230, v218, v230
	v_add_f32_e32 v230, v219, v230
	v_add_f32_e32 v230, v220, v230
	v_add_f32_e32 v230, v221, v230
	v_mov_b32_e32 v231, v177
	s_nop 0
	v_add_f32_dpp v230, v230, v230 row_shr:1 row_mask:0xf bank_mask:0xf bound_ctrl:1
	s_nop 1
	v_add_f32_dpp v230, v230, v230 row_shr:2 row_mask:0xf bank_mask:0xf bound_ctrl:1
	s_nop 1
	v_add_f32_dpp v230, v230, v230 row_shr:4 row_mask:0xf bank_mask:0xf bound_ctrl:1
	s_nop 1
	v_add_f32_dpp v230, v230, v230 row_shr:8 row_mask:0xf bank_mask:0xf bound_ctrl:1
	s_nop 1
	v_mov_b32_dpp v231, v230 row_bcast:15 row_mask:0xa bank_mask:0xf
	v_add_f32_e32 v230, v230, v231
	v_mov_b32_e32 v231, v177
	s_nop 1
	v_mov_b32_dpp v231, v230 row_bcast:31 row_mask:0xc bank_mask:0xf
	v_add_f32_e32 v230, v230, v231
	s_nop 0
	v_readlane_b32 s6, v230, 63
	s_nop 1
	v_fma_f32 v232, s6, v245, v238
	v_cmp_gt_f32_e32 vcc, s85, v232
	v_mul_f32_e32 v231, 0x4b800000, v232
	s_nop 0
	v_cndmask_b32_e32 v232, v232, v231, vcc
	v_rsq_f32_e32 v232, v232
	s_nop 0
	v_mul_f32_e32 v231, 0x45800000, v232
	v_cndmask_b32_e32 v232, v232, v231, vcc
	v_pk_mul_f32 v[222:223], v[140:141], v[232:233] op_sel_hi:[1,0]
	v_pk_mul_f32 v[224:225], v[142:143], v[232:233] op_sel_hi:[1,0]
	v_pk_mul_f32 v[226:227], v[144:145], v[232:233] op_sel_hi:[1,0]
	v_pk_mul_f32 v[228:229], v[146:147], v[232:233] op_sel_hi:[1,0]
	v_pk_mul_f32 v[222:223], v[198:199], v[222:223]
	v_pk_mul_f32 v[224:225], v[200:201], v[224:225]
	v_pk_mul_f32 v[226:227], v[202:203], v[226:227]
	v_pk_mul_f32 v[228:229], v[204:205], v[228:229]
	v_cvt_pk_bf16_f32 v234, v222, v223
	v_cvt_pk_bf16_f32 v235, v224, v225
	v_cvt_pk_bf16_f32 v236, v226, v227
	v_cvt_pk_bf16_f32 v237, v228, v229
	global_store_dwordx4 v[166:167], v[234:237], off offset:1024
	s_waitcnt vmcnt(27)
; __device__ __forceinline__ float silu_f(float v) { return v * __builtin_amdgcn_rcpf(1.0f + __expf(-v)); }
;     __device__ __forceinline__ const char* a(const pg8::Unit& u) const { return (const char*)ws + aoff + (size_t)u.pm * 256 * K_ * 2 + (u.kq < 0 ? 0 : u.kq * (K_ / 4) * 2); }
;     __device__ __forceinline__ const char* b(const pg8::Unit& u) const { return (const char*)ws + boff + (size_t)u.pn * 256 * K_ * 2 + (u.kq < 0 ? 0 : u.kq * (K_ / 4) * 2); }
;     __device__ __forceinline__ const char* a(const pg8::Unit& u) const { return (const char*)ws + WS_A + (size_t)u.pm * 256 * D * 2; }
;     __device__ __forceinline__ const char* b(const pg8::Unit& u) const { return (const char*)ws + boff + (size_t)u.pn * 256 * D * 2; }
;     __device__ __forceinline__ const char* a(const pg8::Unit& u) const { return (const char*)ws + WS_A + (size_t)u.pm * 256 * D * 2; }
;     __device__ __forceinline__ const char* b(const pg8::Unit& u) const { return (const char*)ws + boff + (size_t)u.pn * 256 * D * 2; }
;     __device__ __forceinline__ const char* a(const pg8::Unit& u) const { return (const char*)ws + WS_W1 + (size_t)(u.pm & 1) * 256 * 256 * 2; }
;     __device__ __forceinline__ const char* b(const pg8::Unit& u) const { return (const char*)ws + WS_A + ((size_t)u.pn * 256 * D + (size_t)(u.pm >> 1) * 256) * 2; }
; __device__ __forceinline__ void ssd_gate_norm_phase(Frame& F, int j, int nrows) {
;     ...
;     for (int r = gw; r < nrows; r += NGW) {
; #pragma unroll 4
;         for (int g = 0; g < 8; ++g) { const size_t off = (size_t)r * DI + g * 512 + lane * 8;
;             float a[8], b[8], zz[8]; unpack8(__builtin_nontemporal_load((const u32x4*)(yf + off)), a); unpack8(__builtin_nontemporal_load((const u32x4*)(yb + off)), b); unpack8(__builtin_nontemporal_load((const u32x4*)(z + off)), zz);
;             float ss = 0.f;
; #pragma unroll
;             for (int c = 0; c < 8; ++c) { a[c] = (a[c] + b[c]) * silu_f(zz[c]); ss += a[c] * a[c]; }
;             const float rs = rsqrtf(wave_sum(ss, lane) * (1.0f / 512.0f) + EPS);
;             const f32x4* gp = (const f32x4*)(ng + g * 512 + lane * 8); const f32x4 g0 = gp[0], g1 = gp[1];
;             a[0] *= rs * g0.x; a[1] *= rs * g0.y; a[2] *= rs * g0.z; a[3] *= rs * g0.w; a[4] *= rs * g1.x; a[5] *= rs * g1.y; a[6] *= rs * g1.z; a[7] *= rs * g1.w;
;             *(u32x4*)(yf + off) = pack8(a); }
	v_lshlrev_b32_e32 v198, 16, v76
	v_and_b32_e32 v199, 0xffff0000, v76
	v_lshlrev_b32_e32 v206, 16, v80
	v_and_b32_e32 v207, 0xffff0000, v80
	v_lshlrev_b32_e32 v214, 16, v84
	v_and_b32_e32 v215, 0xffff0000, v84
	v_lshlrev_b32_e32 v200, 16, v77
	v_and_b32_e32 v201, 0xffff0000, v77
	v_lshlrev_b32_e32 v208, 16, v81
	v_and_b32_e32 v209, 0xffff0000, v81
	v_lshlrev_b32_e32 v216, 16, v85
	v_and_b32_e32 v217, 0xffff0000, v85
	v_lshlrev_b32_e32 v202, 16, v78
	v_and_b32_e32 v203, 0xffff0000, v78
	v_lshlrev_b32_e32 v210, 16, v82
	v_and_b32_e32 v211, 0xffff0000, v82
	v_lshlrev_b32_e32 v218, 16, v86
	v_and_b32_e32 v219, 0xffff0000, v86
	v_lshlrev_b32_e32 v204, 16, v79
	v_and_b32_e32 v205, 0xffff0000, v79
	v_lshlrev_b32_e32 v212, 16, v83
	v_and_b32_e32 v213, 0xffff0000, v83
	v_lshlrev_b32_e32 v220, 16, v87
	v_and_b32_e32 v221, 0xffff0000, v87
	global_load_dwordx4 v[76:79], v[170:171], off offset:2048 nt
	global_load_dwordx4 v[80:83], v[174:175], off offset:2048 nt
	global_load_dwordx4 v[84:87], v[180:181], off offset:2048 nt
	v_pk_add_f32 v[198:199], v[198:199], v[206:207]
	v_pk_add_f32 v[200:201], v[200:201], v[208:209]
	v_pk_add_f32 v[202:203], v[202:203], v[210:211]
	v_pk_add_f32 v[204:205], v[204:205], v[212:213]
	v_mul_f32_e32 v206, 0xbfb8aa3b, v214
	v_mul_f32_e32 v207, 0xbfb8aa3b, v215
	v_mul_f32_e32 v208, 0xbfb8aa3b, v216
	v_mul_f32_e32 v209, 0xbfb8aa3b, v217
	v_mul_f32_e32 v210, 0xbfb8aa3b, v218
	v_mul_f32_e32 v211, 0xbfb8aa3b, v219
	v_mul_f32_e32 v212, 0xbfb8aa3b, v220
	v_mul_f32_e32 v213, 0xbfb8aa3b, v221
	v_exp_f32_e32 v206, v206
	v_exp_f32_e32 v207, v207
	v_exp_f32_e32 v208, v208
	v_exp_f32_e32 v209, v209
	v_exp_f32_e32 v210, v210
	v_exp_f32_e32 v211, v211
	v_exp_f32_e32 v212, v212
	v_exp_f32_e32 v213, v213
	v_add_f32_e32 v206, 1.0, v206
	v_add_f32_e32 v207, 1.0, v207
	v_add_f32_e32 v208, 1.0, v208
	v_add_f32_e32 v209, 1.0, v209
	v_add_f32_e32 v210, 1.0, v210
	v_add_f32_e32 v211, 1.0, v211
	v_add_f32_e32 v212, 1.0, v212
	v_add_f32_e32 v213, 1.0, v213
	v_rcp_f32_e32 v206, v206
	v_rcp_f32_e32 v207, v207
	v_rcp_f32_e32 v208, v208
	v_rcp_f32_e32 v209, v209
	v_rcp_f32_e32 v210, v210
	v_rcp_f32_e32 v211, v211
	v_rcp_f32_e32 v212, v212
	v_rcp_f32_e32 v213, v213
	s_nop 0
	v_pk_mul_f32 v[206:207], v[206:207], v[214:215]
	v_pk_mul_f32 v[208:209], v[208:209], v[216:217]
	v_pk_mul_f32 v[210:211], v[210:211], v[218:219]
	v_pk_mul_f32 v[212:213], v[212:213], v[220:221]
	v_pk_mul_f32 v[198:199], v[198:199], v[206:207]
	v_pk_mul_f32 v[200:201], v[200:201], v[208:209]
	v_pk_mul_f32 v[202:203], v[202:203], v[210:211]
	v_pk_mul_f32 v[204:205], v[204:205], v[212:213]
	v_pk_mul_f32 v[214:215], v[198:199], v[198:199]
	v_pk_mul_f32 v[216:217], v[200:201], v[200:201]
	v_pk_mul_f32 v[218:219], v[202:203], v[202:203]
	v_pk_mul_f32 v[220:221], v[204:205], v[204:205]
	v_add_f32_e32 v230, v214, v215
	v_add_f32_e32 v230, v216, v230
	v_add_f32_e32 v230, v217, v230
	v_add_f32_e32 v230, v218, v230
	v_add_f32_e32 v230, v219, v230
	v_add_f32_e32 v230, v220, v230
	v_add_f32_e32 v230, v221, v230
	v_mov_b32_e32 v231, v177
	s_nop 0
	v_add_f32_dpp v230, v230, v230 row_shr:1 row_mask:0xf bank_mask:0xf bound_ctrl:1
	s_nop 1
	v_add_f32_dpp v230, v230, v230 row_shr:2 row_mask:0xf bank_mask:0xf bound_ctrl:1
	s_nop 1
	v_add_f32_dpp v230, v230, v230 row_shr:4 row_mask:0xf bank_mask:0xf bound_ctrl:1
	s_nop 1
	v_add_f32_dpp v230, v230, v230 row_shr:8 row_mask:0xf bank_mask:0xf bound_ctrl:1
	s_nop 1
	v_mov_b32_dpp v231, v230 row_bcast:15 row_mask:0xa bank_mask:0xf
	v_add_f32_e32 v230, v230, v231
	v_mov_b32_e32 v231, v177
	s_nop 1
	v_mov_b32_dpp v231, v230 row_bcast:31 row_mask:0xc bank_mask:0xf
	v_add_f32_e32 v230, v230, v231
	s_nop 0
	v_readlane_b32 s6, v230, 63
	s_nop 1
	v_fma_f32 v232, s6, v245, v238
	v_cmp_gt_f32_e32 vcc, s85, v232
	v_mul_f32_e32 v231, 0x4b800000, v232
	s_nop 0
	v_cndmask_b32_e32 v232, v232, v231, vcc
	v_rsq_f32_e32 v232, v232
	s_nop 0
	v_mul_f32_e32 v231, 0x45800000, v232
	v_cndmask_b32_e32 v232, v232, v231, vcc
	v_pk_mul_f32 v[222:223], v[148:149], v[232:233] op_sel_hi:[1,0]
	v_pk_mul_f32 v[224:225], v[150:151], v[232:233] op_sel_hi:[1,0]
	v_pk_mul_f32 v[226:227], v[152:153], v[232:233] op_sel_hi:[1,0]
	v_pk_mul_f32 v[228:229], v[154:155], v[232:233] op_sel_hi:[1,0]
	v_pk_mul_f32 v[222:223], v[198:199], v[222:223]
	v_pk_mul_f32 v[224:225], v[200:201], v[224:225]
	v_pk_mul_f32 v[226:227], v[202:203], v[226:227]
	v_pk_mul_f32 v[228:229], v[204:205], v[228:229]
	v_cvt_pk_bf16_f32 v234, v222, v223
	v_cvt_pk_bf16_f32 v235, v224, v225
	v_cvt_pk_bf16_f32 v236, v226, v227
	v_cvt_pk_bf16_f32 v237, v228, v229
	global_store_dwordx4 v[166:167], v[234:237], off offset:2048
	s_waitcnt vmcnt(28)
; __device__ __forceinline__ float silu_f(float v) { return v * __builtin_amdgcn_rcpf(1.0f + __expf(-v)); }
;     __device__ __forceinline__ const char* a(const pg8::Unit& u) const { return (const char*)ws + aoff + (size_t)u.pm * 256 * K_ * 2 + (u.kq < 0 ? 0 : u.kq * (K_ / 4) * 2); }
;     __device__ __forceinline__ const char* b(const pg8::Unit& u) const { return (const char*)ws + boff + (size_t)u.pn * 256 * K_ * 2 + (u.kq < 0 ? 0 : u.kq * (K_ / 4) * 2); }
;     __device__ __forceinline__ const char* a(const pg8::Unit& u) const { return (const char*)ws + WS_A + (size_t)u.pm * 256 * D * 2; }
;     __device__ __forceinline__ const char* b(const pg8::Unit& u) const { return (const char*)ws + boff + (size_t)u.pn * 256 * D * 2; }
;     __device__ __forceinline__ const char* a(const pg8::Unit& u) const { return (const char*)ws + WS_A + (size_t)u.pm * 256 * D * 2; }
;     __device__ __forceinline__ const char* b(const pg8::Unit& u) const { return (const char*)ws + boff + (size_t)u.pn * 256 * D * 2; }
;     __device__ __forceinline__ const char* a(const pg8::Unit& u) const { return (const char*)ws + WS_W1 + (size_t)(u.pm & 1) * 256 * 256 * 2; }
;     __device__ __forceinline__ const char* b(const pg8::Unit& u) const { return (const char*)ws + WS_A + ((size_t)u.pn * 256 * D + (size_t)(u.pm >> 1) * 256) * 2; }
; __device__ __forceinline__ void ssd_gate_norm_phase(Frame& F, int j, int nrows) {
;     ...
;     for (int r = gw; r < nrows; r += NGW) {
; #pragma unroll 4
;         for (int g = 0; g < 8; ++g) { const size_t off = (size_t)r * DI + g * 512 + lane * 8;
;             float a[8], b[8], zz[8]; unpack8(__builtin_nontemporal_load((const u32x4*)(yf + off)), a); unpack8(__builtin_nontemporal_load((const u32x4*)(yb + off)), b); unpack8(__builtin_nontemporal_load((const u32x4*)(z + off)), zz);
;             float ss = 0.f;
; #pragma unroll
;             for (int c = 0; c < 8; ++c) { a[c] = (a[c] + b[c]) * silu_f(zz[c]); ss += a[c] * a[c]; }
;             const float rs = rsqrtf(wave_sum(ss, lane) * (1.0f / 512.0f) + EPS);
;             const f32x4* gp = (const f32x4*)(ng + g * 512 + lane * 8); const f32x4 g0 = gp[0], g1 = gp[1];
;             a[0] *= rs * g0.x; a[1] *= rs * g0.y; a[2] *= rs * g0.z; a[3] *= rs * g0.w; a[4] *= rs * g1.x; a[5] *= rs * g1.y; a[6] *= rs * g1.z; a[7] *= rs * g1.w;
;             *(u32x4*)(yf + off) = pack8(a); }
	v_lshlrev_b32_e32 v198, 16, v88
	v_and_b32_e32 v199, 0xffff0000, v88
	v_lshlrev_b32_e32 v206, 16, v92
	v_and_b32_e32 v207, 0xffff0000, v92
	v_lshlrev_b32_e32 v214, 16, v96
	v_and_b32_e32 v215, 0xffff0000, v96
	v_lshlrev_b32_e32 v200, 16, v89
	v_and_b32_e32 v201, 0xffff0000, v89
	v_lshlrev_b32_e32 v208, 16, v93
	v_and_b32_e32 v209, 0xffff0000, v93
	v_lshlrev_b32_e32 v216, 16, v97
	v_and_b32_e32 v217, 0xffff0000, v97
	v_lshlrev_b32_e32 v202, 16, v90
	v_and_b32_e32 v203, 0xffff0000, v90
	v_lshlrev_b32_e32 v210, 16, v94
	v_and_b32_e32 v211, 0xffff0000, v94
	v_lshlrev_b32_e32 v218, 16, v98
	v_and_b32_e32 v219, 0xffff0000, v98
	v_lshlrev_b32_e32 v204, 16, v91
	v_and_b32_e32 v205, 0xffff0000, v91
	v_lshlrev_b32_e32 v212, 16, v95
	v_and_b32_e32 v213, 0xffff0000, v95
	v_lshlrev_b32_e32 v220, 16, v99
	v_and_b32_e32 v221, 0xffff0000, v99
	global_load_dwordx4 v[88:91], v[170:171], off offset:3072 nt
	global_load_dwordx4 v[92:95], v[174:175], off offset:3072 nt
	global_load_dwordx4 v[96:99], v[180:181], off offset:3072 nt
	v_pk_add_f32 v[198:199], v[198:199], v[206:207]
	v_pk_add_f32 v[200:201], v[200:201], v[208:209]
	v_pk_add_f32 v[202:203], v[202:203], v[210:211]
	v_pk_add_f32 v[204:205], v[204:205], v[212:213]
	v_mul_f32_e32 v206, 0xbfb8aa3b, v214
	v_mul_f32_e32 v207, 0xbfb8aa3b, v215
	v_mul_f32_e32 v208, 0xbfb8aa3b, v216
	v_mul_f32_e32 v209, 0xbfb8aa3b, v217
	v_mul_f32_e32 v210, 0xbfb8aa3b, v218
	v_mul_f32_e32 v211, 0xbfb8aa3b, v219
	v_mul_f32_e32 v212, 0xbfb8aa3b, v220
	v_mul_f32_e32 v213, 0xbfb8aa3b, v221
	v_exp_f32_e32 v206, v206
	v_exp_f32_e32 v207, v207
	v_exp_f32_e32 v208, v208
	v_exp_f32_e32 v209, v209
	v_exp_f32_e32 v210, v210
	v_exp_f32_e32 v211, v211
	v_exp_f32_e32 v212, v212
	v_exp_f32_e32 v213, v213
	v_add_f32_e32 v206, 1.0, v206
	v_add_f32_e32 v207, 1.0, v207
	v_add_f32_e32 v208, 1.0, v208
	v_add_f32_e32 v209, 1.0, v209
	v_add_f32_e32 v210, 1.0, v210
	v_add_f32_e32 v211, 1.0, v211
	v_add_f32_e32 v212, 1.0, v212
	v_add_f32_e32 v213, 1.0, v213
	v_rcp_f32_e32 v206, v206
	v_rcp_f32_e32 v207, v207
	v_rcp_f32_e32 v208, v208
	v_rcp_f32_e32 v209, v209
	v_rcp_f32_e32 v210, v210
	v_rcp_f32_e32 v211, v211
	v_rcp_f32_e32 v212, v212
	v_rcp_f32_e32 v213, v213
	s_nop 0
	v_pk_mul_f32 v[206:207], v[206:207], v[214:215]
	v_pk_mul_f32 v[208:209], v[208:209], v[216:217]
	v_pk_mul_f32 v[210:211], v[210:211], v[218:219]
	v_pk_mul_f32 v[212:213], v[212:213], v[220:221]
	v_pk_mul_f32 v[198:199], v[198:199], v[206:207]
	v_pk_mul_f32 v[200:201], v[200:201], v[208:209]
	v_pk_mul_f32 v[202:203], v[202:203], v[210:211]
	v_pk_mul_f32 v[204:205], v[204:205], v[212:213]
	v_pk_mul_f32 v[214:215], v[198:199], v[198:199]
	v_pk_mul_f32 v[216:217], v[200:201], v[200:201]
	v_pk_mul_f32 v[218:219], v[202:203], v[202:203]
	v_pk_mul_f32 v[220:221], v[204:205], v[204:205]
	v_add_f32_e32 v230, v214, v215
	v_add_f32_e32 v230, v216, v230
	v_add_f32_e32 v230, v217, v230
	v_add_f32_e32 v230, v218, v230
	v_add_f32_e32 v230, v219, v230
	v_add_f32_e32 v230, v220, v230
	v_add_f32_e32 v230, v221, v230
	v_mov_b32_e32 v231, v177
	s_nop 0
	v_add_f32_dpp v230, v230, v230 row_shr:1 row_mask:0xf bank_mask:0xf bound_ctrl:1
	s_nop 1
	v_add_f32_dpp v230, v230, v230 row_shr:2 row_mask:0xf bank_mask:0xf bound_ctrl:1
	s_nop 1
	v_add_f32_dpp v230, v230, v230 row_shr:4 row_mask:0xf bank_mask:0xf bound_ctrl:1
	s_nop 1
	v_add_f32_dpp v230, v230, v230 row_shr:8 row_mask:0xf bank_mask:0xf bound_ctrl:1
	s_nop 1
	v_mov_b32_dpp v231, v230 row_bcast:15 row_mask:0xa bank_mask:0xf
	v_add_f32_e32 v230, v230, v231
	v_mov_b32_e32 v231, v177
	s_nop 1
	v_mov_b32_dpp v231, v230 row_bcast:31 row_mask:0xc bank_mask:0xf
	v_add_f32_e32 v230, v230, v231
	s_nop 0
	v_readlane_b32 s6, v230, 63
	s_nop 1
	v_fma_f32 v232, s6, v245, v238
	v_cmp_gt_f32_e32 vcc, s85, v232
	v_mul_f32_e32 v231, 0x4b800000, v232
	s_nop 0
	v_cndmask_b32_e32 v232, v232, v231, vcc
	v_rsq_f32_e32 v232, v232
	s_nop 0
	v_mul_f32_e32 v231, 0x45800000, v232
	v_cndmask_b32_e32 v232, v232, v231, vcc
	v_pk_mul_f32 v[222:223], v[156:157], v[232:233] op_sel_hi:[1,0]
	v_pk_mul_f32 v[224:225], v[158:159], v[232:233] op_sel_hi:[1,0]
	v_pk_mul_f32 v[226:227], v[160:161], v[232:233] op_sel_hi:[1,0]
	v_pk_mul_f32 v[228:229], v[162:163], v[232:233] op_sel_hi:[1,0]
	v_pk_mul_f32 v[222:223], v[198:199], v[222:223]
	v_pk_mul_f32 v[224:225], v[200:201], v[224:225]
	v_pk_mul_f32 v[226:227], v[202:203], v[226:227]
	v_pk_mul_f32 v[228:229], v[204:205], v[228:229]
	v_cvt_pk_bf16_f32 v234, v222, v223
	v_cvt_pk_bf16_f32 v235, v224, v225
	v_cvt_pk_bf16_f32 v236, v226, v227
	v_cvt_pk_bf16_f32 v237, v228, v229
	global_store_dwordx4 v[166:167], v[234:237], off offset:3072
	v_mov_b32_e32 v164, v168
	v_mov_b32_e32 v165, v169
	v_mov_b32_e32 v166, v170
	v_mov_b32_e32 v167, v171
	v_lshl_add_u64 v[168:169], v[168:169], 0, s[0:1]
	v_lshl_add_u64 v[170:171], v[170:171], 0, s[0:1]
	v_lshl_add_u64 v[172:173], v[172:173], 0, s[0:1]
	v_lshl_add_u64 v[174:175], v[174:175], 0, s[0:1]
	v_lshl_add_u64 v[178:179], v[178:179], 0, s[0:1]
	v_lshl_add_u64 v[180:181], v[180:181], 0, s[0:1]
	s_mov_b32 s4, s5
	s_branch .Lgn_row
; __device__ __forceinline__ float silu_f(float v) { return v * __builtin_amdgcn_rcpf(1.0f + __expf(-v)); }
;     __device__ __forceinline__ const char* a(const pg8::Unit& u) const { return (const char*)ws + aoff + (size_t)u.pm * 256 * K_ * 2 + (u.kq < 0 ? 0 : u.kq * (K_ / 4) * 2); }
;     __device__ __forceinline__ const char* b(const pg8::Unit& u) const { return (const char*)ws + boff + (size_t)u.pn * 256 * K_ * 2 + (u.kq < 0 ? 0 : u.kq * (K_ / 4) * 2); }
;     __device__ __forceinline__ const char* a(const pg8::Unit& u) const { return (const char*)ws + WS_A + (size_t)u.pm * 256 * D * 2; }
;     __device__ __forceinline__ const char* b(const pg8::Unit& u) const { return (const char*)ws + boff + (size_t)u.pn * 256 * D * 2; }
;     __device__ __forceinline__ const char* a(const pg8::Unit& u) const { return (const char*)ws + WS_A + (size_t)u.pm * 256 * D * 2; }
;     __device__ __forceinline__ const char* b(const pg8::Unit& u) const { return (const char*)ws + boff + (size_t)u.pn * 256 * D * 2; }
;     __device__ __forceinline__ const char* a(const pg8::Unit& u) const { return (const char*)ws + WS_W1 + (size_t)(u.pm & 1) * 256 * 256 * 2; }
;     __device__ __forceinline__ const char* b(const pg8::Unit& u) const { return (const char*)ws + WS_A + ((size_t)u.pn * 256 * D + (size_t)(u.pm >> 1) * 256) * 2; }
; __device__ __forceinline__ void ssd_gate_norm_phase(Frame& F, int j, int nrows) {
;     ...
;     for (int r = gw; r < nrows; r += NGW) {
; #pragma unroll 4
;         for (int g = 0; g < 8; ++g) { const size_t off = (size_t)r * DI + g * 512 + lane * 8;
;             float a[8], b[8], zz[8]; unpack8(__builtin_nontemporal_load((const u32x4*)(yf + off)), a); unpack8(__builtin_nontemporal_load((const u32x4*)(yb + off)), b); unpack8(__builtin_nontemporal_load((const u32x4*)(z + off)), zz);
;             float ss = 0.f;
; #pragma unroll
;             for (int c = 0; c < 8; ++c) { a[c] = (a[c] + b[c]) * silu_f(zz[c]); ss += a[c] * a[c]; }
;             const float rs = rsqrtf(wave_sum(ss, lane) * (1.0f / 512.0f) + EPS);
;             const f32x4* gp = (const f32x4*)(ng + g * 512 + lane * 8); const f32x4 g0 = gp[0], g1 = gp[1];
;             a[0] *= rs * g0.x; a[1] *= rs * g0.y; a[2] *= rs * g0.z; a[3] *= rs * g0.w; a[4] *= rs * g1.x; a[5] *= rs * g1.y; a[6] *= rs * g1.z; a[7] *= rs * g1.w;
;             *(u32x4*)(yf + off) = pack8(a); }
.Lgn_last:
	s_waitcnt vmcnt(21)
	v_lshlrev_b32_e32 v198, 16, v4
	v_and_b32_e32 v199, 0xffff0000, v4
	v_lshlrev_b32_e32 v206, 16, v8
	v_and_b32_e32 v207, 0xffff0000, v8
	v_lshlrev_b32_e32 v214, 16, v12
	v_and_b32_e32 v215, 0xffff0000, v12
	v_lshlrev_b32_e32 v200, 16, v5
	v_and_b32_e32 v201, 0xffff0000, v5
	v_lshlrev_b32_e32 v208, 16, v9
	v_and_b32_e32 v209, 0xffff0000, v9
	v_lshlrev_b32_e32 v216, 16, v13
	v_and_b32_e32 v217, 0xffff0000, v13
	v_lshlrev_b32_e32 v202, 16, v6
	v_and_b32_e32 v203, 0xffff0000, v6
	v_lshlrev_b32_e32 v210, 16, v10
	v_and_b32_e32 v211, 0xffff0000, v10
	v_lshlrev_b32_e32 v218, 16, v14
	v_and_b32_e32 v219, 0xffff0000, v14
	v_lshlrev_b32_e32 v204, 16, v7
	v_and_b32_e32 v205, 0xffff0000, v7
	v_lshlrev_b32_e32 v212, 16, v11
	v_and_b32_e32 v213, 0xffff0000, v11
	v_lshlrev_b32_e32 v220, 16, v15
	v_and_b32_e32 v221, 0xffff0000, v15
	v_pk_add_f32 v[198:199], v[198:199], v[206:207]
	v_pk_add_f32 v[200:201], v[200:201], v[208:209]
	v_pk_add_f32 v[202:203], v[202:203], v[210:211]
	v_pk_add_f32 v[204:205], v[204:205], v[212:213]
	v_mul_f32_e32 v206, 0xbfb8aa3b, v214
	v_mul_f32_e32 v207, 0xbfb8aa3b, v215
	v_mul_f32_e32 v208, 0xbfb8aa3b, v216
	v_mul_f32_e32 v209, 0xbfb8aa3b, v217
	v_mul_f32_e32 v210, 0xbfb8aa3b, v218
	v_mul_f32_e32 v211, 0xbfb8aa3b, v219
	v_mul_f32_e32 v212, 0xbfb8aa3b, v220
	v_mul_f32_e32 v213, 0xbfb8aa3b, v221
	v_exp_f32_e32 v206, v206
	v_exp_f32_e32 v207, v207
	v_exp_f32_e32 v208, v208
	v_exp_f32_e32 v209, v209
	v_exp_f32_e32 v210, v210
	v_exp_f32_e32 v211, v211
	v_exp_f32_e32 v212, v212
	v_exp_f32_e32 v213, v213
	v_add_f32_e32 v206, 1.0, v206
	v_add_f32_e32 v207, 1.0, v207
	v_add_f32_e32 v208, 1.0, v208
	v_add_f32_e32 v209, 1.0, v209
	v_add_f32_e32 v210, 1.0, v210
	v_add_f32_e32 v211, 1.0, v211
	v_add_f32_e32 v212, 1.0, v212
	v_add_f32_e32 v213, 1.0, v213
	v_rcp_f32_e32 v206, v206
	v_rcp_f32_e32 v207, v207
	v_rcp_f32_e32 v208, v208
	v_rcp_f32_e32 v209, v209
	v_rcp_f32_e32 v210, v210
	v_rcp_f32_e32 v211, v211
	v_rcp_f32_e32 v212, v212
	v_rcp_f32_e32 v213, v213
	s_nop 0
	v_pk_mul_f32 v[206:207], v[206:207], v[214:215]
	v_pk_mul_f32 v[208:209], v[208:209], v[216:217]
	v_pk_mul_f32 v[210:211], v[210:211], v[218:219]
	v_pk_mul_f32 v[212:213], v[212:213], v[220:221]
	v_pk_mul_f32 v[198:199], v[198:199], v[206:207]
	v_pk_mul_f32 v[200:201], v[200:201], v[208:209]
	v_pk_mul_f32 v[202:203], v[202:203], v[210:211]
	v_pk_mul_f32 v[204:205], v[204:205], v[212:213]
	v_pk_mul_f32 v[214:215], v[198:199], v[198:199]
	v_pk_mul_f32 v[216:217], v[200:201], v[200:201]
	v_pk_mul_f32 v[218:219], v[202:203], v[202:203]
	v_pk_mul_f32 v[220:221], v[204:205], v[204:205]
	v_add_f32_e32 v230, v214, v215
	v_add_f32_e32 v230, v216, v230
	v_add_f32_e32 v230, v217, v230
	v_add_f32_e32 v230, v218, v230
	v_add_f32_e32 v230, v219, v230
	v_add_f32_e32 v230, v220, v230
	v_add_f32_e32 v230, v221, v230
	v_mov_b32_e32 v231, v177
	s_nop 0
	v_add_f32_dpp v230, v230, v230 row_shr:1 row_mask:0xf bank_mask:0xf bound_ctrl:1
	s_nop 1
	v_add_f32_dpp v230, v230, v230 row_shr:2 row_mask:0xf bank_mask:0xf bound_ctrl:1
	s_nop 1
	v_add_f32_dpp v230, v230, v230 row_shr:4 row_mask:0xf bank_mask:0xf bound_ctrl:1
	s_nop 1
	v_add_f32_dpp v230, v230, v230 row_shr:8 row_mask:0xf bank_mask:0xf bound_ctrl:1
	s_nop 1
	v_mov_b32_dpp v231, v230 row_bcast:15 row_mask:0xa bank_mask:0xf
	v_add_f32_e32 v230, v230, v231
	v_mov_b32_e32 v231, v177
	s_nop 1
	v_mov_b32_dpp v231, v230 row_bcast:31 row_mask:0xc bank_mask:0xf
	v_add_f32_e32 v230, v230, v231
	s_nop 0
	v_readlane_b32 s6, v230, 63
	s_nop 1
	v_fma_f32 v232, s6, v245, v238
	v_cmp_gt_f32_e32 vcc, s85, v232
	v_mul_f32_e32 v231, 0x4b800000, v232
	s_nop 0
	v_cndmask_b32_e32 v232, v232, v231, vcc
	v_rsq_f32_e32 v232, v232
	s_nop 0
	v_mul_f32_e32 v231, 0x45800000, v232
	v_cndmask_b32_e32 v232, v232, v231, vcc
	v_pk_mul_f32 v[222:223], v[100:101], v[232:233] op_sel_hi:[1,0]
	v_pk_mul_f32 v[224:225], v[102:103], v[232:233] op_sel_hi:[1,0]
	v_pk_mul_f32 v[226:227], v[104:105], v[232:233] op_sel_hi:[1,0]
	v_pk_mul_f32 v[228:229], v[106:107], v[232:233] op_sel_hi:[1,0]
	v_pk_mul_f32 v[222:223], v[198:199], v[222:223]
	v_pk_mul_f32 v[224:225], v[200:201], v[224:225]
	v_pk_mul_f32 v[226:227], v[202:203], v[226:227]
	v_pk_mul_f32 v[228:229], v[204:205], v[228:229]
	v_cvt_pk_bf16_f32 v234, v222, v223
	v_cvt_pk_bf16_f32 v235, v224, v225
	v_cvt_pk_bf16_f32 v236, v226, v227
	v_cvt_pk_bf16_f32 v237, v228, v229
	global_store_dwordx4 v[164:165], v[234:237], off
	s_waitcnt vmcnt(19)
; __device__ __forceinline__ float silu_f(float v) { return v * __builtin_amdgcn_rcpf(1.0f + __expf(-v)); }
;     __device__ __forceinline__ const char* a(const pg8::Unit& u) const { return (const char*)ws + aoff + (size_t)u.pm * 256 * K_ * 2 + (u.kq < 0 ? 0 : u.kq * (K_ / 4) * 2); }
;     __device__ __forceinline__ const char* b(const pg8::Unit& u) const { return (const char*)ws + boff + (size_t)u.pn * 256 * K_ * 2 + (u.kq < 0 ? 0 : u.kq * (K_ / 4) * 2); }
;     __device__ __forceinline__ const char* a(const pg8::Unit& u) const { return (const char*)ws + WS_A + (size_t)u.pm * 256 * D * 2; }
;     __device__ __forceinline__ const char* b(const pg8::Unit& u) const { return (const char*)ws + boff + (size_t)u.pn * 256 * D * 2; }
;     __device__ __forceinline__ const char* a(const pg8::Unit& u) const { return (const char*)ws + WS_A + (size_t)u.pm * 256 * D * 2; }
;     __device__ __forceinline__ const char* b(const pg8::Unit& u) const { return (const char*)ws + boff + (size_t)u.pn * 256 * D * 2; }
;     __device__ __forceinline__ const char* a(const pg8::Unit& u) const { return (const char*)ws + WS_W1 + (size_t)(u.pm & 1) * 256 * 256 * 2; }
;     __device__ __forceinline__ const char* b(const pg8::Unit& u) const { return (const char*)ws + WS_A + ((size_t)u.pn * 256 * D + (size_t)(u.pm >> 1) * 256) * 2; }
; __device__ __forceinline__ void ssd_gate_norm_phase(Frame& F, int j, int nrows) {
;     ...
;     for (int r = gw; r < nrows; r += NGW) {
; #pragma unroll 4
;         for (int g = 0; g < 8; ++g) { const size_t off = (size_t)r * DI + g * 512 + lane * 8;
;             float a[8], b[8], zz[8]; unpack8(__builtin_nontemporal_load((const u32x4*)(yf + off)), a); unpack8(__builtin_nontemporal_load((const u32x4*)(yb + off)), b); unpack8(__builtin_nontemporal_load((const u32x4*)(z + off)), zz);
;             float ss = 0.f;
; #pragma unroll
;             for (int c = 0; c < 8; ++c) { a[c] = (a[c] + b[c]) * silu_f(zz[c]); ss += a[c] * a[c]; }
;             const float rs = rsqrtf(wave_sum(ss, lane) * (1.0f / 512.0f) + EPS);
;             const f32x4* gp = (const f32x4*)(ng + g * 512 + lane * 8); const f32x4 g0 = gp[0], g1 = gp[1];
;             a[0] *= rs * g0.x; a[1] *= rs * g0.y; a[2] *= rs * g0.z; a[3] *= rs * g0.w; a[4] *= rs * g1.x; a[5] *= rs * g1.y; a[6] *= rs * g1.z; a[7] *= rs * g1.w;
;             *(u32x4*)(yf + off) = pack8(a); }
	v_lshlrev_b32_e32 v198, 16, v16
	v_and_b32_e32 v199, 0xffff0000, v16
	v_lshlrev_b32_e32 v206, 16, v20
	v_and_b32_e32 v207, 0xffff0000, v20
	v_lshlrev_b32_e32 v214, 16, v24
	v_and_b32_e32 v215, 0xffff0000, v24
	v_lshlrev_b32_e32 v200, 16, v17
	v_and_b32_e32 v201, 0xffff0000, v17
	v_lshlrev_b32_e32 v208, 16, v21
	v_and_b32_e32 v209, 0xffff0000, v21
	v_lshlrev_b32_e32 v216, 16, v25
	v_and_b32_e32 v217, 0xffff0000, v25
	v_lshlrev_b32_e32 v202, 16, v18
	v_and_b32_e32 v203, 0xffff0000, v18
	v_lshlrev_b32_e32 v210, 16, v22
	v_and_b32_e32 v211, 0xffff0000, v22
	v_lshlrev_b32_e32 v218, 16, v26
	v_and_b32_e32 v219, 0xffff0000, v26
	v_lshlrev_b32_e32 v204, 16, v19
	v_and_b32_e32 v205, 0xffff0000, v19
	v_lshlrev_b32_e32 v212, 16, v23
	v_and_b32_e32 v213, 0xffff0000, v23
	v_lshlrev_b32_e32 v220, 16, v27
	v_and_b32_e32 v221, 0xffff0000, v27
	v_pk_add_f32 v[198:199], v[198:199], v[206:207]
	v_pk_add_f32 v[200:201], v[200:201], v[208:209]
	v_pk_add_f32 v[202:203], v[202:203], v[210:211]
	v_pk_add_f32 v[204:205], v[204:205], v[212:213]
	v_mul_f32_e32 v206, 0xbfb8aa3b, v214
	v_mul_f32_e32 v207, 0xbfb8aa3b, v215
	v_mul_f32_e32 v208, 0xbfb8aa3b, v216
	v_mul_f32_e32 v209, 0xbfb8aa3b, v217
	v_mul_f32_e32 v210, 0xbfb8aa3b, v218
	v_mul_f32_e32 v211, 0xbfb8aa3b, v219
	v_mul_f32_e32 v212, 0xbfb8aa3b, v220
	v_mul_f32_e32 v213, 0xbfb8aa3b, v221
	v_exp_f32_e32 v206, v206
	v_exp_f32_e32 v207, v207
	v_exp_f32_e32 v208, v208
	v_exp_f32_e32 v209, v209
	v_exp_f32_e32 v210, v210
	v_exp_f32_e32 v211, v211
	v_exp_f32_e32 v212, v212
	v_exp_f32_e32 v213, v213
	v_add_f32_e32 v206, 1.0, v206
	v_add_f32_e32 v207, 1.0, v207
	v_add_f32_e32 v208, 1.0, v208
	v_add_f32_e32 v209, 1.0, v209
	v_add_f32_e32 v210, 1.0, v210
	v_add_f32_e32 v211, 1.0, v211
	v_add_f32_e32 v212, 1.0, v212
	v_add_f32_e32 v213, 1.0, v213
	v_rcp_f32_e32 v206, v206
	v_rcp_f32_e32 v207, v207
	v_rcp_f32_e32 v208, v208
	v_rcp_f32_e32 v209, v209
	v_rcp_f32_e32 v210, v210
	v_rcp_f32_e32 v211, v211
	v_rcp_f32_e32 v212, v212
	v_rcp_f32_e32 v213, v213
	s_nop 0
	v_pk_mul_f32 v[206:207], v[206:207], v[214:215]
	v_pk_mul_f32 v[208:209], v[208:209], v[216:217]
	v_pk_mul_f32 v[210:211], v[210:211], v[218:219]
	v_pk_mul_f32 v[212:213], v[212:213], v[220:221]
	v_pk_mul_f32 v[198:199], v[198:199], v[206:207]
	v_pk_mul_f32 v[200:201], v[200:201], v[208:209]
	v_pk_mul_f32 v[202:203], v[202:203], v[210:211]
	v_pk_mul_f32 v[204:205], v[204:205], v[212:213]
	v_pk_mul_f32 v[214:215], v[198:199], v[198:199]
	v_pk_mul_f32 v[216:217], v[200:201], v[200:201]
	v_pk_mul_f32 v[218:219], v[202:203], v[202:203]
	v_pk_mul_f32 v[220:221], v[204:205], v[204:205]
	v_add_f32_e32 v230, v214, v215
	v_add_f32_e32 v230, v216, v230
	v_add_f32_e32 v230, v217, v230
	v_add_f32_e32 v230, v218, v230
	v_add_f32_e32 v230, v219, v230
	v_add_f32_e32 v230, v220, v230
	v_add_f32_e32 v230, v221, v230
	v_mov_b32_e32 v231, v177
	s_nop 0
	v_add_f32_dpp v230, v230, v230 row_shr:1 row_mask:0xf bank_mask:0xf bound_ctrl:1
	s_nop 1
	v_add_f32_dpp v230, v230, v230 row_shr:2 row_mask:0xf bank_mask:0xf bound_ctrl:1
	s_nop 1
	v_add_f32_dpp v230, v230, v230 row_shr:4 row_mask:0xf bank_mask:0xf bound_ctrl:1
	s_nop 1
	v_add_f32_dpp v230, v230, v230 row_shr:8 row_mask:0xf bank_mask:0xf bound_ctrl:1
	s_nop 1
	v_mov_b32_dpp v231, v230 row_bcast:15 row_mask:0xa bank_mask:0xf
	v_add_f32_e32 v230, v230, v231
	v_mov_b32_e32 v231, v177
	s_nop 1
	v_mov_b32_dpp v231, v230 row_bcast:31 row_mask:0xc bank_mask:0xf
	v_add_f32_e32 v230, v230, v231
	s_nop 0
	v_readlane_b32 s6, v230, 63
	s_nop 1
	v_fma_f32 v232, s6, v245, v238
	v_cmp_gt_f32_e32 vcc, s85, v232
	v_mul_f32_e32 v231, 0x4b800000, v232
	s_nop 0
	v_cndmask_b32_e32 v232, v232, v231, vcc
	v_rsq_f32_e32 v232, v232
	s_nop 0
	v_mul_f32_e32 v231, 0x45800000, v232
	v_cndmask_b32_e32 v232, v232, v231, vcc
	v_pk_mul_f32 v[222:223], v[108:109], v[232:233] op_sel_hi:[1,0]
	v_pk_mul_f32 v[224:225], v[110:111], v[232:233] op_sel_hi:[1,0]
	v_pk_mul_f32 v[226:227], v[112:113], v[232:233] op_sel_hi:[1,0]
	v_pk_mul_f32 v[228:229], v[114:115], v[232:233] op_sel_hi:[1,0]
	v_pk_mul_f32 v[222:223], v[198:199], v[222:223]
	v_pk_mul_f32 v[224:225], v[200:201], v[224:225]
	v_pk_mul_f32 v[226:227], v[202:203], v[226:227]
	v_pk_mul_f32 v[228:229], v[204:205], v[228:229]
	v_cvt_pk_bf16_f32 v234, v222, v223
	v_cvt_pk_bf16_f32 v235, v224, v225
	v_cvt_pk_bf16_f32 v236, v226, v227
	v_cvt_pk_bf16_f32 v237, v228, v229
	global_store_dwordx4 v[164:165], v[234:237], off offset:1024
	s_waitcnt vmcnt(17)
; __device__ __forceinline__ float silu_f(float v) { return v * __builtin_amdgcn_rcpf(1.0f + __expf(-v)); }
;     __device__ __forceinline__ const char* a(const pg8::Unit& u) const { return (const char*)ws + aoff + (size_t)u.pm * 256 * K_ * 2 + (u.kq < 0 ? 0 : u.kq * (K_ / 4) * 2); }
;     __device__ __forceinline__ const char* b(const pg8::Unit& u) const { return (const char*)ws + boff + (size_t)u.pn * 256 * K_ * 2 + (u.kq < 0 ? 0 : u.kq * (K_ / 4) * 2); }
;     __device__ __forceinline__ const char* a(const pg8::Unit& u) const { return (const char*)ws + WS_A + (size_t)u.pm * 256 * D * 2; }
;     __device__ __forceinline__ const char* b(const pg8::Unit& u) const { return (const char*)ws + boff + (size_t)u.pn * 256 * D * 2; }
;     __device__ __forceinline__ const char* a(const pg8::Unit& u) const { return (const char*)ws + WS_A + (size_t)u.pm * 256 * D * 2; }
;     __device__ __forceinline__ const char* b(const pg8::Unit& u) const { return (const char*)ws + boff + (size_t)u.pn * 256 * D * 2; }
;     __device__ __forceinline__ const char* a(const pg8::Unit& u) const { return (const char*)ws + WS_W1 + (size_t)(u.pm & 1) * 256 * 256 * 2; }
;     __device__ __forceinline__ const char* b(const pg8::Unit& u) const { return (const char*)ws + WS_A + ((size_t)u.pn * 256 * D + (size_t)(u.pm >> 1) * 256) * 2; }
; __device__ __forceinline__ void ssd_gate_norm_phase(Frame& F, int j, int nrows) {
;     ...
;     for (int r = gw; r < nrows; r += NGW) {
; #pragma unroll 4
;         for (int g = 0; g < 8; ++g) { const size_t off = (size_t)r * DI + g * 512 + lane * 8;
;             float a[8], b[8], zz[8]; unpack8(__builtin_nontemporal_load((const u32x4*)(yf + off)), a); unpack8(__builtin_nontemporal_load((const u32x4*)(yb + off)), b); unpack8(__builtin_nontemporal_load((const u32x4*)(z + off)), zz);
;             float ss = 0.f;
; #pragma unroll
;             for (int c = 0; c < 8; ++c) { a[c] = (a[c] + b[c]) * silu_f(zz[c]); ss += a[c] * a[c]; }
;             const float rs = rsqrtf(wave_sum(ss, lane) * (1.0f / 512.0f) + EPS);
;             const f32x4* gp = (const f32x4*)(ng + g * 512 + lane * 8); const f32x4 g0 = gp[0], g1 = gp[1];
;             a[0] *= rs * g0.x; a[1] *= rs * g0.y; a[2] *= rs * g0.z; a[3] *= rs * g0.w; a[4] *= rs * g1.x; a[5] *= rs * g1.y; a[6] *= rs * g1.z; a[7] *= rs * g1.w;
;             *(u32x4*)(yf + off) = pack8(a); }
	v_lshlrev_b32_e32 v198, 16, v28
	v_and_b32_e32 v199, 0xffff0000, v28
	v_lshlrev_b32_e32 v206, 16, v32
	v_and_b32_e32 v207, 0xffff0000, v32
	v_lshlrev_b32_e32 v214, 16, v36
	v_and_b32_e32 v215, 0xffff0000, v36
	v_lshlrev_b32_e32 v200, 16, v29
	v_and_b32_e32 v201, 0xffff0000, v29
	v_lshlrev_b32_e32 v208, 16, v33
	v_and_b32_e32 v209, 0xffff0000, v33
	v_lshlrev_b32_e32 v216, 16, v37
	v_and_b32_e32 v217, 0xffff0000, v37
	v_lshlrev_b32_e32 v202, 16, v30
	v_and_b32_e32 v203, 0xffff0000, v30
	v_lshlrev_b32_e32 v210, 16, v34
	v_and_b32_e32 v211, 0xffff0000, v34
	v_lshlrev_b32_e32 v218, 16, v38
	v_and_b32_e32 v219, 0xffff0000, v38
	v_lshlrev_b32_e32 v204, 16, v31
	v_and_b32_e32 v205, 0xffff0000, v31
	v_lshlrev_b32_e32 v212, 16, v35
	v_and_b32_e32 v213, 0xffff0000, v35
	v_lshlrev_b32_e32 v220, 16, v39
	v_and_b32_e32 v221, 0xffff0000, v39
	v_pk_add_f32 v[198:199], v[198:199], v[206:207]
	v_pk_add_f32 v[200:201], v[200:201], v[208:209]
	v_pk_add_f32 v[202:203], v[202:203], v[210:211]
	v_pk_add_f32 v[204:205], v[204:205], v[212:213]
	v_mul_f32_e32 v206, 0xbfb8aa3b, v214
	v_mul_f32_e32 v207, 0xbfb8aa3b, v215
	v_mul_f32_e32 v208, 0xbfb8aa3b, v216
	v_mul_f32_e32 v209, 0xbfb8aa3b, v217
	v_mul_f32_e32 v210, 0xbfb8aa3b, v218
	v_mul_f32_e32 v211, 0xbfb8aa3b, v219
	v_mul_f32_e32 v212, 0xbfb8aa3b, v220
	v_mul_f32_e32 v213, 0xbfb8aa3b, v221
	v_exp_f32_e32 v206, v206
	v_exp_f32_e32 v207, v207
	v_exp_f32_e32 v208, v208
	v_exp_f32_e32 v209, v209
	v_exp_f32_e32 v210, v210
	v_exp_f32_e32 v211, v211
	v_exp_f32_e32 v212, v212
	v_exp_f32_e32 v213, v213
	v_add_f32_e32 v206, 1.0, v206
	v_add_f32_e32 v207, 1.0, v207
	v_add_f32_e32 v208, 1.0, v208
	v_add_f32_e32 v209, 1.0, v209
	v_add_f32_e32 v210, 1.0, v210
	v_add_f32_e32 v211, 1.0, v211
	v_add_f32_e32 v212, 1.0, v212
	v_add_f32_e32 v213, 1.0, v213
	v_rcp_f32_e32 v206, v206
	v_rcp_f32_e32 v207, v207
	v_rcp_f32_e32 v208, v208
	v_rcp_f32_e32 v209, v209
	v_rcp_f32_e32 v210, v210
	v_rcp_f32_e32 v211, v211
	v_rcp_f32_e32 v212, v212
	v_rcp_f32_e32 v213, v213
	s_nop 0
	v_pk_mul_f32 v[206:207], v[206:207], v[214:215]
	v_pk_mul_f32 v[208:209], v[208:209], v[216:217]
	v_pk_mul_f32 v[210:211], v[210:211], v[218:219]
	v_pk_mul_f32 v[212:213], v[212:213], v[220:221]
	v_pk_mul_f32 v[198:199], v[198:199], v[206:207]
	v_pk_mul_f32 v[200:201], v[200:201], v[208:209]
	v_pk_mul_f32 v[202:203], v[202:203], v[210:211]
	v_pk_mul_f32 v[204:205], v[204:205], v[212:213]
	v_pk_mul_f32 v[214:215], v[198:199], v[198:199]
	v_pk_mul_f32 v[216:217], v[200:201], v[200:201]
	v_pk_mul_f32 v[218:219], v[202:203], v[202:203]
	v_pk_mul_f32 v[220:221], v[204:205], v[204:205]
	v_add_f32_e32 v230, v214, v215
	v_add_f32_e32 v230, v216, v230
	v_add_f32_e32 v230, v217, v230
	v_add_f32_e32 v230, v218, v230
	v_add_f32_e32 v230, v219, v230
	v_add_f32_e32 v230, v220, v230
	v_add_f32_e32 v230, v221, v230
	v_mov_b32_e32 v231, v177
	s_nop 0
	v_add_f32_dpp v230, v230, v230 row_shr:1 row_mask:0xf bank_mask:0xf bound_ctrl:1
	s_nop 1
	v_add_f32_dpp v230, v230, v230 row_shr:2 row_mask:0xf bank_mask:0xf bound_ctrl:1
	s_nop 1
	v_add_f32_dpp v230, v230, v230 row_shr:4 row_mask:0xf bank_mask:0xf bound_ctrl:1
	s_nop 1
	v_add_f32_dpp v230, v230, v230 row_shr:8 row_mask:0xf bank_mask:0xf bound_ctrl:1
	s_nop 1
	v_mov_b32_dpp v231, v230 row_bcast:15 row_mask:0xa bank_mask:0xf
	v_add_f32_e32 v230, v230, v231
	v_mov_b32_e32 v231, v177
	s_nop 1
	v_mov_b32_dpp v231, v230 row_bcast:31 row_mask:0xc bank_mask:0xf
	v_add_f32_e32 v230, v230, v231
	s_nop 0
	v_readlane_b32 s6, v230, 63
	s_nop 1
	v_fma_f32 v232, s6, v245, v238
	v_cmp_gt_f32_e32 vcc, s85, v232
	v_mul_f32_e32 v231, 0x4b800000, v232
	s_nop 0
	v_cndmask_b32_e32 v232, v232, v231, vcc
	v_rsq_f32_e32 v232, v232
	s_nop 0
	v_mul_f32_e32 v231, 0x45800000, v232
	v_cndmask_b32_e32 v232, v232, v231, vcc
	v_pk_mul_f32 v[222:223], v[116:117], v[232:233] op_sel_hi:[1,0]
	v_pk_mul_f32 v[224:225], v[118:119], v[232:233] op_sel_hi:[1,0]
	v_pk_mul_f32 v[226:227], v[120:121], v[232:233] op_sel_hi:[1,0]
	v_pk_mul_f32 v[228:229], v[122:123], v[232:233] op_sel_hi:[1,0]
	v_pk_mul_f32 v[222:223], v[198:199], v[222:223]
	v_pk_mul_f32 v[224:225], v[200:201], v[224:225]
	v_pk_mul_f32 v[226:227], v[202:203], v[226:227]
	v_pk_mul_f32 v[228:229], v[204:205], v[228:229]
	v_cvt_pk_bf16_f32 v234, v222, v223
	v_cvt_pk_bf16_f32 v235, v224, v225
	v_cvt_pk_bf16_f32 v236, v226, v227
	v_cvt_pk_bf16_f32 v237, v228, v229
	global_store_dwordx4 v[164:165], v[234:237], off offset:2048
	s_waitcnt vmcnt(15)
; __device__ __forceinline__ float silu_f(float v) { return v * __builtin_amdgcn_rcpf(1.0f + __expf(-v)); }
; #define WS_SHR(c) v += __builtin_bit_cast(float, __builtin_amdgcn_update_dpp(0, __builtin_bit_cast(int, v), c, 0xf, 0xf, true))
;     __device__ __forceinline__ const char* a(const pg8::Unit& u) const { return (const char*)ws + aoff + (size_t)u.pm * 256 * K_ * 2 + (u.kq < 0 ? 0 : u.kq * (K_ / 4) * 2); }
;     __device__ __forceinline__ const char* b(const pg8::Unit& u) const { return (const char*)ws + boff + (size_t)u.pn * 256 * K_ * 2 + (u.kq < 0 ? 0 : u.kq * (K_ / 4) * 2); }
;     __device__ __forceinline__ const char* a(const pg8::Unit& u) const { return (const char*)ws + WS_A + (size_t)u.pm * 256 * D * 2; }
;     __device__ __forceinline__ const char* b(const pg8::Unit& u) const { return (const char*)ws + boff + (size_t)u.pn * 256 * D * 2; }
; __device__ __forceinline__ float wave_sum(float v, int lane) {
;     (void)lane;
;     ...
;     WS_SHR(0x111); WS_SHR(0x112); WS_SHR(0x114); WS_SHR(0x118);
;     ...
;     v += __builtin_bit_cast(float, __builtin_amdgcn_update_dpp(0, __builtin_bit_cast(int, v), 0x142, 0xa, 0xf, false));
;     v += __builtin_bit_cast(float, __builtin_amdgcn_update_dpp(0, __builtin_bit_cast(int, v), 0x143, 0xc, 0xf, false));
;     return __builtin_bit_cast(float, __builtin_amdgcn_readlane(__builtin_bit_cast(int, v), 63));
; __device__ __forceinline__ void ssd_gate_norm_phase(Frame& F, int j, int nrows) {
;     ...
;         for (int g = 0; g < 8; ++g) { const size_t off = (size_t)r * DI + g * 512 + lane * 8;
;             float a[8], b[8], zz[8]; unpack8(__builtin_nontemporal_load((const u32x4*)(yf + off)), a); unpack8(__builtin_nontemporal_load((const u32x4*)(yb + off)), b); unpack8(__builtin_nontemporal_load((const u32x4*)(z + off)), zz);
;             float ss = 0.f;
; #pragma unroll
;             for (int c = 0; c < 8; ++c) { a[c] = (a[c] + b[c]) * silu_f(zz[c]); ss += a[c] * a[c]; }
;             const float rs = rsqrtf(wave_sum(ss, lane) * (1.0f / 512.0f) + EPS);
;             const f32x4* gp = (const f32x4*)(ng + g * 512 + lane * 8); const f32x4 g0 = gp[0], g1 = gp[1];
;             a[0] *= rs * g0.x; a[1] *= rs * g0.y; a[2] *= rs * g0.z; a[3] *= rs * g0.w; a[4] *= rs * g1.x; a[5] *= rs * g1.y; a[6] *= rs * g1.z; a[7] *= rs * g1.w;
;             *(u32x4*)(yf + off) = pack8(a); }
	v_lshlrev_b32_e32 v198, 16, v40
	v_and_b32_e32 v199, 0xffff0000, v40
	v_lshlrev_b32_e32 v206, 16, v44
	v_and_b32_e32 v207, 0xffff0000, v44
	v_lshlrev_b32_e32 v214, 16, v48
	v_and_b32_e32 v215, 0xffff0000, v48
	v_lshlrev_b32_e32 v200, 16, v41
	v_and_b32_e32 v201, 0xffff0000, v41
	v_lshlrev_b32_e32 v208, 16, v45
	v_and_b32_e32 v209, 0xffff0000, v45
	v_lshlrev_b32_e32 v216, 16, v49
	v_and_b32_e32 v217, 0xffff0000, v49
	v_lshlrev_b32_e32 v202, 16, v42
	v_and_b32_e32 v203, 0xffff0000, v42
	v_lshlrev_b32_e32 v210, 16, v46
	v_and_b32_e32 v211, 0xffff0000, v46
	v_lshlrev_b32_e32 v218, 16, v50
	v_and_b32_e32 v219, 0xffff0000, v50
	v_lshlrev_b32_e32 v204, 16, v43
	v_and_b32_e32 v205, 0xffff0000, v43
	v_lshlrev_b32_e32 v212, 16, v47
	v_and_b32_e32 v213, 0xffff0000, v47
	v_lshlrev_b32_e32 v220, 16, v51
	v_and_b32_e32 v221, 0xffff0000, v51
	v_pk_add_f32 v[198:199], v[198:199], v[206:207]
	v_pk_add_f32 v[200:201], v[200:201], v[208:209]
	v_pk_add_f32 v[202:203], v[202:203], v[210:211]
	v_pk_add_f32 v[204:205], v[204:205], v[212:213]
	v_mul_f32_e32 v206, 0xbfb8aa3b, v214
	v_mul_f32_e32 v207, 0xbfb8aa3b, v215
	v_mul_f32_e32 v208, 0xbfb8aa3b, v216
	v_mul_f32_e32 v209, 0xbfb8aa3b, v217
	v_mul_f32_e32 v210, 0xbfb8aa3b, v218
	v_mul_f32_e32 v211, 0xbfb8aa3b, v219
	v_mul_f32_e32 v212, 0xbfb8aa3b, v220
	v_mul_f32_e32 v213, 0xbfb8aa3b, v221
	v_exp_f32_e32 v206, v206
	v_exp_f32_e32 v207, v207
	v_exp_f32_e32 v208, v208
	v_exp_f32_e32 v209, v209
	v_exp_f32_e32 v210, v210
	v_exp_f32_e32 v211, v211
	v_exp_f32_e32 v212, v212
	v_exp_f32_e32 v213, v213
	v_add_f32_e32 v206, 1.0, v206
	v_add_f32_e32 v207, 1.0, v207
	v_add_f32_e32 v208, 1.0, v208
	v_add_f32_e32 v209, 1.0, v209
	v_add_f32_e32 v210, 1.0, v210
	v_add_f32_e32 v211, 1.0, v211
	v_add_f32_e32 v212, 1.0, v212
	v_add_f32_e32 v213, 1.0, v213
	v_rcp_f32_e32 v206, v206
	v_rcp_f32_e32 v207, v207
	v_rcp_f32_e32 v208, v208
	v_rcp_f32_e32 v209, v209
	v_rcp_f32_e32 v210, v210
	v_rcp_f32_e32 v211, v211
	v_rcp_f32_e32 v212, v212
	v_rcp_f32_e32 v213, v213
	s_nop 0
	v_pk_mul_f32 v[206:207], v[206:207], v[214:215]
	v_pk_mul_f32 v[208:209], v[208:209], v[216:217]
	v_pk_mul_f32 v[210:211], v[210:211], v[218:219]
	v_pk_mul_f32 v[212:213], v[212:213], v[220:221]
	v_pk_mul_f32 v[198:199], v[198:199], v[206:207]
	v_pk_mul_f32 v[200:201], v[200:201], v[208:209]
	v_pk_mul_f32 v[202:203], v[202:203], v[210:211]
	v_pk_mul_f32 v[204:205], v[204:205], v[212:213]
	v_pk_mul_f32 v[214:215], v[198:199], v[198:199]
	v_pk_mul_f32 v[216:217], v[200:201], v[200:201]
	v_pk_mul_f32 v[218:219], v[202:203], v[202:203]
	v_pk_mul_f32 v[220:221], v[204:205], v[204:205]
	v_add_f32_e32 v230, v214, v215
	v_add_f32_e32 v230, v216, v230
	v_add_f32_e32 v230, v217, v230
	v_add_f32_e32 v230, v218, v230
	v_add_f32_e32 v230, v219, v230
	v_add_f32_e32 v230, v220, v230
	v_add_f32_e32 v230, v221, v230
	v_mov_b32_e32 v231, v177
	s_nop 0
	v_add_f32_dpp v230, v230, v230 row_shr:1 row_mask:0xf bank_mask:0xf bound_ctrl:1
	s_nop 1
	v_add_f32_dpp v230, v230, v230 row_shr:2 row_mask:0xf bank_mask:0xf bound_ctrl:1
	s_nop 1
	v_add_f32_dpp v230, v230, v230 row_shr:4 row_mask:0xf bank_mask:0xf bound_ctrl:1
	s_nop 1
	v_add_f32_dpp v230, v230, v230 row_shr:8 row_mask:0xf bank_mask:0xf bound_ctrl:1
	s_nop 1
	v_mov_b32_dpp v231, v230 row_bcast:15 row_mask:0xa bank_mask:0xf
	v_add_f32_e32 v230, v230, v231
	v_mov_b32_e32 v231, v177
	s_nop 1
	v_mov_b32_dpp v231, v230 row_bcast:31 row_mask:0xc bank_mask:0xf
	v_add_f32_e32 v230, v230, v231
	s_nop 0
	v_readlane_b32 s6, v230, 63
	s_nop 1
	v_fma_f32 v232, s6, v245, v238
	v_cmp_gt_f32_e32 vcc, s85, v232
	v_mul_f32_e32 v231, 0x4b800000, v232
	s_nop 0
	v_cndmask_b32_e32 v232, v232, v231, vcc
	v_rsq_f32_e32 v232, v232
	s_nop 0
	v_mul_f32_e32 v231, 0x45800000, v232
	v_cndmask_b32_e32 v232, v232, v231, vcc
	v_pk_mul_f32 v[222:223], v[124:125], v[232:233] op_sel_hi:[1,0]
	v_pk_mul_f32 v[224:225], v[126:127], v[232:233] op_sel_hi:[1,0]
	v_pk_mul_f32 v[226:227], v[128:129], v[232:233] op_sel_hi:[1,0]
	v_pk_mul_f32 v[228:229], v[130:131], v[232:233] op_sel_hi:[1,0]
	v_pk_mul_f32 v[222:223], v[198:199], v[222:223]
	v_pk_mul_f32 v[224:225], v[200:201], v[224:225]
	v_pk_mul_f32 v[226:227], v[202:203], v[226:227]
	v_pk_mul_f32 v[228:229], v[204:205], v[228:229]
	v_cvt_pk_bf16_f32 v234, v222, v223
	v_cvt_pk_bf16_f32 v235, v224, v225
	v_cvt_pk_bf16_f32 v236, v226, v227
	v_cvt_pk_bf16_f32 v237, v228, v229
	global_store_dwordx4 v[164:165], v[234:237], off offset:3072
	s_waitcnt vmcnt(13)
; __device__ __forceinline__ float silu_f(float v) { return v * __builtin_amdgcn_rcpf(1.0f + __expf(-v)); }
; #define WS_SHR(c) v += __builtin_bit_cast(float, __builtin_amdgcn_update_dpp(0, __builtin_bit_cast(int, v), c, 0xf, 0xf, true))
;     __device__ __forceinline__ const char* a(const pg8::Unit& u) const { return (const char*)ws + aoff + (size_t)u.pm * 256 * K_ * 2 + (u.kq < 0 ? 0 : u.kq * (K_ / 4) * 2); }
;     __device__ __forceinline__ const char* b(const pg8::Unit& u) const { return (const char*)ws + boff + (size_t)u.pn * 256 * K_ * 2 + (u.kq < 0 ? 0 : u.kq * (K_ / 4) * 2); }
;     __device__ __forceinline__ const char* a(const pg8::Unit& u) const { return (const char*)ws + WS_A + (size_t)u.pm * 256 * D * 2; }
;     __device__ __forceinline__ const char* b(const pg8::Unit& u) const { return (const char*)ws + boff + (size_t)u.pn * 256 * D * 2; }
; __device__ __forceinline__ float wave_sum(float v, int lane) {
;     (void)lane;
;     ...
;     WS_SHR(0x111); WS_SHR(0x112); WS_SHR(0x114); WS_SHR(0x118);
;     ...
;     v += __builtin_bit_cast(float, __builtin_amdgcn_update_dpp(0, __builtin_bit_cast(int, v), 0x142, 0xa, 0xf, false));
;     v += __builtin_bit_cast(float, __builtin_amdgcn_update_dpp(0, __builtin_bit_cast(int, v), 0x143, 0xc, 0xf, false));
;     return __builtin_bit_cast(float, __builtin_amdgcn_readlane(__builtin_bit_cast(int, v), 63));
; __device__ __forceinline__ void ssd_gate_norm_phase(Frame& F, int j, int nrows) {
;     ...
;         for (int g = 0; g < 8; ++g) { const size_t off = (size_t)r * DI + g * 512 + lane * 8;
;             float a[8], b[8], zz[8]; unpack8(__builtin_nontemporal_load((const u32x4*)(yf + off)), a); unpack8(__builtin_nontemporal_load((const u32x4*)(yb + off)), b); unpack8(__builtin_nontemporal_load((const u32x4*)(z + off)), zz);
;             float ss = 0.f;
; #pragma unroll
;             for (int c = 0; c < 8; ++c) { a[c] = (a[c] + b[c]) * silu_f(zz[c]); ss += a[c] * a[c]; }
;             const float rs = rsqrtf(wave_sum(ss, lane) * (1.0f / 512.0f) + EPS);
;             const f32x4* gp = (const f32x4*)(ng + g * 512 + lane * 8); const f32x4 g0 = gp[0], g1 = gp[1];
;             a[0] *= rs * g0.x; a[1] *= rs * g0.y; a[2] *= rs * g0.z; a[3] *= rs * g0.w; a[4] *= rs * g1.x; a[5] *= rs * g1.y; a[6] *= rs * g1.z; a[7] *= rs * g1.w;
;             *(u32x4*)(yf + off) = pack8(a); }
	v_lshlrev_b32_e32 v198, 16, v52
	v_and_b32_e32 v199, 0xffff0000, v52
	v_lshlrev_b32_e32 v206, 16, v56
	v_and_b32_e32 v207, 0xffff0000, v56
	v_lshlrev_b32_e32 v214, 16, v60
	v_and_b32_e32 v215, 0xffff0000, v60
	v_lshlrev_b32_e32 v200, 16, v53
	v_and_b32_e32 v201, 0xffff0000, v53
	v_lshlrev_b32_e32 v208, 16, v57
	v_and_b32_e32 v209, 0xffff0000, v57
	v_lshlrev_b32_e32 v216, 16, v61
	v_and_b32_e32 v217, 0xffff0000, v61
	v_lshlrev_b32_e32 v202, 16, v54
	v_and_b32_e32 v203, 0xffff0000, v54
	v_lshlrev_b32_e32 v210, 16, v58
	v_and_b32_e32 v211, 0xffff0000, v58
	v_lshlrev_b32_e32 v218, 16, v62
	v_and_b32_e32 v219, 0xffff0000, v62
	v_lshlrev_b32_e32 v204, 16, v55
	v_and_b32_e32 v205, 0xffff0000, v55
	v_lshlrev_b32_e32 v212, 16, v59
	v_and_b32_e32 v213, 0xffff0000, v59
	v_lshlrev_b32_e32 v220, 16, v63
	v_and_b32_e32 v221, 0xffff0000, v63
	v_pk_add_f32 v[198:199], v[198:199], v[206:207]
	v_pk_add_f32 v[200:201], v[200:201], v[208:209]
	v_pk_add_f32 v[202:203], v[202:203], v[210:211]
	v_pk_add_f32 v[204:205], v[204:205], v[212:213]
	v_mul_f32_e32 v206, 0xbfb8aa3b, v214
	v_mul_f32_e32 v207, 0xbfb8aa3b, v215
	v_mul_f32_e32 v208, 0xbfb8aa3b, v216
	v_mul_f32_e32 v209, 0xbfb8aa3b, v217
	v_mul_f32_e32 v210, 0xbfb8aa3b, v218
	v_mul_f32_e32 v211, 0xbfb8aa3b, v219
	v_mul_f32_e32 v212, 0xbfb8aa3b, v220
	v_mul_f32_e32 v213, 0xbfb8aa3b, v221
	v_exp_f32_e32 v206, v206
	v_exp_f32_e32 v207, v207
	v_exp_f32_e32 v208, v208
	v_exp_f32_e32 v209, v209
	v_exp_f32_e32 v210, v210
	v_exp_f32_e32 v211, v211
	v_exp_f32_e32 v212, v212
	v_exp_f32_e32 v213, v213
	v_add_f32_e32 v206, 1.0, v206
	v_add_f32_e32 v207, 1.0, v207
	v_add_f32_e32 v208, 1.0, v208
	v_add_f32_e32 v209, 1.0, v209
	v_add_f32_e32 v210, 1.0, v210
	v_add_f32_e32 v211, 1.0, v211
	v_add_f32_e32 v212, 1.0, v212
	v_add_f32_e32 v213, 1.0, v213
	v_rcp_f32_e32 v206, v206
	v_rcp_f32_e32 v207, v207
	v_rcp_f32_e32 v208, v208
	v_rcp_f32_e32 v209, v209
	v_rcp_f32_e32 v210, v210
	v_rcp_f32_e32 v211, v211
	v_rcp_f32_e32 v212, v212
	v_rcp_f32_e32 v213, v213
	s_nop 0
	v_pk_mul_f32 v[206:207], v[206:207], v[214:215]
	v_pk_mul_f32 v[208:209], v[208:209], v[216:217]
	v_pk_mul_f32 v[210:211], v[210:211], v[218:219]
	v_pk_mul_f32 v[212:213], v[212:213], v[220:221]
	v_pk_mul_f32 v[198:199], v[198:199], v[206:207]
	v_pk_mul_f32 v[200:201], v[200:201], v[208:209]
	v_pk_mul_f32 v[202:203], v[202:203], v[210:211]
	v_pk_mul_f32 v[204:205], v[204:205], v[212:213]
	v_pk_mul_f32 v[214:215], v[198:199], v[198:199]
	v_pk_mul_f32 v[216:217], v[200:201], v[200:201]
	v_pk_mul_f32 v[218:219], v[202:203], v[202:203]
	v_pk_mul_f32 v[220:221], v[204:205], v[204:205]
	v_add_f32_e32 v230, v214, v215
	v_add_f32_e32 v230, v216, v230
	v_add_f32_e32 v230, v217, v230
	v_add_f32_e32 v230, v218, v230
	v_add_f32_e32 v230, v219, v230
	v_add_f32_e32 v230, v220, v230
	v_add_f32_e32 v230, v221, v230
	v_mov_b32_e32 v231, v177
	s_nop 0
	v_add_f32_dpp v230, v230, v230 row_shr:1 row_mask:0xf bank_mask:0xf bound_ctrl:1
	s_nop 1
	v_add_f32_dpp v230, v230, v230 row_shr:2 row_mask:0xf bank_mask:0xf bound_ctrl:1
	s_nop 1
	v_add_f32_dpp v230, v230, v230 row_shr:4 row_mask:0xf bank_mask:0xf bound_ctrl:1
	s_nop 1
	v_add_f32_dpp v230, v230, v230 row_shr:8 row_mask:0xf bank_mask:0xf bound_ctrl:1
	s_nop 1
	v_mov_b32_dpp v231, v230 row_bcast:15 row_mask:0xa bank_mask:0xf
	v_add_f32_e32 v230, v230, v231
	v_mov_b32_e32 v231, v177
	s_nop 1
	v_mov_b32_dpp v231, v230 row_bcast:31 row_mask:0xc bank_mask:0xf
	v_add_f32_e32 v230, v230, v231
	s_nop 0
	v_readlane_b32 s6, v230, 63
	s_nop 1
	v_fma_f32 v232, s6, v245, v238
	v_cmp_gt_f32_e32 vcc, s85, v232
	v_mul_f32_e32 v231, 0x4b800000, v232
	s_nop 0
	v_cndmask_b32_e32 v232, v232, v231, vcc
	v_rsq_f32_e32 v232, v232
	s_nop 0
	v_mul_f32_e32 v231, 0x45800000, v232
	v_cndmask_b32_e32 v232, v232, v231, vcc
	v_pk_mul_f32 v[222:223], v[132:133], v[232:233] op_sel_hi:[1,0]
	v_pk_mul_f32 v[224:225], v[134:135], v[232:233] op_sel_hi:[1,0]
	v_pk_mul_f32 v[226:227], v[136:137], v[232:233] op_sel_hi:[1,0]
	v_pk_mul_f32 v[228:229], v[138:139], v[232:233] op_sel_hi:[1,0]
	v_pk_mul_f32 v[222:223], v[198:199], v[222:223]
	v_pk_mul_f32 v[224:225], v[200:201], v[224:225]
	v_pk_mul_f32 v[226:227], v[202:203], v[226:227]
	v_pk_mul_f32 v[228:229], v[204:205], v[228:229]
	v_cvt_pk_bf16_f32 v234, v222, v223
	v_cvt_pk_bf16_f32 v235, v224, v225
	v_cvt_pk_bf16_f32 v236, v226, v227
	v_cvt_pk_bf16_f32 v237, v228, v229
	global_store_dwordx4 v[166:167], v[234:237], off
	s_waitcnt vmcnt(11)
; __device__ __forceinline__ float silu_f(float v) { return v * __builtin_amdgcn_rcpf(1.0f + __expf(-v)); }
; #define WS_SHR(c) v += __builtin_bit_cast(float, __builtin_amdgcn_update_dpp(0, __builtin_bit_cast(int, v), c, 0xf, 0xf, true))
;     __device__ __forceinline__ const char* a(const pg8::Unit& u) const { return (const char*)ws + aoff + (size_t)u.pm * 256 * K_ * 2 + (u.kq < 0 ? 0 : u.kq * (K_ / 4) * 2); }
;     __device__ __forceinline__ const char* b(const pg8::Unit& u) const { return (const char*)ws + boff + (size_t)u.pn * 256 * K_ * 2 + (u.kq < 0 ? 0 : u.kq * (K_ / 4) * 2); }
;     __device__ __forceinline__ const char* a(const pg8::Unit& u) const { return (const char*)ws + WS_A + (size_t)u.pm * 256 * D * 2; }
;     __device__ __forceinline__ const char* b(const pg8::Unit& u) const { return (const char*)ws + boff + (size_t)u.pn * 256 * D * 2; }
; __device__ __forceinline__ float wave_sum(float v, int lane) {
;     (void)lane;
;     ...
;     WS_SHR(0x111); WS_SHR(0x112); WS_SHR(0x114); WS_SHR(0x118);
;     ...
;     v += __builtin_bit_cast(float, __builtin_amdgcn_update_dpp(0, __builtin_bit_cast(int, v), 0x142, 0xa, 0xf, false));
;     v += __builtin_bit_cast(float, __builtin_amdgcn_update_dpp(0, __builtin_bit_cast(int, v), 0x143, 0xc, 0xf, false));
;     return __builtin_bit_cast(float, __builtin_amdgcn_readlane(__builtin_bit_cast(int, v), 63));
; __device__ __forceinline__ void ssd_gate_norm_phase(Frame& F, int j, int nrows) {
;     ...
;         for (int g = 0; g < 8; ++g) { const size_t off = (size_t)r * DI + g * 512 + lane * 8;
;             float a[8], b[8], zz[8]; unpack8(__builtin_nontemporal_load((const u32x4*)(yf + off)), a); unpack8(__builtin_nontemporal_load((const u32x4*)(yb + off)), b); unpack8(__builtin_nontemporal_load((const u32x4*)(z + off)), zz);
;             float ss = 0.f;
; #pragma unroll
;             for (int c = 0; c < 8; ++c) { a[c] = (a[c] + b[c]) * silu_f(zz[c]); ss += a[c] * a[c]; }
;             const float rs = rsqrtf(wave_sum(ss, lane) * (1.0f / 512.0f) + EPS);
;             const f32x4* gp = (const f32x4*)(ng + g * 512 + lane * 8); const f32x4 g0 = gp[0], g1 = gp[1];
;             a[0] *= rs * g0.x; a[1] *= rs * g0.y; a[2] *= rs * g0.z; a[3] *= rs * g0.w; a[4] *= rs * g1.x; a[5] *= rs * g1.y; a[6] *= rs * g1.z; a[7] *= rs * g1.w;
;             *(u32x4*)(yf + off) = pack8(a); }
	v_lshlrev_b32_e32 v198, 16, v64
	v_and_b32_e32 v199, 0xffff0000, v64
	v_lshlrev_b32_e32 v206, 16, v68
	v_and_b32_e32 v207, 0xffff0000, v68
	v_lshlrev_b32_e32 v214, 16, v72
	v_and_b32_e32 v215, 0xffff0000, v72
	v_lshlrev_b32_e32 v200, 16, v65
	v_and_b32_e32 v201, 0xffff0000, v65
	v_lshlrev_b32_e32 v208, 16, v69
	v_and_b32_e32 v209, 0xffff0000, v69
	v_lshlrev_b32_e32 v216, 16, v73
	v_and_b32_e32 v217, 0xffff0000, v73
	v_lshlrev_b32_e32 v202, 16, v66
	v_and_b32_e32 v203, 0xffff0000, v66
	v_lshlrev_b32_e32 v210, 16, v70
	v_and_b32_e32 v211, 0xffff0000, v70
	v_lshlrev_b32_e32 v218, 16, v74
	v_and_b32_e32 v219, 0xffff0000, v74
	v_lshlrev_b32_e32 v204, 16, v67
	v_and_b32_e32 v205, 0xffff0000, v67
	v_lshlrev_b32_e32 v212, 16, v71
	v_and_b32_e32 v213, 0xffff0000, v71
	v_lshlrev_b32_e32 v220, 16, v75
	v_and_b32_e32 v221, 0xffff0000, v75
	v_pk_add_f32 v[198:199], v[198:199], v[206:207]
	v_pk_add_f32 v[200:201], v[200:201], v[208:209]
	v_pk_add_f32 v[202:203], v[202:203], v[210:211]
	v_pk_add_f32 v[204:205], v[204:205], v[212:213]
	v_mul_f32_e32 v206, 0xbfb8aa3b, v214
	v_mul_f32_e32 v207, 0xbfb8aa3b, v215
	v_mul_f32_e32 v208, 0xbfb8aa3b, v216
	v_mul_f32_e32 v209, 0xbfb8aa3b, v217
	v_mul_f32_e32 v210, 0xbfb8aa3b, v218
	v_mul_f32_e32 v211, 0xbfb8aa3b, v219
	v_mul_f32_e32 v212, 0xbfb8aa3b, v220
	v_mul_f32_e32 v213, 0xbfb8aa3b, v221
	v_exp_f32_e32 v206, v206
	v_exp_f32_e32 v207, v207
	v_exp_f32_e32 v208, v208
	v_exp_f32_e32 v209, v209
	v_exp_f32_e32 v210, v210
	v_exp_f32_e32 v211, v211
	v_exp_f32_e32 v212, v212
	v_exp_f32_e32 v213, v213
	v_add_f32_e32 v206, 1.0, v206
	v_add_f32_e32 v207, 1.0, v207
	v_add_f32_e32 v208, 1.0, v208
	v_add_f32_e32 v209, 1.0, v209
	v_add_f32_e32 v210, 1.0, v210
	v_add_f32_e32 v211, 1.0, v211
	v_add_f32_e32 v212, 1.0, v212
	v_add_f32_e32 v213, 1.0, v213
	v_rcp_f32_e32 v206, v206
	v_rcp_f32_e32 v207, v207
	v_rcp_f32_e32 v208, v208
	v_rcp_f32_e32 v209, v209
	v_rcp_f32_e32 v210, v210
	v_rcp_f32_e32 v211, v211
	v_rcp_f32_e32 v212, v212
	v_rcp_f32_e32 v213, v213
	s_nop 0
	v_pk_mul_f32 v[206:207], v[206:207], v[214:215]
	v_pk_mul_f32 v[208:209], v[208:209], v[216:217]
	v_pk_mul_f32 v[210:211], v[210:211], v[218:219]
	v_pk_mul_f32 v[212:213], v[212:213], v[220:221]
	v_pk_mul_f32 v[198:199], v[198:199], v[206:207]
	v_pk_mul_f32 v[200:201], v[200:201], v[208:209]
	v_pk_mul_f32 v[202:203], v[202:203], v[210:211]
	v_pk_mul_f32 v[204:205], v[204:205], v[212:213]
	v_pk_mul_f32 v[214:215], v[198:199], v[198:199]
	v_pk_mul_f32 v[216:217], v[200:201], v[200:201]
	v_pk_mul_f32 v[218:219], v[202:203], v[202:203]
	v_pk_mul_f32 v[220:221], v[204:205], v[204:205]
	v_add_f32_e32 v230, v214, v215
	v_add_f32_e32 v230, v216, v230
	v_add_f32_e32 v230, v217, v230
	v_add_f32_e32 v230, v218, v230
	v_add_f32_e32 v230, v219, v230
	v_add_f32_e32 v230, v220, v230
	v_add_f32_e32 v230, v221, v230
	v_mov_b32_e32 v231, v177
	s_nop 0
	v_add_f32_dpp v230, v230, v230 row_shr:1 row_mask:0xf bank_mask:0xf bound_ctrl:1
	s_nop 1
	v_add_f32_dpp v230, v230, v230 row_shr:2 row_mask:0xf bank_mask:0xf bound_ctrl:1
	s_nop 1
	v_add_f32_dpp v230, v230, v230 row_shr:4 row_mask:0xf bank_mask:0xf bound_ctrl:1
	s_nop 1
	v_add_f32_dpp v230, v230, v230 row_shr:8 row_mask:0xf bank_mask:0xf bound_ctrl:1
	s_nop 1
	v_mov_b32_dpp v231, v230 row_bcast:15 row_mask:0xa bank_mask:0xf
	v_add_f32_e32 v230, v230, v231
	v_mov_b32_e32 v231, v177
	s_nop 1
	v_mov_b32_dpp v231, v230 row_bcast:31 row_mask:0xc bank_mask:0xf
	v_add_f32_e32 v230, v230, v231
	s_nop 0
	v_readlane_b32 s6, v230, 63
	s_nop 1
	v_fma_f32 v232, s6, v245, v238
	v_cmp_gt_f32_e32 vcc, s85, v232
	v_mul_f32_e32 v231, 0x4b800000, v232
	s_nop 0
	v_cndmask_b32_e32 v232, v232, v231, vcc
	v_rsq_f32_e32 v232, v232
	s_nop 0
	v_mul_f32_e32 v231, 0x45800000, v232
	v_cndmask_b32_e32 v232, v232, v231, vcc
	v_pk_mul_f32 v[222:223], v[140:141], v[232:233] op_sel_hi:[1,0]
	v_pk_mul_f32 v[224:225], v[142:143], v[232:233] op_sel_hi:[1,0]
	v_pk_mul_f32 v[226:227], v[144:145], v[232:233] op_sel_hi:[1,0]
	v_pk_mul_f32 v[228:229], v[146:147], v[232:233] op_sel_hi:[1,0]
	v_pk_mul_f32 v[222:223], v[198:199], v[222:223]
	v_pk_mul_f32 v[224:225], v[200:201], v[224:225]
	v_pk_mul_f32 v[226:227], v[202:203], v[226:227]
	v_pk_mul_f32 v[228:229], v[204:205], v[228:229]
	v_cvt_pk_bf16_f32 v234, v222, v223
	v_cvt_pk_bf16_f32 v235, v224, v225
	v_cvt_pk_bf16_f32 v236, v226, v227
	v_cvt_pk_bf16_f32 v237, v228, v229
	global_store_dwordx4 v[166:167], v[234:237], off offset:1024
	s_waitcnt vmcnt(9)
; __device__ __forceinline__ float silu_f(float v) { return v * __builtin_amdgcn_rcpf(1.0f + __expf(-v)); }
; #define WS_SHR(c) v += __builtin_bit_cast(float, __builtin_amdgcn_update_dpp(0, __builtin_bit_cast(int, v), c, 0xf, 0xf, true))
;     __device__ __forceinline__ const char* a(const pg8::Unit& u) const { return (const char*)ws + aoff + (size_t)u.pm * 256 * K_ * 2 + (u.kq < 0 ? 0 : u.kq * (K_ / 4) * 2); }
;     __device__ __forceinline__ const char* b(const pg8::Unit& u) const { return (const char*)ws + boff + (size_t)u.pn * 256 * K_ * 2 + (u.kq < 0 ? 0 : u.kq * (K_ / 4) * 2); }
;     __device__ __forceinline__ const char* a(const pg8::Unit& u) const { return (const char*)ws + WS_A + (size_t)u.pm * 256 * D * 2; }
;     __device__ __forceinline__ const char* b(const pg8::Unit& u) const { return (const char*)ws + boff + (size_t)u.pn * 256 * D * 2; }
; __device__ __forceinline__ float wave_sum(float v, int lane) {
;     (void)lane;
;     ...
;     WS_SHR(0x111); WS_SHR(0x112); WS_SHR(0x114); WS_SHR(0x118);
;     ...
;     v += __builtin_bit_cast(float, __builtin_amdgcn_update_dpp(0, __builtin_bit_cast(int, v), 0x142, 0xa, 0xf, false));
;     v += __builtin_bit_cast(float, __builtin_amdgcn_update_dpp(0, __builtin_bit_cast(int, v), 0x143, 0xc, 0xf, false));
;     return __builtin_bit_cast(float, __builtin_amdgcn_readlane(__builtin_bit_cast(int, v), 63));
; __device__ __forceinline__ void ssd_gate_norm_phase(Frame& F, int j, int nrows) {
;     ...
;         for (int g = 0; g < 8; ++g) { const size_t off = (size_t)r * DI + g * 512 + lane * 8;
;             float a[8], b[8], zz[8]; unpack8(__builtin_nontemporal_load((const u32x4*)(yf + off)), a); unpack8(__builtin_nontemporal_load((const u32x4*)(yb + off)), b); unpack8(__builtin_nontemporal_load((const u32x4*)(z + off)), zz);
;             float ss = 0.f;
; #pragma unroll
;             for (int c = 0; c < 8; ++c) { a[c] = (a[c] + b[c]) * silu_f(zz[c]); ss += a[c] * a[c]; }
;             const float rs = rsqrtf(wave_sum(ss, lane) * (1.0f / 512.0f) + EPS);
;             const f32x4* gp = (const f32x4*)(ng + g * 512 + lane * 8); const f32x4 g0 = gp[0], g1 = gp[1];
;             a[0] *= rs * g0.x; a[1] *= rs * g0.y; a[2] *= rs * g0.z; a[3] *= rs * g0.w; a[4] *= rs * g1.x; a[5] *= rs * g1.y; a[6] *= rs * g1.z; a[7] *= rs * g1.w;
;             *(u32x4*)(yf + off) = pack8(a); }
	v_lshlrev_b32_e32 v198, 16, v76
	v_and_b32_e32 v199, 0xffff0000, v76
	v_lshlrev_b32_e32 v206, 16, v80
	v_and_b32_e32 v207, 0xffff0000, v80
	v_lshlrev_b32_e32 v214, 16, v84
	v_and_b32_e32 v215, 0xffff0000, v84
	v_lshlrev_b32_e32 v200, 16, v77
	v_and_b32_e32 v201, 0xffff0000, v77
	v_lshlrev_b32_e32 v208, 16, v81
	v_and_b32_e32 v209, 0xffff0000, v81
	v_lshlrev_b32_e32 v216, 16, v85
	v_and_b32_e32 v217, 0xffff0000, v85
	v_lshlrev_b32_e32 v202, 16, v78
	v_and_b32_e32 v203, 0xffff0000, v78
	v_lshlrev_b32_e32 v210, 16, v82
	v_and_b32_e32 v211, 0xffff0000, v82
	v_lshlrev_b32_e32 v218, 16, v86
	v_and_b32_e32 v219, 0xffff0000, v86
	v_lshlrev_b32_e32 v204, 16, v79
	v_and_b32_e32 v205, 0xffff0000, v79
	v_lshlrev_b32_e32 v212, 16, v83
	v_and_b32_e32 v213, 0xffff0000, v83
	v_lshlrev_b32_e32 v220, 16, v87
	v_and_b32_e32 v221, 0xffff0000, v87
	v_pk_add_f32 v[198:199], v[198:199], v[206:207]
	v_pk_add_f32 v[200:201], v[200:201], v[208:209]
	v_pk_add_f32 v[202:203], v[202:203], v[210:211]
	v_pk_add_f32 v[204:205], v[204:205], v[212:213]
	v_mul_f32_e32 v206, 0xbfb8aa3b, v214
	v_mul_f32_e32 v207, 0xbfb8aa3b, v215
	v_mul_f32_e32 v208, 0xbfb8aa3b, v216
	v_mul_f32_e32 v209, 0xbfb8aa3b, v217
	v_mul_f32_e32 v210, 0xbfb8aa3b, v218
	v_mul_f32_e32 v211, 0xbfb8aa3b, v219
	v_mul_f32_e32 v212, 0xbfb8aa3b, v220
	v_mul_f32_e32 v213, 0xbfb8aa3b, v221
	v_exp_f32_e32 v206, v206
	v_exp_f32_e32 v207, v207
	v_exp_f32_e32 v208, v208
	v_exp_f32_e32 v209, v209
	v_exp_f32_e32 v210, v210
	v_exp_f32_e32 v211, v211
	v_exp_f32_e32 v212, v212
	v_exp_f32_e32 v213, v213
	v_add_f32_e32 v206, 1.0, v206
	v_add_f32_e32 v207, 1.0, v207
	v_add_f32_e32 v208, 1.0, v208
	v_add_f32_e32 v209, 1.0, v209
	v_add_f32_e32 v210, 1.0, v210
	v_add_f32_e32 v211, 1.0, v211
	v_add_f32_e32 v212, 1.0, v212
	v_add_f32_e32 v213, 1.0, v213
	v_rcp_f32_e32 v206, v206
	v_rcp_f32_e32 v207, v207
	v_rcp_f32_e32 v208, v208
	v_rcp_f32_e32 v209, v209
	v_rcp_f32_e32 v210, v210
	v_rcp_f32_e32 v211, v211
	v_rcp_f32_e32 v212, v212
	v_rcp_f32_e32 v213, v213
	s_nop 0
	v_pk_mul_f32 v[206:207], v[206:207], v[214:215]
	v_pk_mul_f32 v[208:209], v[208:209], v[216:217]
	v_pk_mul_f32 v[210:211], v[210:211], v[218:219]
	v_pk_mul_f32 v[212:213], v[212:213], v[220:221]
	v_pk_mul_f32 v[198:199], v[198:199], v[206:207]
	v_pk_mul_f32 v[200:201], v[200:201], v[208:209]
	v_pk_mul_f32 v[202:203], v[202:203], v[210:211]
	v_pk_mul_f32 v[204:205], v[204:205], v[212:213]
	v_pk_mul_f32 v[214:215], v[198:199], v[198:199]
	v_pk_mul_f32 v[216:217], v[200:201], v[200:201]
	v_pk_mul_f32 v[218:219], v[202:203], v[202:203]
	v_pk_mul_f32 v[220:221], v[204:205], v[204:205]
	v_add_f32_e32 v230, v214, v215
	v_add_f32_e32 v230, v216, v230
	v_add_f32_e32 v230, v217, v230
	v_add_f32_e32 v230, v218, v230
	v_add_f32_e32 v230, v219, v230
	v_add_f32_e32 v230, v220, v230
	v_add_f32_e32 v230, v221, v230
	v_mov_b32_e32 v231, v177
	s_nop 0
	v_add_f32_dpp v230, v230, v230 row_shr:1 row_mask:0xf bank_mask:0xf bound_ctrl:1
	s_nop 1
	v_add_f32_dpp v230, v230, v230 row_shr:2 row_mask:0xf bank_mask:0xf bound_ctrl:1
	s_nop 1
	v_add_f32_dpp v230, v230, v230 row_shr:4 row_mask:0xf bank_mask:0xf bound_ctrl:1
	s_nop 1
	v_add_f32_dpp v230, v230, v230 row_shr:8 row_mask:0xf bank_mask:0xf bound_ctrl:1
	s_nop 1
	v_mov_b32_dpp v231, v230 row_bcast:15 row_mask:0xa bank_mask:0xf
	v_add_f32_e32 v230, v230, v231
	v_mov_b32_e32 v231, v177
	s_nop 1
	v_mov_b32_dpp v231, v230 row_bcast:31 row_mask:0xc bank_mask:0xf
	v_add_f32_e32 v230, v230, v231
	s_nop 0
	v_readlane_b32 s6, v230, 63
	s_nop 1
	v_fma_f32 v232, s6, v245, v238
	v_cmp_gt_f32_e32 vcc, s85, v232
	v_mul_f32_e32 v231, 0x4b800000, v232
	s_nop 0
	v_cndmask_b32_e32 v232, v232, v231, vcc
	v_rsq_f32_e32 v232, v232
	s_nop 0
	v_mul_f32_e32 v231, 0x45800000, v232
	v_cndmask_b32_e32 v232, v232, v231, vcc
	v_pk_mul_f32 v[222:223], v[148:149], v[232:233] op_sel_hi:[1,0]
	v_pk_mul_f32 v[224:225], v[150:151], v[232:233] op_sel_hi:[1,0]
	v_pk_mul_f32 v[226:227], v[152:153], v[232:233] op_sel_hi:[1,0]
	v_pk_mul_f32 v[228:229], v[154:155], v[232:233] op_sel_hi:[1,0]
	v_pk_mul_f32 v[222:223], v[198:199], v[222:223]
	v_pk_mul_f32 v[224:225], v[200:201], v[224:225]
	v_pk_mul_f32 v[226:227], v[202:203], v[226:227]
	v_pk_mul_f32 v[228:229], v[204:205], v[228:229]
	v_cvt_pk_bf16_f32 v234, v222, v223
	v_cvt_pk_bf16_f32 v235, v224, v225
	v_cvt_pk_bf16_f32 v236, v226, v227
	v_cvt_pk_bf16_f32 v237, v228, v229
	global_store_dwordx4 v[166:167], v[234:237], off offset:2048
	s_waitcnt vmcnt(7)
; __device__ __forceinline__ float silu_f(float v) { return v * __builtin_amdgcn_rcpf(1.0f + __expf(-v)); }
; #define WS_SHR(c) v += __builtin_bit_cast(float, __builtin_amdgcn_update_dpp(0, __builtin_bit_cast(int, v), c, 0xf, 0xf, true))
;     __device__ __forceinline__ const char* a(const pg8::Unit& u) const { return (const char*)ws + aoff + (size_t)u.pm * 256 * K_ * 2 + (u.kq < 0 ? 0 : u.kq * (K_ / 4) * 2); }
;     __device__ __forceinline__ const char* b(const pg8::Unit& u) const { return (const char*)ws + boff + (size_t)u.pn * 256 * K_ * 2 + (u.kq < 0 ? 0 : u.kq * (K_ / 4) * 2); }
;     __device__ __forceinline__ const char* a(const pg8::Unit& u) const { return (const char*)ws + WS_A + (size_t)u.pm * 256 * D * 2; }
;     __device__ __forceinline__ const char* b(const pg8::Unit& u) const { return (const char*)ws + boff + (size_t)u.pn * 256 * D * 2; }
; __device__ __forceinline__ float wave_sum(float v, int lane) {
;     (void)lane;
;     ...
;     WS_SHR(0x111); WS_SHR(0x112); WS_SHR(0x114); WS_SHR(0x118);
;     ...
;     v += __builtin_bit_cast(float, __builtin_amdgcn_update_dpp(0, __builtin_bit_cast(int, v), 0x142, 0xa, 0xf, false));
;     v += __builtin_bit_cast(float, __builtin_amdgcn_update_dpp(0, __builtin_bit_cast(int, v), 0x143, 0xc, 0xf, false));
;     return __builtin_bit_cast(float, __builtin_amdgcn_readlane(__builtin_bit_cast(int, v), 63));
; __device__ __forceinline__ void ssd_gate_norm_phase(Frame& F, int j, int nrows) {
;     ...
;         for (int g = 0; g < 8; ++g) { const size_t off = (size_t)r * DI + g * 512 + lane * 8;
;             float a[8], b[8], zz[8]; unpack8(__builtin_nontemporal_load((const u32x4*)(yf + off)), a); unpack8(__builtin_nontemporal_load((const u32x4*)(yb + off)), b); unpack8(__builtin_nontemporal_load((const u32x4*)(z + off)), zz);
;             float ss = 0.f;
; #pragma unroll
;             for (int c = 0; c < 8; ++c) { a[c] = (a[c] + b[c]) * silu_f(zz[c]); ss += a[c] * a[c]; }
;             const float rs = rsqrtf(wave_sum(ss, lane) * (1.0f / 512.0f) + EPS);
;             const f32x4* gp = (const f32x4*)(ng + g * 512 + lane * 8); const f32x4 g0 = gp[0], g1 = gp[1];
;             a[0] *= rs * g0.x; a[1] *= rs * g0.y; a[2] *= rs * g0.z; a[3] *= rs * g0.w; a[4] *= rs * g1.x; a[5] *= rs * g1.y; a[6] *= rs * g1.z; a[7] *= rs * g1.w;
;             *(u32x4*)(yf + off) = pack8(a); }
	v_lshlrev_b32_e32 v198, 16, v88
	v_and_b32_e32 v199, 0xffff0000, v88
	v_lshlrev_b32_e32 v206, 16, v92
	v_and_b32_e32 v207, 0xffff0000, v92
	v_lshlrev_b32_e32 v214, 16, v96
	v_and_b32_e32 v215, 0xffff0000, v96
	v_lshlrev_b32_e32 v200, 16, v89
	v_and_b32_e32 v201, 0xffff0000, v89
	v_lshlrev_b32_e32 v208, 16, v93
	v_and_b32_e32 v209, 0xffff0000, v93
	v_lshlrev_b32_e32 v216, 16, v97
	v_and_b32_e32 v217, 0xffff0000, v97
	v_lshlrev_b32_e32 v202, 16, v90
	v_and_b32_e32 v203, 0xffff0000, v90
	v_lshlrev_b32_e32 v210, 16, v94
	v_and_b32_e32 v211, 0xffff0000, v94
	v_lshlrev_b32_e32 v218, 16, v98
	v_and_b32_e32 v219, 0xffff0000, v98
	v_lshlrev_b32_e32 v204, 16, v91
	v_and_b32_e32 v205, 0xffff0000, v91
	v_lshlrev_b32_e32 v212, 16, v95
	v_and_b32_e32 v213, 0xffff0000, v95
	v_lshlrev_b32_e32 v220, 16, v99
	v_and_b32_e32 v221, 0xffff0000, v99
	v_pk_add_f32 v[198:199], v[198:199], v[206:207]
	v_pk_add_f32 v[200:201], v[200:201], v[208:209]
	v_pk_add_f32 v[202:203], v[202:203], v[210:211]
	v_pk_add_f32 v[204:205], v[204:205], v[212:213]
	v_mul_f32_e32 v206, 0xbfb8aa3b, v214
	v_mul_f32_e32 v207, 0xbfb8aa3b, v215
	v_mul_f32_e32 v208, 0xbfb8aa3b, v216
	v_mul_f32_e32 v209, 0xbfb8aa3b, v217
	v_mul_f32_e32 v210, 0xbfb8aa3b, v218
	v_mul_f32_e32 v211, 0xbfb8aa3b, v219
	v_mul_f32_e32 v212, 0xbfb8aa3b, v220
	v_mul_f32_e32 v213, 0xbfb8aa3b, v221
	v_exp_f32_e32 v206, v206
	v_exp_f32_e32 v207, v207
	v_exp_f32_e32 v208, v208
	v_exp_f32_e32 v209, v209
	v_exp_f32_e32 v210, v210
	v_exp_f32_e32 v211, v211
	v_exp_f32_e32 v212, v212
	v_exp_f32_e32 v213, v213
	v_add_f32_e32 v206, 1.0, v206
	v_add_f32_e32 v207, 1.0, v207
	v_add_f32_e32 v208, 1.0, v208
	v_add_f32_e32 v209, 1.0, v209
	v_add_f32_e32 v210, 1.0, v210
	v_add_f32_e32 v211, 1.0, v211
	v_add_f32_e32 v212, 1.0, v212
	v_add_f32_e32 v213, 1.0, v213
	v_rcp_f32_e32 v206, v206
	v_rcp_f32_e32 v207, v207
	v_rcp_f32_e32 v208, v208
	v_rcp_f32_e32 v209, v209
	v_rcp_f32_e32 v210, v210
	v_rcp_f32_e32 v211, v211
	v_rcp_f32_e32 v212, v212
	v_rcp_f32_e32 v213, v213
	s_nop 0
	v_pk_mul_f32 v[206:207], v[206:207], v[214:215]
	v_pk_mul_f32 v[208:209], v[208:209], v[216:217]
	v_pk_mul_f32 v[210:211], v[210:211], v[218:219]
	v_pk_mul_f32 v[212:213], v[212:213], v[220:221]
	v_pk_mul_f32 v[198:199], v[198:199], v[206:207]
	v_pk_mul_f32 v[200:201], v[200:201], v[208:209]
	v_pk_mul_f32 v[202:203], v[202:203], v[210:211]
	v_pk_mul_f32 v[204:205], v[204:205], v[212:213]
	v_pk_mul_f32 v[214:215], v[198:199], v[198:199]
	v_pk_mul_f32 v[216:217], v[200:201], v[200:201]
	v_pk_mul_f32 v[218:219], v[202:203], v[202:203]
	v_pk_mul_f32 v[220:221], v[204:205], v[204:205]
	v_add_f32_e32 v230, v214, v215
	v_add_f32_e32 v230, v216, v230
	v_add_f32_e32 v230, v217, v230
	v_add_f32_e32 v230, v218, v230
	v_add_f32_e32 v230, v219, v230
	v_add_f32_e32 v230, v220, v230
	v_add_f32_e32 v230, v221, v230
	v_mov_b32_e32 v231, v177
	s_nop 0
	v_add_f32_dpp v230, v230, v230 row_shr:1 row_mask:0xf bank_mask:0xf bound_ctrl:1
	s_nop 1
	v_add_f32_dpp v230, v230, v230 row_shr:2 row_mask:0xf bank_mask:0xf bound_ctrl:1
	s_nop 1
	v_add_f32_dpp v230, v230, v230 row_shr:4 row_mask:0xf bank_mask:0xf bound_ctrl:1
	s_nop 1
	v_add_f32_dpp v230, v230, v230 row_shr:8 row_mask:0xf bank_mask:0xf bound_ctrl:1
	s_nop 1
	v_mov_b32_dpp v231, v230 row_bcast:15 row_mask:0xa bank_mask:0xf
	v_add_f32_e32 v230, v230, v231
	v_mov_b32_e32 v231, v177
	s_nop 1
	v_mov_b32_dpp v231, v230 row_bcast:31 row_mask:0xc bank_mask:0xf
	v_add_f32_e32 v230, v230, v231
	s_nop 0
	v_readlane_b32 s6, v230, 63
	s_nop 1
	v_fma_f32 v232, s6, v245, v238
	v_cmp_gt_f32_e32 vcc, s85, v232
	v_mul_f32_e32 v231, 0x4b800000, v232
	s_nop 0
	v_cndmask_b32_e32 v232, v232, v231, vcc
	v_rsq_f32_e32 v232, v232
	s_nop 0
	v_mul_f32_e32 v231, 0x45800000, v232
	v_cndmask_b32_e32 v232, v232, v231, vcc
	v_pk_mul_f32 v[222:223], v[156:157], v[232:233] op_sel_hi:[1,0]
	v_pk_mul_f32 v[224:225], v[158:159], v[232:233] op_sel_hi:[1,0]
	v_pk_mul_f32 v[226:227], v[160:161], v[232:233] op_sel_hi:[1,0]
	v_pk_mul_f32 v[228:229], v[162:163], v[232:233] op_sel_hi:[1,0]
	v_pk_mul_f32 v[222:223], v[198:199], v[222:223]
	v_pk_mul_f32 v[224:225], v[200:201], v[224:225]
	v_pk_mul_f32 v[226:227], v[202:203], v[226:227]
	v_pk_mul_f32 v[228:229], v[204:205], v[228:229]
	v_cvt_pk_bf16_f32 v234, v222, v223
	v_cvt_pk_bf16_f32 v235, v224, v225
	v_cvt_pk_bf16_f32 v236, v226, v227
	v_cvt_pk_bf16_f32 v237, v228, v229
	global_store_dwordx4 v[166:167], v[234:237], off offset:3072

; __global__ void __launch_bounds__(NWAVES * 64, 2) trunk_fwd(Args args) {
	.amdhsa_kernel _Z9trunk_fwd4Args
		.amdhsa_group_segment_fixed_size 0
		.amdhsa_private_segment_fixed_size 0
		.amdhsa_kernarg_size 456
		.amdhsa_user_sgpr_count 2
		.amdhsa_user_sgpr_dispatch_ptr 0
		.amdhsa_user_sgpr_queue_ptr 0
		.amdhsa_user_sgpr_kernarg_segment_ptr 1
		.amdhsa_user_sgpr_dispatch_id 0
		.amdhsa_user_sgpr_kernarg_preload_length 0
		.amdhsa_user_sgpr_kernarg_preload_offset 0
		.amdhsa_user_sgpr_private_segment_size 0
		.amdhsa_uses_dynamic_stack 0
		.amdhsa_enable_private_segment 0
		.amdhsa_system_sgpr_workgroup_id_x 1
		.amdhsa_system_sgpr_workgroup_id_y 0
		.amdhsa_system_sgpr_workgroup_id_z 0
		.amdhsa_system_sgpr_workgroup_info 0
		.amdhsa_system_vgpr_workitem_id 0
		.amdhsa_next_free_vgpr 256
		.amdhsa_next_free_sgpr 102
		.amdhsa_accum_offset 256
		.amdhsa_reserve_vcc 1
		.amdhsa_float_round_mode_32 0
		.amdhsa_float_round_mode_16_64 0
		.amdhsa_float_denorm_mode_32 3
		.amdhsa_float_denorm_mode_16_64 3
		.amdhsa_dx10_clamp 1
		.amdhsa_ieee_mode 1
		.amdhsa_fp16_overflow 0
		.amdhsa_tg_split 0
		.amdhsa_exception_fp_ieee_invalid_op 0
		.amdhsa_exception_fp_denorm_src 0
		.amdhsa_exception_fp_ieee_div_zero 0
		.amdhsa_exception_fp_ieee_overflow 0
		.amdhsa_exception_fp_ieee_underflow 0
		.amdhsa_exception_fp_ieee_inexact 0
		.amdhsa_exception_int_div_zero 0
	.end_amdhsa_kernel

; __global__ void __launch_bounds__(NWAVES * 64, 2) trunk_fwd(Args args) {
amdhsa.kernels:
  - .agpr_count:     0
    .args:
      - .offset:         0
        .size:           200
        .value_kind:     by_value
      - .offset:         200
        .size:           4
        .value_kind:     hidden_block_count_x
      - .offset:         204
        .size:           4
        .value_kind:     hidden_block_count_y
      - .offset:         208
        .size:           4
        .value_kind:     hidden_block_count_z
      - .offset:         212
        .size:           2
        .value_kind:     hidden_group_size_x
      - .offset:         214
        .size:           2
        .value_kind:     hidden_group_size_y
      - .offset:         216
        .size:           2
        .value_kind:     hidden_group_size_z
      - .offset:         218
        .size:           2
        .value_kind:     hidden_remainder_x
      - .offset:         220
        .size:           2
        .value_kind:     hidden_remainder_y
      - .offset:         222
        .size:           2
        .value_kind:     hidden_remainder_z
      - .offset:         240
        .size:           8
        .value_kind:     hidden_global_offset_x
      - .offset:         248
        .size:           8
        .value_kind:     hidden_global_offset_y
      - .offset:         256
        .size:           8
        .value_kind:     hidden_global_offset_z
      - .offset:         264
        .size:           2
        .value_kind:     hidden_grid_dims
      - .offset:         320
        .size:           4
        .value_kind:     hidden_dynamic_lds_size
    .group_segment_fixed_size: 0
    .kernarg_segment_align: 8
    .kernarg_segment_size: 456
    .language:       OpenCL C
    .language_version:
      - 2
      - 0
    .max_flat_workgroup_size: 512
    .name:           _Z9trunk_fwd4Args
    .private_segment_fixed_size: 0
    .sgpr_count:     108
    .sgpr_spill_count: 305
    .symbol:         _Z9trunk_fwd4Args.kd
    .uniform_work_group_size: 1
    .uses_dynamic_stack: false
    .vgpr_count:     256
    .vgpr_spill_count: 0
    .wavefront_size: 64
